# plus: GEMM K-loop lgkmcnt(0) drains replaced by counted waits at each MFMA's first consumer
# speedup vs baseline: 1.0066x; 1.0024x over previous
.LBB0_304:
	s_add_u32 s2, s68, 0xfff80080
	s_addc_u32 s17, s69, -1
	s_add_i32 s26, 0, 0x10000
	v_add_u32_e32 v156, s26, v141
	ds_read_b128 v[144:147], v156
	ds_read_b128 v[148:151], v156 offset:1024
	ds_read_b128 v[152:155], v156 offset:2048
	ds_read_b128 v[156:159], v156 offset:3072
	s_cmp_eq_u32 s44, 28
	s_cselect_b32 s73, s55, s17
	s_cselect_b32 s72, s83, s2
	s_cselect_b32 s71, s24, s92
	s_cselect_b32 s70, s25, s43
	v_lshl_add_u64 v[164:165], s[68:69], 0, v[136:137]
	s_add_i32 m0, s58, 0xc000
	ds_read_b128 v[160:163], v143
	ds_read_b128 v[188:191], v143 offset:1024
	ds_read_b128 v[192:195], v143 offset:2048
	ds_read_b128 v[196:199], v143 offset:3072
	ds_read_b128 v[200:203], v143 offset:4096
	ds_read_b128 v[216:219], v143 offset:5120
	ds_read_b128 v[220:223], v143 offset:6144
	ds_read_b128 v[224:227], v143 offset:7168
	global_load_lds_dwordx4 v[164:165], off
	v_lshl_add_u64 v[164:165], s[68:69], 0, v[138:139]
	s_add_i32 m0, s58, 0xe000
	s_nop 0
	global_load_lds_dwordx4 v[164:165], off
	s_waitcnt lgkmcnt(8)
	s_barrier
	s_waitcnt lgkmcnt(12)
	s_waitcnt lgkmcnt(12)
	s_waitcnt lgkmcnt(7)
	v_mfma_f32_16x16x32_bf16 v[126:129], v[144:147], v[160:163], v[126:129]
	v_mfma_f32_16x16x32_bf16 v[122:125], v[152:155], v[160:163], v[122:125]
	s_waitcnt lgkmcnt(5)
	v_mfma_f32_16x16x32_bf16 v[118:121], v[144:147], v[192:195], v[118:121]
	v_mfma_f32_16x16x32_bf16 v[114:117], v[152:155], v[192:195], v[114:117]
	s_waitcnt lgkmcnt(3)
	v_mfma_f32_16x16x32_bf16 v[102:105], v[144:147], v[200:203], v[102:105]
	v_mfma_f32_16x16x32_bf16 v[98:101], v[152:155], v[200:203], v[98:101]
	s_waitcnt lgkmcnt(1)
	v_mfma_f32_16x16x32_bf16 v[86:89], v[144:147], v[220:223], v[86:89]
	v_mfma_f32_16x16x32_bf16 v[82:85], v[152:155], v[220:223], v[82:85]
	v_mfma_f32_16x16x32_bf16 v[126:129], v[148:151], v[188:191], v[126:129]
	v_mfma_f32_16x16x32_bf16 v[122:125], v[156:159], v[188:191], v[122:125]
	v_mfma_f32_16x16x32_bf16 v[118:121], v[148:151], v[196:199], v[118:121]
	v_mfma_f32_16x16x32_bf16 v[114:117], v[156:159], v[196:199], v[114:117]
	v_mfma_f32_16x16x32_bf16 v[102:105], v[148:151], v[216:219], v[102:105]
	v_mfma_f32_16x16x32_bf16 v[98:101], v[156:159], v[216:219], v[98:101]
	s_waitcnt lgkmcnt(0)
	v_mfma_f32_16x16x32_bf16 v[86:89], v[148:151], v[224:227], v[86:89]
	v_mfma_f32_16x16x32_bf16 v[82:85], v[156:159], v[224:227], v[82:85]
	s_barrier
	s_add_i32 s2, 0, 0x14000
	v_add_u32_e32 v164, s2, v141
	s_add_i32 s17, s26, s3
	ds_read_b128 v[228:231], v164
	ds_read_b128 v[232:235], v164 offset:1024
	ds_read_b128 v[236:239], v164 offset:2048
	ds_read_b128 v[240:243], v164 offset:3072
	v_lshl_add_u64 v[164:165], s[70:71], 0, v[0:1]
	s_mov_b32 m0, s17
	v_lshl_add_u64 v[204:205], s[70:71], 0, v[130:131]
	global_load_lds_dwordx4 v[164:165], off
	s_add_i32 m0, s17, 0x2000
	s_nop 0
	global_load_lds_dwordx4 v[204:205], off
	s_barrier
	s_waitcnt lgkmcnt(4)
	s_waitcnt lgkmcnt(4)
	s_waitcnt lgkmcnt(3)
	v_mfma_f32_16x16x32_bf16 v[110:113], v[228:231], v[160:163], v[110:113]
	s_waitcnt lgkmcnt(1)
	v_mfma_f32_16x16x32_bf16 v[106:109], v[236:239], v[160:163], v[106:109]
	v_mfma_f32_16x16x32_bf16 v[94:97], v[228:231], v[192:195], v[94:97]
	v_mfma_f32_16x16x32_bf16 v[90:93], v[236:239], v[192:195], v[90:93]
	v_mfma_f32_16x16x32_bf16 v[78:81], v[228:231], v[200:203], v[78:81]
	v_mfma_f32_16x16x32_bf16 v[74:77], v[236:239], v[200:203], v[74:77]
	v_mfma_f32_16x16x32_bf16 v[70:73], v[228:231], v[220:223], v[70:73]
	v_mfma_f32_16x16x32_bf16 v[66:69], v[236:239], v[220:223], v[66:69]
	v_mfma_f32_16x16x32_bf16 v[110:113], v[232:235], v[188:191], v[110:113]
	s_waitcnt lgkmcnt(0)
	v_mfma_f32_16x16x32_bf16 v[106:109], v[240:243], v[188:191], v[106:109]
	v_mfma_f32_16x16x32_bf16 v[94:97], v[232:235], v[196:199], v[94:97]
	v_mfma_f32_16x16x32_bf16 v[90:93], v[240:243], v[196:199], v[90:93]
	v_mfma_f32_16x16x32_bf16 v[78:81], v[232:235], v[216:219], v[78:81]
	v_mfma_f32_16x16x32_bf16 v[74:77], v[240:243], v[216:219], v[74:77]
	v_mfma_f32_16x16x32_bf16 v[70:73], v[232:235], v[224:227], v[70:73]
	v_mfma_f32_16x16x32_bf16 v[66:69], v[240:243], v[224:227], v[66:69]
	s_mov_b32 m0, s58
	v_lshl_add_u64 v[244:245], s[72:73], 0, v[134:135]
	s_barrier
	ds_read_b128 v[160:163], v143 offset:16384
	ds_read_b128 v[188:191], v143 offset:17408
	ds_read_b128 v[192:195], v143 offset:18432
	ds_read_b128 v[196:199], v143 offset:19456
	ds_read_b128 v[200:203], v143 offset:20480
	ds_read_b128 v[216:219], v143 offset:21504
	ds_read_b128 v[220:223], v143 offset:22528
	ds_read_b128 v[224:227], v143 offset:23552
	global_load_lds_dwordx4 v[244:245], off
	v_lshl_add_u64 v[246:247], s[72:73], 0, v[132:133]
	s_mov_b32 m0, s74
	s_nop 0
	global_load_lds_dwordx4 v[246:247], off
	s_barrier
	s_waitcnt lgkmcnt(8)
	s_waitcnt lgkmcnt(8)
	s_waitcnt lgkmcnt(7)
	v_mfma_f32_16x16x32_bf16 v[62:65], v[144:147], v[160:163], v[62:65]
	v_mfma_f32_16x16x32_bf16 v[58:61], v[152:155], v[160:163], v[58:61]
	s_waitcnt lgkmcnt(5)
	v_mfma_f32_16x16x32_bf16 v[54:57], v[144:147], v[192:195], v[54:57]
	v_mfma_f32_16x16x32_bf16 v[50:53], v[152:155], v[192:195], v[50:53]
	s_waitcnt lgkmcnt(3)
	v_mfma_f32_16x16x32_bf16 v[38:41], v[144:147], v[200:203], v[38:41]
	v_mfma_f32_16x16x32_bf16 v[34:37], v[152:155], v[200:203], v[34:37]
	s_waitcnt lgkmcnt(1)
	v_mfma_f32_16x16x32_bf16 v[22:25], v[144:147], v[220:223], v[22:25]
	v_mfma_f32_16x16x32_bf16 v[18:21], v[152:155], v[220:223], v[18:21]
	v_mfma_f32_16x16x32_bf16 v[62:65], v[148:151], v[188:191], v[62:65]
	v_mfma_f32_16x16x32_bf16 v[58:61], v[156:159], v[188:191], v[58:61]
	v_mfma_f32_16x16x32_bf16 v[54:57], v[148:151], v[196:199], v[54:57]
	v_mfma_f32_16x16x32_bf16 v[50:53], v[156:159], v[196:199], v[50:53]
	v_mfma_f32_16x16x32_bf16 v[38:41], v[148:151], v[216:219], v[38:41]
	v_mfma_f32_16x16x32_bf16 v[34:37], v[156:159], v[216:219], v[34:37]
	s_waitcnt lgkmcnt(0)
	v_mfma_f32_16x16x32_bf16 v[22:25], v[148:151], v[224:227], v[22:25]
	v_mfma_f32_16x16x32_bf16 v[18:21], v[156:159], v[224:227], v[18:21]
	s_barrier
	s_add_u32 s26, s70, 0x80000
	s_addc_u32 s27, s71, 0
	s_add_i32 s2, s2, s3
	v_lshl_add_u64 v[144:145], s[26:27], 0, v[0:1]
	s_mov_b32 m0, s2
	s_nop 0
	global_load_lds_dwordx4 v[144:145], off
	v_lshl_add_u64 v[144:145], s[26:27], 0, v[130:131]
	s_add_i32 m0, s2, 0x2000
	s_nop 0
	global_load_lds_dwordx4 v[144:145], off
	s_waitcnt vmcnt(6)
	s_barrier
	v_mfma_f32_16x16x32_bf16 v[46:49], v[228:231], v[160:163], v[46:49]
	v_mfma_f32_16x16x32_bf16 v[42:45], v[236:239], v[160:163], v[42:45]
	v_mfma_f32_16x16x32_bf16 v[30:33], v[228:231], v[192:195], v[30:33]
	v_mfma_f32_16x16x32_bf16 v[26:29], v[236:239], v[192:195], v[26:29]
	v_mfma_f32_16x16x32_bf16 v[14:17], v[228:231], v[200:203], v[14:17]
	v_mfma_f32_16x16x32_bf16 v[10:13], v[236:239], v[200:203], v[10:13]
	v_mfma_f32_16x16x32_bf16 v[6:9], v[228:231], v[220:223], v[6:9]
	v_mfma_f32_16x16x32_bf16 v[2:5], v[236:239], v[220:223], v[2:5]
	v_mfma_f32_16x16x32_bf16 v[46:49], v[232:235], v[188:191], v[46:49]
	v_mfma_f32_16x16x32_bf16 v[42:45], v[240:243], v[188:191], v[42:45]
	v_mfma_f32_16x16x32_bf16 v[30:33], v[232:235], v[196:199], v[30:33]
	v_mfma_f32_16x16x32_bf16 v[26:29], v[240:243], v[196:199], v[26:29]
	v_mfma_f32_16x16x32_bf16 v[14:17], v[232:235], v[216:219], v[14:17]
	v_mfma_f32_16x16x32_bf16 v[10:13], v[240:243], v[216:219], v[10:13]
	v_mfma_f32_16x16x32_bf16 v[6:9], v[232:235], v[224:227], v[6:9]
	v_mfma_f32_16x16x32_bf16 v[2:5], v[240:243], v[224:227], v[2:5]
	s_add_i32 s2, 0, 0x18000
	v_add_u32_e32 v156, s2, v141
	s_barrier
	ds_read_b128 v[144:147], v156
	ds_read_b128 v[148:151], v156 offset:1024
	ds_read_b128 v[152:155], v156 offset:2048
	ds_read_b128 v[156:159], v156 offset:3072
	s_add_u32 s26, s72, 0x80000
	s_addc_u32 s27, s73, 0
	s_mov_b32 m0, s75
	v_lshl_add_u64 v[228:229], s[26:27], 0, v[134:135]
	ds_read_b128 v[160:163], v143 offset:32768
	ds_read_b128 v[188:191], v143 offset:33792
	ds_read_b128 v[192:195], v143 offset:34816
	ds_read_b128 v[196:199], v143 offset:35840
	ds_read_b128 v[200:203], v143 offset:36864
	ds_read_b128 v[216:219], v143 offset:37888
	ds_read_b128 v[220:223], v143 offset:38912
	ds_read_b128 v[224:227], v143 offset:39936
	global_load_lds_dwordx4 v[228:229], off
	v_lshl_add_u64 v[228:229], s[26:27], 0, v[132:133]
	s_mov_b32 m0, s79
	s_nop 0
	global_load_lds_dwordx4 v[228:229], off
	s_waitcnt lgkmcnt(8)
	s_barrier
	s_waitcnt lgkmcnt(12)
	s_waitcnt lgkmcnt(12)
	s_waitcnt lgkmcnt(7)
	v_mfma_f32_16x16x32_bf16 v[126:129], v[144:147], v[160:163], v[126:129]
	v_mfma_f32_16x16x32_bf16 v[122:125], v[152:155], v[160:163], v[122:125]
	s_waitcnt lgkmcnt(5)
	v_mfma_f32_16x16x32_bf16 v[118:121], v[144:147], v[192:195], v[118:121]
	v_mfma_f32_16x16x32_bf16 v[114:117], v[152:155], v[192:195], v[114:117]
	s_waitcnt lgkmcnt(3)
	v_mfma_f32_16x16x32_bf16 v[102:105], v[144:147], v[200:203], v[102:105]
	v_mfma_f32_16x16x32_bf16 v[98:101], v[152:155], v[200:203], v[98:101]
	s_waitcnt lgkmcnt(1)
	v_mfma_f32_16x16x32_bf16 v[86:89], v[144:147], v[220:223], v[86:89]
	v_mfma_f32_16x16x32_bf16 v[82:85], v[152:155], v[220:223], v[82:85]
	v_mfma_f32_16x16x32_bf16 v[126:129], v[148:151], v[188:191], v[126:129]
	v_mfma_f32_16x16x32_bf16 v[122:125], v[156:159], v[188:191], v[122:125]
	v_mfma_f32_16x16x32_bf16 v[118:121], v[148:151], v[196:199], v[118:121]
	v_mfma_f32_16x16x32_bf16 v[114:117], v[156:159], v[196:199], v[114:117]
	v_mfma_f32_16x16x32_bf16 v[102:105], v[148:151], v[216:219], v[102:105]
	v_mfma_f32_16x16x32_bf16 v[98:101], v[156:159], v[216:219], v[98:101]
	s_waitcnt lgkmcnt(0)
	v_mfma_f32_16x16x32_bf16 v[86:89], v[148:151], v[224:227], v[86:89]
	v_mfma_f32_16x16x32_bf16 v[82:85], v[156:159], v[224:227], v[82:85]
	s_barrier
	s_add_i32 s17, 0, 0x1c000
	s_add_i32 s2, s2, s3
	v_add_u32_e32 v206, s17, v141
	v_lshl_add_u64 v[164:165], v[164:165], 0, s[28:29]
	s_mov_b32 m0, s2
	ds_read_b128 v[228:231], v206
	ds_read_b128 v[232:235], v206 offset:1024
	ds_read_b128 v[236:239], v206 offset:2048
	ds_read_b128 v[240:243], v206 offset:3072
	global_load_lds_dwordx4 v[164:165], off
	v_lshl_add_u64 v[164:165], v[204:205], 0, s[28:29]
	s_add_i32 m0, s2, 0x2000
	s_nop 0
	global_load_lds_dwordx4 v[164:165], off
	s_barrier
	s_waitcnt lgkmcnt(4)
	s_waitcnt lgkmcnt(4)
	s_waitcnt lgkmcnt(3)
	v_mfma_f32_16x16x32_bf16 v[110:113], v[228:231], v[160:163], v[110:113]
	s_waitcnt lgkmcnt(1)
	v_mfma_f32_16x16x32_bf16 v[106:109], v[236:239], v[160:163], v[106:109]
	v_mfma_f32_16x16x32_bf16 v[94:97], v[228:231], v[192:195], v[94:97]
	v_mfma_f32_16x16x32_bf16 v[90:93], v[236:239], v[192:195], v[90:93]
	v_mfma_f32_16x16x32_bf16 v[78:81], v[228:231], v[200:203], v[78:81]
	v_mfma_f32_16x16x32_bf16 v[74:77], v[236:239], v[200:203], v[74:77]
	v_mfma_f32_16x16x32_bf16 v[70:73], v[228:231], v[220:223], v[70:73]
	v_mfma_f32_16x16x32_bf16 v[66:69], v[236:239], v[220:223], v[66:69]
	v_mfma_f32_16x16x32_bf16 v[110:113], v[232:235], v[188:191], v[110:113]
	s_waitcnt lgkmcnt(0)
	v_mfma_f32_16x16x32_bf16 v[106:109], v[240:243], v[188:191], v[106:109]
	v_mfma_f32_16x16x32_bf16 v[94:97], v[232:235], v[196:199], v[94:97]
	v_mfma_f32_16x16x32_bf16 v[90:93], v[240:243], v[196:199], v[90:93]
	v_mfma_f32_16x16x32_bf16 v[78:81], v[232:235], v[216:219], v[78:81]
	v_mfma_f32_16x16x32_bf16 v[74:77], v[240:243], v[216:219], v[74:77]
	v_mfma_f32_16x16x32_bf16 v[70:73], v[232:235], v[224:227], v[70:73]
	v_mfma_f32_16x16x32_bf16 v[66:69], v[240:243], v[224:227], v[66:69]
	s_mov_b32 m0, s80
	v_lshl_add_u64 v[164:165], v[244:245], 0, s[28:29]
	s_barrier
	ds_read_b128 v[160:163], v143 offset:49152
	ds_read_b128 v[188:191], v143 offset:50176
	ds_read_b128 v[192:195], v143 offset:51200
	ds_read_b128 v[196:199], v143 offset:52224
	ds_read_b128 v[200:203], v143 offset:53248
	ds_read_b128 v[216:219], v143 offset:54272
	ds_read_b128 v[220:223], v143 offset:55296
	ds_read_b128 v[224:227], v143 offset:56320
	global_load_lds_dwordx4 v[164:165], off
	v_lshl_add_u64 v[164:165], v[246:247], 0, s[28:29]
	s_mov_b32 m0, s81
	s_nop 0
	global_load_lds_dwordx4 v[164:165], off
	s_barrier
	s_waitcnt lgkmcnt(8)
	s_waitcnt lgkmcnt(8)
	s_waitcnt lgkmcnt(7)
	v_mfma_f32_16x16x32_bf16 v[62:65], v[144:147], v[160:163], v[62:65]
	v_mfma_f32_16x16x32_bf16 v[58:61], v[152:155], v[160:163], v[58:61]
	s_waitcnt lgkmcnt(5)
	v_mfma_f32_16x16x32_bf16 v[54:57], v[144:147], v[192:195], v[54:57]
	v_mfma_f32_16x16x32_bf16 v[50:53], v[152:155], v[192:195], v[50:53]
	s_waitcnt lgkmcnt(3)
	v_mfma_f32_16x16x32_bf16 v[38:41], v[144:147], v[200:203], v[38:41]
	v_mfma_f32_16x16x32_bf16 v[34:37], v[152:155], v[200:203], v[34:37]
	s_waitcnt lgkmcnt(1)
	v_mfma_f32_16x16x32_bf16 v[22:25], v[144:147], v[220:223], v[22:25]
	v_mfma_f32_16x16x32_bf16 v[18:21], v[152:155], v[220:223], v[18:21]
	v_mfma_f32_16x16x32_bf16 v[62:65], v[148:151], v[188:191], v[62:65]
	v_mfma_f32_16x16x32_bf16 v[58:61], v[156:159], v[188:191], v[58:61]
	v_mfma_f32_16x16x32_bf16 v[54:57], v[148:151], v[196:199], v[54:57]
	v_mfma_f32_16x16x32_bf16 v[50:53], v[156:159], v[196:199], v[50:53]
	v_mfma_f32_16x16x32_bf16 v[38:41], v[148:151], v[216:219], v[38:41]
	v_mfma_f32_16x16x32_bf16 v[34:37], v[156:159], v[216:219], v[34:37]
	s_waitcnt lgkmcnt(0)
	v_mfma_f32_16x16x32_bf16 v[22:25], v[148:151], v[224:227], v[22:25]
	v_mfma_f32_16x16x32_bf16 v[18:21], v[156:159], v[224:227], v[18:21]
	s_barrier
	s_add_u32 s26, s70, 0x80080
	s_addc_u32 s27, s71, 0
	s_add_i32 s2, s17, s3
	v_lshl_add_u64 v[144:145], s[26:27], 0, v[0:1]
	s_mov_b32 m0, s2
	s_nop 0
	global_load_lds_dwordx4 v[144:145], off
	v_lshl_add_u64 v[144:145], s[26:27], 0, v[130:131]
	s_add_i32 m0, s2, 0x2000
	s_nop 0
	global_load_lds_dwordx4 v[144:145], off
	s_waitcnt vmcnt(6)
	s_barrier
	v_mfma_f32_16x16x32_bf16 v[46:49], v[228:231], v[160:163], v[46:49]
	v_mfma_f32_16x16x32_bf16 v[42:45], v[236:239], v[160:163], v[42:45]
	v_mfma_f32_16x16x32_bf16 v[30:33], v[228:231], v[192:195], v[30:33]
	v_mfma_f32_16x16x32_bf16 v[26:29], v[236:239], v[192:195], v[26:29]
	v_mfma_f32_16x16x32_bf16 v[14:17], v[228:231], v[200:203], v[14:17]
	v_mfma_f32_16x16x32_bf16 v[10:13], v[236:239], v[200:203], v[10:13]
	v_mfma_f32_16x16x32_bf16 v[6:9], v[228:231], v[220:223], v[6:9]
	v_mfma_f32_16x16x32_bf16 v[2:5], v[236:239], v[220:223], v[2:5]
	v_mfma_f32_16x16x32_bf16 v[46:49], v[232:235], v[188:191], v[46:49]
	v_mfma_f32_16x16x32_bf16 v[42:45], v[240:243], v[188:191], v[42:45]
	v_mfma_f32_16x16x32_bf16 v[30:33], v[232:235], v[196:199], v[30:33]
	v_mfma_f32_16x16x32_bf16 v[26:29], v[240:243], v[196:199], v[26:29]
	v_mfma_f32_16x16x32_bf16 v[14:17], v[232:235], v[216:219], v[14:17]
	v_mfma_f32_16x16x32_bf16 v[10:13], v[240:243], v[216:219], v[10:13]
	v_mfma_f32_16x16x32_bf16 v[6:9], v[232:235], v[224:227], v[6:9]
	v_mfma_f32_16x16x32_bf16 v[2:5], v[240:243], v[224:227], v[2:5]
	s_add_i32 s44, s44, 2
	s_add_u32 s68, s68, 0x100
	s_addc_u32 s69, s69, 0
	s_add_u32 s43, s43, 0x100
	s_addc_u32 s92, s92, 0
	s_cmp_gt_u32 s44, 29
	s_barrier
	s_cbranch_scc0 .LBB0_304
	v_lshl_add_u32 v146, s47, 8, v140
	v_lshl_or_b32 v144, s46, 8, v142
	v_cvt_pk_bf16_f32 v126, v126, v127
	v_cvt_pk_bf16_f32 v127, v128, v129
	v_cvt_pk_bf16_f32 v128, v122, v123
	v_mov_b64_e32 v[122:123], s[22:23]
	v_ashrrev_i32_e32 v145, 31, v144
	v_cvt_pk_bf16_f32 v70, v70, v71
	v_cvt_pk_bf16_f32 v71, v72, v73
	v_cvt_pk_bf16_f32 v72, v66, v67
	v_add_u32_e32 v66, 0x80, v146
	v_cvt_pk_bf16_f32 v129, v124, v125
	v_mad_i64_i32 v[124:125], s[24:25], v146, s97, v[122:123]
	v_lshlrev_b64 v[144:145], 1, v[144:145]
	v_cvt_pk_bf16_f32 v62, v62, v63
	v_cvt_pk_bf16_f32 v63, v64, v65
	v_cvt_pk_bf16_f32 v64, v58, v59
	v_mad_i64_i32 v[58:59], s[24:25], v66, s97, v[122:123]
	v_lshl_add_u64 v[124:125], v[124:125], 0, v[144:145]
	v_cvt_pk_bf16_f32 v110, v110, v111
	v_cvt_pk_bf16_f32 v111, v112, v113
	v_cvt_pk_bf16_f32 v112, v106, v107
	v_cvt_pk_bf16_f32 v113, v108, v109
	v_lshl_add_u64 v[58:59], v[58:59], 0, v[144:145]
	v_cvt_pk_bf16_f32 v46, v46, v47
	v_cvt_pk_bf16_f32 v47, v48, v49
	v_cvt_pk_bf16_f32 v48, v42, v43
	v_cvt_pk_bf16_f32 v49, v44, v45
	global_store_dwordx4 v[124:125], v[110:113], off offset:256
	global_store_dwordx4 v[58:59], v[46:49], off offset:256
	v_cvt_pk_bf16_f32 v94, v94, v95
	v_or_b32_e32 v110, 16, v146
	v_add_u32_e32 v46, 0x90, v146
	v_mad_i64_i32 v[110:111], s[24:25], v110, s97, v[122:123]
	v_mad_i64_i32 v[46:47], s[24:25], v46, s97, v[122:123]
	v_lshl_add_u64 v[110:111], v[110:111], 0, v[144:145]
	v_cvt_pk_bf16_f32 v95, v96, v97
	v_cvt_pk_bf16_f32 v96, v90, v91
	v_cvt_pk_bf16_f32 v97, v92, v93
	v_lshl_add_u64 v[46:47], v[46:47], 0, v[144:145]
	v_cvt_pk_bf16_f32 v30, v30, v31
	v_cvt_pk_bf16_f32 v31, v32, v33
	v_cvt_pk_bf16_f32 v32, v26, v27
	v_cvt_pk_bf16_f32 v33, v28, v29
	global_store_dwordx4 v[110:111], v[94:97], off offset:256
	global_store_dwordx4 v[46:47], v[30:33], off offset:256
	v_cvt_pk_bf16_f32 v78, v78, v79
	v_or_b32_e32 v94, 32, v146
	v_add_u32_e32 v30, 0xa0, v146
	v_mad_i64_i32 v[94:95], s[24:25], v94, s97, v[122:123]
	v_mad_i64_i32 v[30:31], s[24:25], v30, s97, v[122:123]
	v_lshl_add_u64 v[94:95], v[94:95], 0, v[144:145]
	v_cvt_pk_bf16_f32 v79, v80, v81
	v_cvt_pk_bf16_f32 v80, v74, v75
	v_cvt_pk_bf16_f32 v81, v76, v77
	v_lshl_add_u64 v[30:31], v[30:31], 0, v[144:145]
	v_cvt_pk_bf16_f32 v14, v14, v15
	v_cvt_pk_bf16_f32 v15, v16, v17
	v_cvt_pk_bf16_f32 v16, v10, v11
	v_cvt_pk_bf16_f32 v17, v12, v13
	global_store_dwordx4 v[94:95], v[78:81], off offset:256
	global_store_dwordx4 v[30:31], v[14:17], off offset:256
	v_cvt_pk_bf16_f32 v106, v118, v119
	v_or_b32_e32 v78, 48, v146
	v_add_u32_e32 v14, 0xb0, v146
	v_mad_i64_i32 v[78:79], s[24:25], v78, s97, v[122:123]
	v_mad_i64_i32 v[14:15], s[24:25], v14, s97, v[122:123]
	v_cvt_pk_bf16_f32 v107, v120, v121
	v_cvt_pk_bf16_f32 v108, v114, v115
	v_cvt_pk_bf16_f32 v109, v116, v117
	v_cvt_pk_bf16_f32 v90, v102, v103
	v_cvt_pk_bf16_f32 v91, v104, v105
	v_cvt_pk_bf16_f32 v92, v98, v99
	v_cvt_pk_bf16_f32 v93, v100, v101
	v_cvt_pk_bf16_f32 v74, v86, v87
	v_cvt_pk_bf16_f32 v75, v88, v89
	v_cvt_pk_bf16_f32 v76, v82, v83
	v_cvt_pk_bf16_f32 v77, v84, v85
	v_lshl_add_u64 v[78:79], v[78:79], 0, v[144:145]
	v_cvt_pk_bf16_f32 v73, v68, v69
	v_cvt_pk_bf16_f32 v65, v60, v61
	v_cvt_pk_bf16_f32 v42, v54, v55
	v_cvt_pk_bf16_f32 v43, v56, v57
	v_cvt_pk_bf16_f32 v44, v50, v51
	v_cvt_pk_bf16_f32 v45, v52, v53
	v_cvt_pk_bf16_f32 v26, v38, v39
	v_cvt_pk_bf16_f32 v27, v40, v41
	v_cvt_pk_bf16_f32 v28, v34, v35
	v_cvt_pk_bf16_f32 v29, v36, v37
	v_cvt_pk_bf16_f32 v10, v22, v23
	v_cvt_pk_bf16_f32 v11, v24, v25
	v_cvt_pk_bf16_f32 v12, v18, v19
	v_cvt_pk_bf16_f32 v13, v20, v21
	v_lshl_add_u64 v[14:15], v[14:15], 0, v[144:145]
	v_cvt_pk_bf16_f32 v6, v6, v7
	v_cvt_pk_bf16_f32 v7, v8, v9
	v_cvt_pk_bf16_f32 v8, v2, v3
	v_cvt_pk_bf16_f32 v9, v4, v5
	s_and_b64 vcc, exec, s[0:1]
	s_mov_b32 s46, s42
	s_mov_b32 s47, s54
	s_mov_b64 s[70:71], s[64:65]
	s_mov_b64 s[68:69], s[62:63]
	global_store_dwordx4 v[124:125], v[126:129], off
	global_store_dwordx4 v[110:111], v[106:109], off
	global_store_dwordx4 v[94:95], v[90:93], off
	global_store_dwordx4 v[78:79], v[74:77], off
	global_store_dwordx4 v[78:79], v[70:73], off offset:256
	global_store_dwordx4 v[58:59], v[62:65], off
	global_store_dwordx4 v[46:47], v[42:45], off
	global_store_dwordx4 v[30:31], v[26:29], off
	global_store_dwordx4 v[14:15], v[10:13], off
	global_store_dwordx4 v[14:15], v[6:9], off offset:256
	s_cbranch_vccz .LBB0_301
	v_readlane_b32 s0, v254, 12
	s_waitcnt vmcnt(0)
	v_readlane_b32 s1, v254, 13
	v_readlane_b32 s84, v251, 38
	v_readlane_b32 s18, v253, 0
	s_andn2_b64 vcc, exec, s[0:1]
	v_readlane_b32 s85, v251, 39
	v_readlane_b32 s86, v251, 40
	v_readlane_b32 s87, v251, 41
	v_readlane_b32 s14, v250, 63
	v_readlane_b32 s19, v253, 1
	s_cbranch_vccnz .LBB0_308
	s_barrier

.LBB0_433:
	s_add_u32 s6, s78, 0x100
	s_addc_u32 s7, s79, 0
	s_add_i32 s2, 0, 0x10000
	v_add_u32_e32 v0, s2, v153
	ds_read_b128 v[142:145], v0
	ds_read_b128 v[146:149], v0 offset:1024
	ds_read_b128 v[156:159], v0 offset:2048
	ds_read_b128 v[160:163], v0 offset:3072
	s_cmp_eq_u32 s44, 4
	s_cselect_b32 s83, s75, s7
	s_cselect_b32 s82, s74, s6
	s_cselect_b32 s81, s11, s46
	s_cselect_b32 s80, s24, s25
	v_lshl_add_u64 v[150:151], s[78:79], 0, v[138:139]
	s_add_i32 m0, s58, 0xc000
	ds_read_b128 v[188:191], v155
	ds_read_b128 v[192:195], v155 offset:1024
	ds_read_b128 v[196:199], v155 offset:2048
	ds_read_b128 v[200:203], v155 offset:3072
	ds_read_b128 v[216:219], v155 offset:4096
	ds_read_b128 v[220:223], v155 offset:5120
	ds_read_b128 v[224:227], v155 offset:6144
	ds_read_b128 v[228:231], v155 offset:7168
	global_load_lds_dwordx4 v[150:151], off
	v_lshl_add_u64 v[150:151], s[78:79], 0, v[140:141]
	s_add_i32 m0, s58, 0xe000
	s_nop 0
	global_load_lds_dwordx4 v[150:151], off
	s_waitcnt lgkmcnt(8)
	s_barrier
	s_waitcnt lgkmcnt(12)
	s_waitcnt lgkmcnt(12)
	s_waitcnt lgkmcnt(7)
	v_mfma_f32_16x16x32_bf16 v[126:129], v[142:145], v[188:191], v[126:129]
	v_mfma_f32_16x16x32_bf16 v[122:125], v[156:159], v[188:191], v[122:125]
	s_waitcnt lgkmcnt(5)
	v_mfma_f32_16x16x32_bf16 v[110:113], v[142:145], v[196:199], v[110:113]
	v_mfma_f32_16x16x32_bf16 v[106:109], v[156:159], v[196:199], v[106:109]
	s_waitcnt lgkmcnt(3)
	v_mfma_f32_16x16x32_bf16 v[94:97], v[142:145], v[216:219], v[94:97]
	v_mfma_f32_16x16x32_bf16 v[90:93], v[156:159], v[216:219], v[90:93]
	s_waitcnt lgkmcnt(1)
	v_mfma_f32_16x16x32_bf16 v[78:81], v[142:145], v[224:227], v[78:81]
	v_mfma_f32_16x16x32_bf16 v[74:77], v[156:159], v[224:227], v[74:77]
	v_mfma_f32_16x16x32_bf16 v[126:129], v[146:149], v[192:195], v[126:129]
	v_mfma_f32_16x16x32_bf16 v[122:125], v[160:163], v[192:195], v[122:125]
	v_mfma_f32_16x16x32_bf16 v[110:113], v[146:149], v[200:203], v[110:113]
	v_mfma_f32_16x16x32_bf16 v[106:109], v[160:163], v[200:203], v[106:109]
	v_mfma_f32_16x16x32_bf16 v[94:97], v[146:149], v[220:223], v[94:97]
	v_mfma_f32_16x16x32_bf16 v[90:93], v[160:163], v[220:223], v[90:93]
	s_waitcnt lgkmcnt(0)
	v_mfma_f32_16x16x32_bf16 v[78:81], v[146:149], v[228:231], v[78:81]
	v_mfma_f32_16x16x32_bf16 v[74:77], v[160:163], v[228:231], v[74:77]
	s_barrier
	s_add_i32 s17, 0, 0x14000
	s_add_i32 s2, s2, s3
	v_add_u32_e32 v0, s17, v153
	v_lshl_add_u64 v[150:151], s[80:81], 0, v[134:135]
	s_mov_b32 m0, s2
	ds_read_b128 v[232:235], v0
	ds_read_b128 v[236:239], v0 offset:1024
	ds_read_b128 v[240:243], v0 offset:2048
	ds_read_b128 v[244:247], v0 offset:3072
	global_load_lds_dwordx4 v[150:151], off
	v_lshl_add_u64 v[164:165], s[80:81], 0, v[130:131]
	s_add_i32 m0, s2, 0x2000
	s_nop 0
	global_load_lds_dwordx4 v[164:165], off
	s_barrier
	s_waitcnt lgkmcnt(4)
	s_waitcnt lgkmcnt(4)
	s_waitcnt lgkmcnt(3)
	v_mfma_f32_16x16x32_bf16 v[118:121], v[232:235], v[188:191], v[118:121]
	s_waitcnt lgkmcnt(1)
	v_mfma_f32_16x16x32_bf16 v[114:117], v[240:243], v[188:191], v[114:117]
	v_mfma_f32_16x16x32_bf16 v[102:105], v[232:235], v[196:199], v[102:105]
	v_mfma_f32_16x16x32_bf16 v[98:101], v[240:243], v[196:199], v[98:101]
	v_mfma_f32_16x16x32_bf16 v[86:89], v[232:235], v[216:219], v[86:89]
	v_mfma_f32_16x16x32_bf16 v[82:85], v[240:243], v[216:219], v[82:85]
	v_mfma_f32_16x16x32_bf16 v[70:73], v[232:235], v[224:227], v[70:73]
	v_mfma_f32_16x16x32_bf16 v[66:69], v[240:243], v[224:227], v[66:69]
	v_mfma_f32_16x16x32_bf16 v[118:121], v[236:239], v[192:195], v[118:121]
	s_waitcnt lgkmcnt(0)
	v_mfma_f32_16x16x32_bf16 v[114:117], v[244:247], v[192:195], v[114:117]
	v_mfma_f32_16x16x32_bf16 v[102:105], v[236:239], v[200:203], v[102:105]
	v_mfma_f32_16x16x32_bf16 v[98:101], v[244:247], v[200:203], v[98:101]
	v_mfma_f32_16x16x32_bf16 v[86:89], v[236:239], v[220:223], v[86:89]
	v_mfma_f32_16x16x32_bf16 v[82:85], v[244:247], v[220:223], v[82:85]
	v_mfma_f32_16x16x32_bf16 v[70:73], v[236:239], v[228:231], v[70:73]
	v_mfma_f32_16x16x32_bf16 v[66:69], v[244:247], v[228:231], v[66:69]
	s_mov_b32 m0, s58
	v_lshl_add_u64 v[204:205], s[82:83], 0, v[136:137]
	s_barrier
	ds_read_b128 v[188:191], v155 offset:16384
	ds_read_b128 v[192:195], v155 offset:17408
	ds_read_b128 v[196:199], v155 offset:18432
	ds_read_b128 v[200:203], v155 offset:19456
	ds_read_b128 v[216:219], v155 offset:20480
	ds_read_b128 v[220:223], v155 offset:21504
	ds_read_b128 v[224:227], v155 offset:22528
	ds_read_b128 v[228:231], v155 offset:23552
	global_load_lds_dwordx4 v[204:205], off
	v_lshl_add_u64 v[248:249], s[82:83], 0, v[132:133]
	s_mov_b32 m0, s69
	s_nop 0
	global_load_lds_dwordx4 v[248:249], off
	s_barrier
	s_waitcnt lgkmcnt(8)
	s_waitcnt lgkmcnt(8)
	s_waitcnt lgkmcnt(7)
	v_mfma_f32_16x16x32_bf16 v[62:65], v[142:145], v[188:191], v[62:65]
	v_mfma_f32_16x16x32_bf16 v[58:61], v[156:159], v[188:191], v[58:61]
	s_waitcnt lgkmcnt(5)
	v_mfma_f32_16x16x32_bf16 v[46:49], v[142:145], v[196:199], v[46:49]
	v_mfma_f32_16x16x32_bf16 v[42:45], v[156:159], v[196:199], v[42:45]
	s_waitcnt lgkmcnt(3)
	v_mfma_f32_16x16x32_bf16 v[30:33], v[142:145], v[216:219], v[30:33]
	v_mfma_f32_16x16x32_bf16 v[26:29], v[156:159], v[216:219], v[26:29]
	s_waitcnt lgkmcnt(1)
	v_mfma_f32_16x16x32_bf16 v[14:17], v[142:145], v[224:227], v[14:17]
	v_mfma_f32_16x16x32_bf16 v[10:13], v[156:159], v[224:227], v[10:13]
	v_mfma_f32_16x16x32_bf16 v[62:65], v[146:149], v[192:195], v[62:65]
	v_mfma_f32_16x16x32_bf16 v[58:61], v[160:163], v[192:195], v[58:61]
	v_mfma_f32_16x16x32_bf16 v[46:49], v[146:149], v[200:203], v[46:49]
	v_mfma_f32_16x16x32_bf16 v[42:45], v[160:163], v[200:203], v[42:45]
	v_mfma_f32_16x16x32_bf16 v[30:33], v[146:149], v[220:223], v[30:33]
	v_mfma_f32_16x16x32_bf16 v[26:29], v[160:163], v[220:223], v[26:29]
	s_waitcnt lgkmcnt(0)
	v_mfma_f32_16x16x32_bf16 v[14:17], v[146:149], v[228:231], v[14:17]
	v_mfma_f32_16x16x32_bf16 v[10:13], v[160:163], v[228:231], v[10:13]
	s_barrier
	s_add_u32 s26, s80, 0x20000
	s_addc_u32 s27, s81, 0
	s_add_i32 s2, s17, s3
	v_lshl_add_u64 v[142:143], s[26:27], 0, v[134:135]
	s_mov_b32 m0, s2
	s_nop 0
	global_load_lds_dwordx4 v[142:143], off
	v_lshl_add_u64 v[142:143], s[26:27], 0, v[130:131]
	s_add_i32 m0, s2, 0x2000
	s_nop 0
	global_load_lds_dwordx4 v[142:143], off
	s_waitcnt vmcnt(6)
	s_barrier
	v_mfma_f32_16x16x32_bf16 v[54:57], v[232:235], v[188:191], v[54:57]
	v_mfma_f32_16x16x32_bf16 v[50:53], v[240:243], v[188:191], v[50:53]
	v_mfma_f32_16x16x32_bf16 v[38:41], v[232:235], v[196:199], v[38:41]
	v_mfma_f32_16x16x32_bf16 v[34:37], v[240:243], v[196:199], v[34:37]
	v_mfma_f32_16x16x32_bf16 v[22:25], v[232:235], v[216:219], v[22:25]
	v_mfma_f32_16x16x32_bf16 v[18:21], v[240:243], v[216:219], v[18:21]
	v_mfma_f32_16x16x32_bf16 v[6:9], v[232:235], v[224:227], v[6:9]
	v_mfma_f32_16x16x32_bf16 v[2:5], v[240:243], v[224:227], v[2:5]
	v_mfma_f32_16x16x32_bf16 v[54:57], v[236:239], v[192:195], v[54:57]
	v_mfma_f32_16x16x32_bf16 v[50:53], v[244:247], v[192:195], v[50:53]
	v_mfma_f32_16x16x32_bf16 v[38:41], v[236:239], v[200:203], v[38:41]
	v_mfma_f32_16x16x32_bf16 v[34:37], v[244:247], v[200:203], v[34:37]
	v_mfma_f32_16x16x32_bf16 v[22:25], v[236:239], v[220:223], v[22:25]
	v_mfma_f32_16x16x32_bf16 v[18:21], v[244:247], v[220:223], v[18:21]
	v_mfma_f32_16x16x32_bf16 v[6:9], v[236:239], v[228:231], v[6:9]
	v_mfma_f32_16x16x32_bf16 v[2:5], v[244:247], v[228:231], v[2:5]
	s_add_i32 s2, 0, 0x18000
	v_add_u32_e32 v0, s2, v153
	s_barrier
	ds_read_b128 v[142:145], v0
	ds_read_b128 v[146:149], v0 offset:1024
	ds_read_b128 v[156:159], v0 offset:2048
	ds_read_b128 v[160:163], v0 offset:3072
	s_add_u32 s26, s82, 0xd0000
	s_addc_u32 s27, s83, 0
	s_mov_b32 m0, s92
	v_lshl_add_u64 v[232:233], s[26:27], 0, v[136:137]
	ds_read_b128 v[188:191], v155 offset:32768
	ds_read_b128 v[192:195], v155 offset:33792
	ds_read_b128 v[196:199], v155 offset:34816
	ds_read_b128 v[200:203], v155 offset:35840
	ds_read_b128 v[216:219], v155 offset:36864
	ds_read_b128 v[220:223], v155 offset:37888
	ds_read_b128 v[224:227], v155 offset:38912
	ds_read_b128 v[228:231], v155 offset:39936
	global_load_lds_dwordx4 v[232:233], off
	v_lshl_add_u64 v[232:233], s[26:27], 0, v[132:133]
	s_mov_b32 m0, s93
	s_nop 0
	global_load_lds_dwordx4 v[232:233], off
	s_waitcnt lgkmcnt(8)
	s_barrier
	s_waitcnt lgkmcnt(12)
	s_waitcnt lgkmcnt(12)
	s_waitcnt lgkmcnt(7)
	v_mfma_f32_16x16x32_bf16 v[126:129], v[142:145], v[188:191], v[126:129]
	v_mfma_f32_16x16x32_bf16 v[122:125], v[156:159], v[188:191], v[122:125]
	s_waitcnt lgkmcnt(5)
	v_mfma_f32_16x16x32_bf16 v[110:113], v[142:145], v[196:199], v[110:113]
	v_mfma_f32_16x16x32_bf16 v[106:109], v[156:159], v[196:199], v[106:109]
	s_waitcnt lgkmcnt(3)
	v_mfma_f32_16x16x32_bf16 v[94:97], v[142:145], v[216:219], v[94:97]
	v_mfma_f32_16x16x32_bf16 v[90:93], v[156:159], v[216:219], v[90:93]
	s_waitcnt lgkmcnt(1)
	v_mfma_f32_16x16x32_bf16 v[78:81], v[142:145], v[224:227], v[78:81]
	v_mfma_f32_16x16x32_bf16 v[74:77], v[156:159], v[224:227], v[74:77]
	v_mfma_f32_16x16x32_bf16 v[126:129], v[146:149], v[192:195], v[126:129]
	v_mfma_f32_16x16x32_bf16 v[122:125], v[160:163], v[192:195], v[122:125]
	v_mfma_f32_16x16x32_bf16 v[110:113], v[146:149], v[200:203], v[110:113]
	v_mfma_f32_16x16x32_bf16 v[106:109], v[160:163], v[200:203], v[106:109]
	v_mfma_f32_16x16x32_bf16 v[94:97], v[146:149], v[220:223], v[94:97]
	v_mfma_f32_16x16x32_bf16 v[90:93], v[160:163], v[220:223], v[90:93]
	s_waitcnt lgkmcnt(0)
	v_mfma_f32_16x16x32_bf16 v[78:81], v[146:149], v[228:231], v[78:81]
	v_mfma_f32_16x16x32_bf16 v[74:77], v[160:163], v[228:231], v[74:77]
	s_barrier
	s_add_i32 s17, 0, 0x1c000
	s_add_i32 s2, s2, s3
	v_add_u32_e32 v0, s17, v153
	v_lshl_add_u64 v[150:151], v[150:151], 0, s[28:29]
	s_mov_b32 m0, s2
	ds_read_b128 v[232:235], v0
	ds_read_b128 v[236:239], v0 offset:1024
	ds_read_b128 v[240:243], v0 offset:2048
	ds_read_b128 v[244:247], v0 offset:3072
	global_load_lds_dwordx4 v[150:151], off
	v_lshl_add_u64 v[150:151], v[164:165], 0, s[28:29]
	s_add_i32 m0, s2, 0x2000
	s_nop 0
	global_load_lds_dwordx4 v[150:151], off
	s_barrier
	s_waitcnt lgkmcnt(4)
	s_waitcnt lgkmcnt(4)
	s_waitcnt lgkmcnt(3)
	v_mfma_f32_16x16x32_bf16 v[118:121], v[232:235], v[188:191], v[118:121]
	s_waitcnt lgkmcnt(1)
	v_mfma_f32_16x16x32_bf16 v[114:117], v[240:243], v[188:191], v[114:117]
	v_mfma_f32_16x16x32_bf16 v[102:105], v[232:235], v[196:199], v[102:105]
	v_mfma_f32_16x16x32_bf16 v[98:101], v[240:243], v[196:199], v[98:101]
	v_mfma_f32_16x16x32_bf16 v[86:89], v[232:235], v[216:219], v[86:89]
	v_mfma_f32_16x16x32_bf16 v[82:85], v[240:243], v[216:219], v[82:85]
	v_mfma_f32_16x16x32_bf16 v[70:73], v[232:235], v[224:227], v[70:73]
	v_mfma_f32_16x16x32_bf16 v[66:69], v[240:243], v[224:227], v[66:69]
	v_mfma_f32_16x16x32_bf16 v[118:121], v[236:239], v[192:195], v[118:121]
	s_waitcnt lgkmcnt(0)
	v_mfma_f32_16x16x32_bf16 v[114:117], v[244:247], v[192:195], v[114:117]
	v_mfma_f32_16x16x32_bf16 v[102:105], v[236:239], v[200:203], v[102:105]
	v_mfma_f32_16x16x32_bf16 v[98:101], v[244:247], v[200:203], v[98:101]
	v_mfma_f32_16x16x32_bf16 v[86:89], v[236:239], v[220:223], v[86:89]
	v_mfma_f32_16x16x32_bf16 v[82:85], v[244:247], v[220:223], v[82:85]
	v_mfma_f32_16x16x32_bf16 v[70:73], v[236:239], v[228:231], v[70:73]
	v_mfma_f32_16x16x32_bf16 v[66:69], v[244:247], v[228:231], v[66:69]
	s_mov_b32 m0, s72
	v_lshl_add_u64 v[150:151], v[204:205], 0, s[28:29]
	s_barrier
	ds_read_b128 v[188:191], v155 offset:49152
	ds_read_b128 v[192:195], v155 offset:50176
	ds_read_b128 v[196:199], v155 offset:51200
	ds_read_b128 v[200:203], v155 offset:52224
	ds_read_b128 v[216:219], v155 offset:53248
	ds_read_b128 v[220:223], v155 offset:54272
	ds_read_b128 v[224:227], v155 offset:55296
	ds_read_b128 v[228:231], v155 offset:56320
	global_load_lds_dwordx4 v[150:151], off
	v_lshl_add_u64 v[150:151], v[248:249], 0, s[28:29]
	s_mov_b32 m0, s73
	s_nop 0
	global_load_lds_dwordx4 v[150:151], off
	s_barrier
	s_waitcnt lgkmcnt(8)
	s_waitcnt lgkmcnt(8)
	s_waitcnt lgkmcnt(7)
	v_mfma_f32_16x16x32_bf16 v[62:65], v[142:145], v[188:191], v[62:65]
	v_mfma_f32_16x16x32_bf16 v[58:61], v[156:159], v[188:191], v[58:61]
	s_waitcnt lgkmcnt(5)
	v_mfma_f32_16x16x32_bf16 v[46:49], v[142:145], v[196:199], v[46:49]
	v_mfma_f32_16x16x32_bf16 v[42:45], v[156:159], v[196:199], v[42:45]
	s_waitcnt lgkmcnt(3)
	v_mfma_f32_16x16x32_bf16 v[30:33], v[142:145], v[216:219], v[30:33]
	v_mfma_f32_16x16x32_bf16 v[26:29], v[156:159], v[216:219], v[26:29]
	s_waitcnt lgkmcnt(1)
	v_mfma_f32_16x16x32_bf16 v[14:17], v[142:145], v[224:227], v[14:17]
	v_mfma_f32_16x16x32_bf16 v[10:13], v[156:159], v[224:227], v[10:13]
	v_mfma_f32_16x16x32_bf16 v[62:65], v[146:149], v[192:195], v[62:65]
	v_mfma_f32_16x16x32_bf16 v[58:61], v[160:163], v[192:195], v[58:61]
	v_mfma_f32_16x16x32_bf16 v[46:49], v[146:149], v[200:203], v[46:49]
	v_mfma_f32_16x16x32_bf16 v[42:45], v[160:163], v[200:203], v[42:45]
	v_mfma_f32_16x16x32_bf16 v[30:33], v[146:149], v[220:223], v[30:33]
	v_mfma_f32_16x16x32_bf16 v[26:29], v[160:163], v[220:223], v[26:29]
	s_waitcnt lgkmcnt(0)
	v_mfma_f32_16x16x32_bf16 v[14:17], v[146:149], v[228:231], v[14:17]
	v_mfma_f32_16x16x32_bf16 v[10:13], v[160:163], v[228:231], v[10:13]
	s_barrier
	s_add_u32 s26, s80, 0x20080
	s_addc_u32 s27, s81, 0
	s_add_i32 s2, s17, s3
	v_lshl_add_u64 v[142:143], s[26:27], 0, v[134:135]
	s_mov_b32 m0, s2
	s_nop 0
	global_load_lds_dwordx4 v[142:143], off
	v_lshl_add_u64 v[142:143], s[26:27], 0, v[130:131]
	s_add_i32 m0, s2, 0x2000
	s_nop 0
	global_load_lds_dwordx4 v[142:143], off
	s_waitcnt vmcnt(6)
	s_barrier
	v_mfma_f32_16x16x32_bf16 v[54:57], v[232:235], v[188:191], v[54:57]
	v_mfma_f32_16x16x32_bf16 v[50:53], v[240:243], v[188:191], v[50:53]
	v_mfma_f32_16x16x32_bf16 v[38:41], v[232:235], v[196:199], v[38:41]
	v_mfma_f32_16x16x32_bf16 v[34:37], v[240:243], v[196:199], v[34:37]
	v_mfma_f32_16x16x32_bf16 v[22:25], v[232:235], v[216:219], v[22:25]
	v_mfma_f32_16x16x32_bf16 v[18:21], v[240:243], v[216:219], v[18:21]
	v_mfma_f32_16x16x32_bf16 v[6:9], v[232:235], v[224:227], v[6:9]
	v_mfma_f32_16x16x32_bf16 v[2:5], v[240:243], v[224:227], v[2:5]
	v_mfma_f32_16x16x32_bf16 v[54:57], v[236:239], v[192:195], v[54:57]
	v_mfma_f32_16x16x32_bf16 v[50:53], v[244:247], v[192:195], v[50:53]
	v_mfma_f32_16x16x32_bf16 v[38:41], v[236:239], v[200:203], v[38:41]
	v_mfma_f32_16x16x32_bf16 v[34:37], v[244:247], v[200:203], v[34:37]
	v_mfma_f32_16x16x32_bf16 v[22:25], v[236:239], v[220:223], v[22:25]
	v_mfma_f32_16x16x32_bf16 v[18:21], v[244:247], v[220:223], v[18:21]
	v_mfma_f32_16x16x32_bf16 v[6:9], v[236:239], v[228:231], v[6:9]
	v_mfma_f32_16x16x32_bf16 v[2:5], v[244:247], v[228:231], v[2:5]
	s_add_i32 s44, s44, 2
	s_add_u32 s25, s25, 0x100
	s_addc_u32 s46, s46, 0
	s_cmp_gt_u32 s44, 5
	s_mov_b64 s[78:79], s[6:7]
	s_barrier
	s_cbranch_scc0 .LBB0_433
	v_lshl_add_u32 v144, s41, 8, v152
	v_ashrrev_i32_e32 v145, 31, v144
	v_lshl_add_u64 v[146:147], v[144:145], 2, s[50:51]
	global_load_dword v216, v[146:147], off
	global_load_dword v217, v[146:147], off offset:64
	global_load_dword v218, v[146:147], off offset:128
	global_load_dword v219, v[146:147], off offset:192
	global_load_dword v220, v[146:147], off offset:512
	global_load_dword v221, v[146:147], off offset:576
	global_load_dword v222, v[146:147], off offset:640
	global_load_dword v223, v[146:147], off offset:704
	v_lshl_or_b32 v142, s40, 8, v154
	s_mov_b32 s2, 0x2aaaaaab
	v_mul_hi_i32 v143, v142, s2
	v_lshlrev_b64 v[148:149], 8, v[144:145]
	v_lshrrev_b32_e32 v145, 31, v143
	v_lshrrev_b32_e32 v143, 5, v143
	v_add_u32_e32 v143, v143, v145
	s_movk_i32 s2, 0xc0
	v_mul_lo_u32 v143, v143, s2
	v_sub_u32_e32 v143, v142, v143
	s_movk_i32 s2, 0x7f
	v_cmp_lt_i32_e32 vcc, s2, v143
	v_add_u32_e32 v143, 0xffffff80, v143
	v_lshl_add_u64 v[148:149], s[20:21], 0, v[148:149]
	s_waitcnt vmcnt(0)
	v_mov_b32_e32 v0, v216
	v_mul_f32_e32 v150, 0x3dd53b94, v0
	v_pk_mul_f32 v[128:129], v[128:129], v[150:151] op_sel_hi:[1,0]
	v_pk_mul_f32 v[126:127], v[126:127], v[150:151] op_sel_hi:[1,0]
	v_pk_mul_f32 v[124:125], v[124:125], v[150:151] op_sel_hi:[1,0]
	v_pk_mul_f32 v[122:123], v[122:123], v[150:151] op_sel_hi:[1,0]
	v_lshrrev_b32_e32 v0, 1, v143
	s_and_saveexec_b64 s[6:7], vcc
	s_cbranch_execz .LBB0_436
	v_lshl_add_u64 v[160:161], v[0:1], 3, v[148:149]
	global_load_dwordx4 v[156:159], v[160:161], off offset:16
	s_nop 0
	global_load_dwordx4 v[160:163], v[160:161], off
	s_waitcnt vmcnt(0)
	v_pk_mul_f32 v[190:191], v[122:123], v[156:157] op_sel:[1,1] op_sel_hi:[0,1]
	v_pk_mul_f32 v[188:189], v[126:127], v[160:161] op_sel:[1,1] op_sel_hi:[0,1]
	v_pk_mul_f32 v[164:165], v[126:127], v[160:161]
	v_pk_fma_f32 v[126:127], v[126:127], v[160:161], v[188:189] op_sel_hi:[1,0,1]
	s_nop 0
	v_mul_f32_e32 v126, v129, v163
	v_pk_fma_f32 v[160:161], v[128:129], v[162:163], v[126:127] op_sel_hi:[1,1,0] neg_lo:[0,0,1] neg_hi:[0,0,1]
	v_mul_f32_e32 v126, v128, v163
	v_pk_fma_f32 v[162:163], v[128:129], v[162:163], v[126:127] op_sel:[1,0,0] op_sel_hi:[0,1,0]
	v_pk_mul_f32 v[128:129], v[122:123], v[156:157]
	v_pk_fma_f32 v[122:123], v[122:123], v[156:157], v[190:191] op_sel_hi:[1,0,1]
	v_sub_f32_e32 v126, v164, v188
	v_mul_f32_e32 v122, v125, v159
	v_pk_fma_f32 v[156:157], v[124:125], v[158:159], v[122:123] op_sel_hi:[1,1,0] neg_lo:[0,0,1] neg_hi:[0,0,1]
	v_mul_f32_e32 v122, v124, v159
	v_pk_fma_f32 v[158:159], v[124:125], v[158:159], v[122:123] op_sel:[1,0,0] op_sel_hi:[0,1,0]
	v_sub_f32_e32 v122, v128, v190
	v_mov_b32_e32 v128, v160
	v_mov_b32_e32 v129, v162
	v_mov_b32_e32 v124, v156
	v_mov_b32_e32 v125, v158

.LBB0_482:
	s_add_u32 s10, s80, 0x100
	s_addc_u32 s11, s81, 0
	s_add_i32 s2, 0, 0x10000
	v_add_u32_e32 v156, s2, v145
	ds_read_b128 v[140:143], v156
	ds_read_b128 v[148:151], v156 offset:1024
	ds_read_b128 v[152:155], v156 offset:2048
	ds_read_b128 v[156:159], v156 offset:3072
	s_cmp_eq_u32 s44, 4
	s_cselect_b32 s93, s77, s11
	s_cselect_b32 s92, s76, s10
	s_cselect_b32 s83, s24, s47
	s_cselect_b32 s82, s25, s46
	v_lshl_add_u64 v[164:165], s[80:81], 0, v[136:137]
	s_add_i32 m0, s58, 0xc000
	ds_read_b128 v[160:163], v147
	ds_read_b128 v[188:191], v147 offset:1024
	ds_read_b128 v[192:195], v147 offset:2048
	ds_read_b128 v[196:199], v147 offset:3072
	ds_read_b128 v[200:203], v147 offset:4096
	ds_read_b128 v[216:219], v147 offset:5120
	ds_read_b128 v[220:223], v147 offset:6144
	ds_read_b128 v[224:227], v147 offset:7168
	global_load_lds_dwordx4 v[164:165], off
	v_lshl_add_u64 v[164:165], s[80:81], 0, v[138:139]
	s_add_i32 m0, s58, 0xe000
	s_nop 0
	global_load_lds_dwordx4 v[164:165], off
	s_waitcnt lgkmcnt(8)
	s_barrier
	s_waitcnt lgkmcnt(12)
	s_waitcnt lgkmcnt(12)
	s_waitcnt lgkmcnt(7)
	v_mfma_f32_16x16x32_bf16 v[126:129], v[140:143], v[160:163], v[126:129]
	v_mfma_f32_16x16x32_bf16 v[122:125], v[152:155], v[160:163], v[122:125]
	s_waitcnt lgkmcnt(5)
	v_mfma_f32_16x16x32_bf16 v[110:113], v[140:143], v[192:195], v[110:113]
	v_mfma_f32_16x16x32_bf16 v[106:109], v[152:155], v[192:195], v[106:109]
	s_waitcnt lgkmcnt(3)
	v_mfma_f32_16x16x32_bf16 v[94:97], v[140:143], v[200:203], v[94:97]
	v_mfma_f32_16x16x32_bf16 v[90:93], v[152:155], v[200:203], v[90:93]
	s_waitcnt lgkmcnt(1)
	v_mfma_f32_16x16x32_bf16 v[78:81], v[140:143], v[220:223], v[78:81]
	v_mfma_f32_16x16x32_bf16 v[74:77], v[152:155], v[220:223], v[74:77]
	v_mfma_f32_16x16x32_bf16 v[126:129], v[148:151], v[188:191], v[126:129]
	v_mfma_f32_16x16x32_bf16 v[122:125], v[156:159], v[188:191], v[122:125]
	v_mfma_f32_16x16x32_bf16 v[110:113], v[148:151], v[196:199], v[110:113]
	v_mfma_f32_16x16x32_bf16 v[106:109], v[156:159], v[196:199], v[106:109]
	v_mfma_f32_16x16x32_bf16 v[94:97], v[148:151], v[216:219], v[94:97]
	v_mfma_f32_16x16x32_bf16 v[90:93], v[156:159], v[216:219], v[90:93]
	s_waitcnt lgkmcnt(0)
	v_mfma_f32_16x16x32_bf16 v[78:81], v[148:151], v[224:227], v[78:81]
	v_mfma_f32_16x16x32_bf16 v[74:77], v[156:159], v[224:227], v[74:77]
	s_barrier
	s_add_i32 s17, 0, 0x14000
	v_add_u32_e32 v164, s17, v145
	s_add_i32 s2, s2, s3
	ds_read_b128 v[228:231], v164
	ds_read_b128 v[232:235], v164 offset:1024
	ds_read_b128 v[236:239], v164 offset:2048
	ds_read_b128 v[240:243], v164 offset:3072
	v_lshl_add_u64 v[164:165], s[82:83], 0, v[0:1]
	s_mov_b32 m0, s2
	v_lshl_add_u64 v[204:205], s[82:83], 0, v[130:131]
	global_load_lds_dwordx4 v[164:165], off
	s_add_i32 m0, s2, 0x2000
	s_nop 0
	global_load_lds_dwordx4 v[204:205], off
	s_barrier
	s_waitcnt lgkmcnt(4)
	s_waitcnt lgkmcnt(4)
	s_waitcnt lgkmcnt(3)
	v_mfma_f32_16x16x32_bf16 v[118:121], v[228:231], v[160:163], v[118:121]
	s_waitcnt lgkmcnt(1)
	v_mfma_f32_16x16x32_bf16 v[114:117], v[236:239], v[160:163], v[114:117]
	v_mfma_f32_16x16x32_bf16 v[102:105], v[228:231], v[192:195], v[102:105]
	v_mfma_f32_16x16x32_bf16 v[98:101], v[236:239], v[192:195], v[98:101]
	v_mfma_f32_16x16x32_bf16 v[86:89], v[228:231], v[200:203], v[86:89]
	v_mfma_f32_16x16x32_bf16 v[82:85], v[236:239], v[200:203], v[82:85]
	v_mfma_f32_16x16x32_bf16 v[70:73], v[228:231], v[220:223], v[70:73]
	v_mfma_f32_16x16x32_bf16 v[66:69], v[236:239], v[220:223], v[66:69]
	v_mfma_f32_16x16x32_bf16 v[118:121], v[232:235], v[188:191], v[118:121]
	s_waitcnt lgkmcnt(0)
	v_mfma_f32_16x16x32_bf16 v[114:117], v[240:243], v[188:191], v[114:117]
	v_mfma_f32_16x16x32_bf16 v[102:105], v[232:235], v[196:199], v[102:105]
	v_mfma_f32_16x16x32_bf16 v[98:101], v[240:243], v[196:199], v[98:101]
	v_mfma_f32_16x16x32_bf16 v[86:89], v[232:235], v[216:219], v[86:89]
	v_mfma_f32_16x16x32_bf16 v[82:85], v[240:243], v[216:219], v[82:85]
	v_mfma_f32_16x16x32_bf16 v[70:73], v[232:235], v[224:227], v[70:73]
	v_mfma_f32_16x16x32_bf16 v[66:69], v[240:243], v[224:227], v[66:69]
	s_mov_b32 m0, s58
	v_lshl_add_u64 v[244:245], s[92:93], 0, v[134:135]
	s_barrier
	ds_read_b128 v[160:163], v147 offset:16384
	ds_read_b128 v[188:191], v147 offset:17408
	ds_read_b128 v[192:195], v147 offset:18432
	ds_read_b128 v[196:199], v147 offset:19456
	ds_read_b128 v[200:203], v147 offset:20480
	ds_read_b128 v[216:219], v147 offset:21504
	ds_read_b128 v[220:223], v147 offset:22528
	ds_read_b128 v[224:227], v147 offset:23552
	global_load_lds_dwordx4 v[244:245], off
	v_lshl_add_u64 v[246:247], s[92:93], 0, v[132:133]
	s_mov_b32 m0, s69
	s_nop 0
	global_load_lds_dwordx4 v[246:247], off
	s_barrier
	s_waitcnt lgkmcnt(8)
	s_waitcnt lgkmcnt(8)
	s_waitcnt lgkmcnt(7)
	v_mfma_f32_16x16x32_bf16 v[62:65], v[140:143], v[160:163], v[62:65]
	v_mfma_f32_16x16x32_bf16 v[58:61], v[152:155], v[160:163], v[58:61]
	s_waitcnt lgkmcnt(5)
	v_mfma_f32_16x16x32_bf16 v[46:49], v[140:143], v[192:195], v[46:49]
	v_mfma_f32_16x16x32_bf16 v[42:45], v[152:155], v[192:195], v[42:45]
	s_waitcnt lgkmcnt(3)
	v_mfma_f32_16x16x32_bf16 v[30:33], v[140:143], v[200:203], v[30:33]
	v_mfma_f32_16x16x32_bf16 v[26:29], v[152:155], v[200:203], v[26:29]
	s_waitcnt lgkmcnt(1)
	v_mfma_f32_16x16x32_bf16 v[14:17], v[140:143], v[220:223], v[14:17]
	v_mfma_f32_16x16x32_bf16 v[10:13], v[152:155], v[220:223], v[10:13]
	v_mfma_f32_16x16x32_bf16 v[62:65], v[148:151], v[188:191], v[62:65]
	v_mfma_f32_16x16x32_bf16 v[58:61], v[156:159], v[188:191], v[58:61]
	v_mfma_f32_16x16x32_bf16 v[46:49], v[148:151], v[196:199], v[46:49]
	v_mfma_f32_16x16x32_bf16 v[42:45], v[156:159], v[196:199], v[42:45]
	v_mfma_f32_16x16x32_bf16 v[30:33], v[148:151], v[216:219], v[30:33]
	v_mfma_f32_16x16x32_bf16 v[26:29], v[156:159], v[216:219], v[26:29]
	s_waitcnt lgkmcnt(0)
	v_mfma_f32_16x16x32_bf16 v[14:17], v[148:151], v[224:227], v[14:17]
	v_mfma_f32_16x16x32_bf16 v[10:13], v[156:159], v[224:227], v[10:13]
	s_barrier
	s_add_u32 s26, s82, 0x20000
	s_addc_u32 s27, s83, 0
	s_add_i32 s2, s17, s3
	v_lshl_add_u64 v[140:141], s[26:27], 0, v[0:1]
	s_mov_b32 m0, s2
	s_nop 0
	global_load_lds_dwordx4 v[140:141], off
	v_lshl_add_u64 v[140:141], s[26:27], 0, v[130:131]
	s_add_i32 m0, s2, 0x2000
	s_nop 0
	global_load_lds_dwordx4 v[140:141], off
	s_waitcnt vmcnt(6)
	s_barrier
	v_mfma_f32_16x16x32_bf16 v[54:57], v[228:231], v[160:163], v[54:57]
	v_mfma_f32_16x16x32_bf16 v[50:53], v[236:239], v[160:163], v[50:53]
	v_mfma_f32_16x16x32_bf16 v[38:41], v[228:231], v[192:195], v[38:41]
	v_mfma_f32_16x16x32_bf16 v[34:37], v[236:239], v[192:195], v[34:37]
	v_mfma_f32_16x16x32_bf16 v[22:25], v[228:231], v[200:203], v[22:25]
	v_mfma_f32_16x16x32_bf16 v[18:21], v[236:239], v[200:203], v[18:21]
	v_mfma_f32_16x16x32_bf16 v[6:9], v[228:231], v[220:223], v[6:9]
	v_mfma_f32_16x16x32_bf16 v[2:5], v[236:239], v[220:223], v[2:5]
	v_mfma_f32_16x16x32_bf16 v[54:57], v[232:235], v[188:191], v[54:57]
	v_mfma_f32_16x16x32_bf16 v[50:53], v[240:243], v[188:191], v[50:53]
	v_mfma_f32_16x16x32_bf16 v[38:41], v[232:235], v[196:199], v[38:41]
	v_mfma_f32_16x16x32_bf16 v[34:37], v[240:243], v[196:199], v[34:37]
	v_mfma_f32_16x16x32_bf16 v[22:25], v[232:235], v[216:219], v[22:25]
	v_mfma_f32_16x16x32_bf16 v[18:21], v[240:243], v[216:219], v[18:21]
	v_mfma_f32_16x16x32_bf16 v[6:9], v[232:235], v[224:227], v[6:9]
	v_mfma_f32_16x16x32_bf16 v[2:5], v[240:243], v[224:227], v[2:5]
	s_add_i32 s2, 0, 0x18000
	v_add_u32_e32 v156, s2, v145
	s_barrier
	ds_read_b128 v[140:143], v156
	ds_read_b128 v[148:151], v156 offset:1024
	ds_read_b128 v[152:155], v156 offset:2048
	ds_read_b128 v[156:159], v156 offset:3072
	s_add_u32 s26, s92, 0xd0000
	s_addc_u32 s27, s93, 0
	s_mov_b32 m0, s70
	v_lshl_add_u64 v[228:229], s[26:27], 0, v[134:135]
	ds_read_b128 v[160:163], v147 offset:32768
	ds_read_b128 v[188:191], v147 offset:33792
	ds_read_b128 v[192:195], v147 offset:34816
	ds_read_b128 v[196:199], v147 offset:35840
	ds_read_b128 v[200:203], v147 offset:36864
	ds_read_b128 v[216:219], v147 offset:37888
	ds_read_b128 v[220:223], v147 offset:38912
	ds_read_b128 v[224:227], v147 offset:39936
	global_load_lds_dwordx4 v[228:229], off
	v_lshl_add_u64 v[228:229], s[26:27], 0, v[132:133]
	s_mov_b32 m0, s71
	s_nop 0
	global_load_lds_dwordx4 v[228:229], off
	s_waitcnt lgkmcnt(8)
	s_barrier
	s_waitcnt lgkmcnt(12)
	s_waitcnt lgkmcnt(12)
	s_waitcnt lgkmcnt(7)
	v_mfma_f32_16x16x32_bf16 v[126:129], v[140:143], v[160:163], v[126:129]
	v_mfma_f32_16x16x32_bf16 v[122:125], v[152:155], v[160:163], v[122:125]
	s_waitcnt lgkmcnt(5)
	v_mfma_f32_16x16x32_bf16 v[110:113], v[140:143], v[192:195], v[110:113]
	v_mfma_f32_16x16x32_bf16 v[106:109], v[152:155], v[192:195], v[106:109]
	s_waitcnt lgkmcnt(3)
	v_mfma_f32_16x16x32_bf16 v[94:97], v[140:143], v[200:203], v[94:97]
	v_mfma_f32_16x16x32_bf16 v[90:93], v[152:155], v[200:203], v[90:93]
	s_waitcnt lgkmcnt(1)
	v_mfma_f32_16x16x32_bf16 v[78:81], v[140:143], v[220:223], v[78:81]
	v_mfma_f32_16x16x32_bf16 v[74:77], v[152:155], v[220:223], v[74:77]
	v_mfma_f32_16x16x32_bf16 v[126:129], v[148:151], v[188:191], v[126:129]
	v_mfma_f32_16x16x32_bf16 v[122:125], v[156:159], v[188:191], v[122:125]
	v_mfma_f32_16x16x32_bf16 v[110:113], v[148:151], v[196:199], v[110:113]
	v_mfma_f32_16x16x32_bf16 v[106:109], v[156:159], v[196:199], v[106:109]
	v_mfma_f32_16x16x32_bf16 v[94:97], v[148:151], v[216:219], v[94:97]
	v_mfma_f32_16x16x32_bf16 v[90:93], v[156:159], v[216:219], v[90:93]
	s_waitcnt lgkmcnt(0)
	v_mfma_f32_16x16x32_bf16 v[78:81], v[148:151], v[224:227], v[78:81]
	v_mfma_f32_16x16x32_bf16 v[74:77], v[156:159], v[224:227], v[74:77]
	s_barrier
	s_add_i32 s17, 0, 0x1c000
	s_add_i32 s2, s2, s3
	v_add_u32_e32 v206, s17, v145
	v_lshl_add_u64 v[164:165], v[164:165], 0, s[28:29]
	s_mov_b32 m0, s2
	ds_read_b128 v[228:231], v206
	ds_read_b128 v[232:235], v206 offset:1024
	ds_read_b128 v[236:239], v206 offset:2048
	ds_read_b128 v[240:243], v206 offset:3072
	global_load_lds_dwordx4 v[164:165], off
	v_lshl_add_u64 v[164:165], v[204:205], 0, s[28:29]
	s_add_i32 m0, s2, 0x2000
	s_nop 0
	global_load_lds_dwordx4 v[164:165], off
	s_barrier
	s_waitcnt lgkmcnt(4)
	s_waitcnt lgkmcnt(4)
	s_waitcnt lgkmcnt(3)
	v_mfma_f32_16x16x32_bf16 v[118:121], v[228:231], v[160:163], v[118:121]
	s_waitcnt lgkmcnt(1)
	v_mfma_f32_16x16x32_bf16 v[114:117], v[236:239], v[160:163], v[114:117]
	v_mfma_f32_16x16x32_bf16 v[102:105], v[228:231], v[192:195], v[102:105]
	v_mfma_f32_16x16x32_bf16 v[98:101], v[236:239], v[192:195], v[98:101]
	v_mfma_f32_16x16x32_bf16 v[86:89], v[228:231], v[200:203], v[86:89]
	v_mfma_f32_16x16x32_bf16 v[82:85], v[236:239], v[200:203], v[82:85]
	v_mfma_f32_16x16x32_bf16 v[70:73], v[228:231], v[220:223], v[70:73]
	v_mfma_f32_16x16x32_bf16 v[66:69], v[236:239], v[220:223], v[66:69]
	v_mfma_f32_16x16x32_bf16 v[118:121], v[232:235], v[188:191], v[118:121]
	s_waitcnt lgkmcnt(0)
	v_mfma_f32_16x16x32_bf16 v[114:117], v[240:243], v[188:191], v[114:117]
	v_mfma_f32_16x16x32_bf16 v[102:105], v[232:235], v[196:199], v[102:105]
	v_mfma_f32_16x16x32_bf16 v[98:101], v[240:243], v[196:199], v[98:101]
	v_mfma_f32_16x16x32_bf16 v[86:89], v[232:235], v[216:219], v[86:89]
	v_mfma_f32_16x16x32_bf16 v[82:85], v[240:243], v[216:219], v[82:85]
	v_mfma_f32_16x16x32_bf16 v[70:73], v[232:235], v[224:227], v[70:73]
	v_mfma_f32_16x16x32_bf16 v[66:69], v[240:243], v[224:227], v[66:69]
	s_mov_b32 m0, s72
	v_lshl_add_u64 v[164:165], v[244:245], 0, s[28:29]
	s_barrier
	ds_read_b128 v[160:163], v147 offset:49152
	ds_read_b128 v[188:191], v147 offset:50176
	ds_read_b128 v[192:195], v147 offset:51200
	ds_read_b128 v[196:199], v147 offset:52224
	ds_read_b128 v[200:203], v147 offset:53248
	ds_read_b128 v[216:219], v147 offset:54272
	ds_read_b128 v[220:223], v147 offset:55296
	ds_read_b128 v[224:227], v147 offset:56320
	global_load_lds_dwordx4 v[164:165], off
	v_lshl_add_u64 v[164:165], v[246:247], 0, s[28:29]
	s_mov_b32 m0, s73
	s_nop 0
	global_load_lds_dwordx4 v[164:165], off
	s_barrier
	s_waitcnt lgkmcnt(8)
	s_waitcnt lgkmcnt(8)
	s_waitcnt lgkmcnt(7)
	v_mfma_f32_16x16x32_bf16 v[62:65], v[140:143], v[160:163], v[62:65]
	v_mfma_f32_16x16x32_bf16 v[58:61], v[152:155], v[160:163], v[58:61]
	s_waitcnt lgkmcnt(5)
	v_mfma_f32_16x16x32_bf16 v[46:49], v[140:143], v[192:195], v[46:49]
	v_mfma_f32_16x16x32_bf16 v[42:45], v[152:155], v[192:195], v[42:45]
	s_waitcnt lgkmcnt(3)
	v_mfma_f32_16x16x32_bf16 v[30:33], v[140:143], v[200:203], v[30:33]
	v_mfma_f32_16x16x32_bf16 v[26:29], v[152:155], v[200:203], v[26:29]
	s_waitcnt lgkmcnt(1)
	v_mfma_f32_16x16x32_bf16 v[14:17], v[140:143], v[220:223], v[14:17]
	v_mfma_f32_16x16x32_bf16 v[10:13], v[152:155], v[220:223], v[10:13]
	v_mfma_f32_16x16x32_bf16 v[62:65], v[148:151], v[188:191], v[62:65]
	v_mfma_f32_16x16x32_bf16 v[58:61], v[156:159], v[188:191], v[58:61]
	v_mfma_f32_16x16x32_bf16 v[46:49], v[148:151], v[196:199], v[46:49]
	v_mfma_f32_16x16x32_bf16 v[42:45], v[156:159], v[196:199], v[42:45]
	v_mfma_f32_16x16x32_bf16 v[30:33], v[148:151], v[216:219], v[30:33]
	v_mfma_f32_16x16x32_bf16 v[26:29], v[156:159], v[216:219], v[26:29]
	s_waitcnt lgkmcnt(0)
	v_mfma_f32_16x16x32_bf16 v[14:17], v[148:151], v[224:227], v[14:17]
	v_mfma_f32_16x16x32_bf16 v[10:13], v[156:159], v[224:227], v[10:13]
	s_barrier
	s_add_u32 s26, s82, 0x20080
	s_addc_u32 s27, s83, 0
	s_add_i32 s2, s17, s3
	v_lshl_add_u64 v[140:141], s[26:27], 0, v[0:1]
	s_mov_b32 m0, s2
	s_nop 0
	global_load_lds_dwordx4 v[140:141], off
	v_lshl_add_u64 v[140:141], s[26:27], 0, v[130:131]
	s_add_i32 m0, s2, 0x2000
	s_nop 0
	global_load_lds_dwordx4 v[140:141], off
	s_waitcnt vmcnt(6)
	s_barrier
	v_mfma_f32_16x16x32_bf16 v[54:57], v[228:231], v[160:163], v[54:57]
	v_mfma_f32_16x16x32_bf16 v[50:53], v[236:239], v[160:163], v[50:53]
	v_mfma_f32_16x16x32_bf16 v[38:41], v[228:231], v[192:195], v[38:41]
	v_mfma_f32_16x16x32_bf16 v[34:37], v[236:239], v[192:195], v[34:37]
	v_mfma_f32_16x16x32_bf16 v[22:25], v[228:231], v[200:203], v[22:25]
	v_mfma_f32_16x16x32_bf16 v[18:21], v[236:239], v[200:203], v[18:21]
	v_mfma_f32_16x16x32_bf16 v[6:9], v[228:231], v[220:223], v[6:9]
	v_mfma_f32_16x16x32_bf16 v[2:5], v[236:239], v[220:223], v[2:5]
	v_mfma_f32_16x16x32_bf16 v[54:57], v[232:235], v[188:191], v[54:57]
	v_mfma_f32_16x16x32_bf16 v[50:53], v[240:243], v[188:191], v[50:53]
	v_mfma_f32_16x16x32_bf16 v[38:41], v[232:235], v[196:199], v[38:41]
	v_mfma_f32_16x16x32_bf16 v[34:37], v[240:243], v[196:199], v[34:37]
	v_mfma_f32_16x16x32_bf16 v[22:25], v[232:235], v[216:219], v[22:25]
	v_mfma_f32_16x16x32_bf16 v[18:21], v[240:243], v[216:219], v[18:21]
	v_mfma_f32_16x16x32_bf16 v[6:9], v[232:235], v[224:227], v[6:9]
	v_mfma_f32_16x16x32_bf16 v[2:5], v[240:243], v[224:227], v[2:5]
	s_add_i32 s44, s44, 2
	s_add_u32 s46, s46, 0x100
	s_addc_u32 s47, s47, 0
	s_cmp_gt_u32 s44, 5
	s_mov_b64 s[80:81], s[10:11]
	s_barrier
	s_cbranch_scc0 .LBB0_482
	v_lshl_add_u32 v142, s63, 8, v144
	v_ashrrev_i32_e32 v143, 31, v142
	v_lshl_add_u64 v[140:141], v[142:143], 2, s[38:39]
	global_load_dword v216, v[140:141], off
	global_load_dword v218, v[140:141], off offset:64
	global_load_dword v220, v[140:141], off offset:128
	global_load_dword v222, v[140:141], off offset:192
	global_load_dword v224, v[140:141], off offset:512
	global_load_dword v226, v[140:141], off offset:576
	global_load_dword v228, v[140:141], off offset:640
	global_load_dword v230, v[140:141], off offset:704
	v_lshl_or_b32 v148, s62, 8, v146
	v_ashrrev_i32_e32 v149, 31, v148
	s_mov_b32 s2, 0x80000
	s_mov_b64 s[4:5], 0x80000
	s_mov_b32 s62, s74
	s_mov_b32 s63, s41
	s_mov_b64 s[82:83], s[78:79]
	s_mov_b64 s[80:81], s[76:77]
	v_readlane_b32 s93, v251, 60
	s_waitcnt vmcnt(7)
	v_mov_b32_e32 v150, v216
	v_pk_mul_f32 v[128:129], v[128:129], v[150:151] op_sel_hi:[1,0]
	v_pk_mul_f32 v[126:127], v[126:127], v[150:151] op_sel_hi:[1,0]
	v_pk_mul_f32 v[122:123], v[122:123], v[150:151] op_sel_hi:[1,0]
	v_pk_mul_f32 v[124:125], v[124:125], v[150:151] op_sel_hi:[1,0]
	v_cvt_pk_bf16_f32 v126, v126, v127
	v_cvt_pk_bf16_f32 v127, v128, v129
	v_cvt_pk_bf16_f32 v128, v122, v123
	v_lshlrev_b64 v[122:123], 12, v[142:143]
	v_cvt_pk_bf16_f32 v129, v124, v125
	v_lshl_add_u64 v[122:123], s[56:57], 0, v[122:123]
	v_lshlrev_b64 v[124:125], 1, v[148:149]
	v_lshl_add_u64 v[122:123], v[122:123], 0, v[124:125]
	global_store_dwordx4 v[122:123], v[126:129], off
	v_pk_mul_f32 v[120:121], v[120:121], v[150:151] op_sel_hi:[1,0]
	v_pk_mul_f32 v[118:119], v[118:119], v[150:151] op_sel_hi:[1,0]
	v_pk_mul_f32 v[126:127], v[116:117], v[150:151] op_sel_hi:[1,0]
	v_pk_mul_f32 v[116:117], v[114:115], v[150:151] op_sel_hi:[1,0]
	v_cvt_pk_bf16_f32 v114, v118, v119
	v_cvt_pk_bf16_f32 v115, v120, v121
	v_cvt_pk_bf16_f32 v116, v116, v117
	v_cvt_pk_bf16_f32 v117, v126, v127
	global_store_dwordx4 v[122:123], v[114:117], off offset:256
	s_nop 1
	v_or_b32_e32 v114, 16, v142
	v_ashrrev_i32_e32 v115, 31, v114
	v_lshl_add_u64 v[116:117], v[114:115], 2, s[38:39]
	s_waitcnt vmcnt(8)
	v_mov_b32_e32 v116, v218
	v_pk_mul_f32 v[110:111], v[110:111], v[116:117] op_sel_hi:[1,0]
	v_pk_mul_f32 v[118:119], v[108:109], v[116:117] op_sel_hi:[1,0]
	v_pk_mul_f32 v[108:109], v[106:107], v[116:117] op_sel_hi:[1,0]
	v_cvt_pk_bf16_f32 v106, v110, v111
	v_lshlrev_b64 v[110:111], 12, v[114:115]
	v_pk_mul_f32 v[112:113], v[112:113], v[116:117] op_sel_hi:[1,0]
	v_lshl_add_u64 v[110:111], s[56:57], 0, v[110:111]
	v_cvt_pk_bf16_f32 v107, v112, v113
	v_cvt_pk_bf16_f32 v108, v108, v109
	v_cvt_pk_bf16_f32 v109, v118, v119
	v_lshl_add_u64 v[110:111], v[110:111], 0, v[124:125]
	global_store_dwordx4 v[110:111], v[106:109], off
	v_pk_mul_f32 v[104:105], v[104:105], v[116:117] op_sel_hi:[1,0]
	v_pk_mul_f32 v[102:103], v[102:103], v[116:117] op_sel_hi:[1,0]
	v_pk_mul_f32 v[106:107], v[100:101], v[116:117] op_sel_hi:[1,0]
	v_pk_mul_f32 v[100:101], v[98:99], v[116:117] op_sel_hi:[1,0]
	v_cvt_pk_bf16_f32 v98, v102, v103
	v_cvt_pk_bf16_f32 v99, v104, v105
	v_cvt_pk_bf16_f32 v100, v100, v101
	v_cvt_pk_bf16_f32 v101, v106, v107
	global_store_dwordx4 v[110:111], v[98:101], off offset:256
	s_nop 1
	v_or_b32_e32 v98, 32, v142
	v_ashrrev_i32_e32 v99, 31, v98
	v_lshl_add_u64 v[100:101], v[98:99], 2, s[38:39]
	s_waitcnt vmcnt(9)
	v_mov_b32_e32 v100, v220
	v_pk_mul_f32 v[94:95], v[94:95], v[100:101] op_sel_hi:[1,0]
	v_pk_mul_f32 v[102:103], v[92:93], v[100:101] op_sel_hi:[1,0]
	v_pk_mul_f32 v[92:93], v[90:91], v[100:101] op_sel_hi:[1,0]
	v_cvt_pk_bf16_f32 v90, v94, v95
	v_lshlrev_b64 v[94:95], 12, v[98:99]
	v_pk_mul_f32 v[96:97], v[96:97], v[100:101] op_sel_hi:[1,0]
	v_lshl_add_u64 v[94:95], s[56:57], 0, v[94:95]
	v_cvt_pk_bf16_f32 v91, v96, v97
	v_cvt_pk_bf16_f32 v92, v92, v93
	v_cvt_pk_bf16_f32 v93, v102, v103
	v_lshl_add_u64 v[94:95], v[94:95], 0, v[124:125]
	global_store_dwordx4 v[94:95], v[90:93], off
	v_pk_mul_f32 v[88:89], v[88:89], v[100:101] op_sel_hi:[1,0]
	v_pk_mul_f32 v[86:87], v[86:87], v[100:101] op_sel_hi:[1,0]
	v_pk_mul_f32 v[90:91], v[84:85], v[100:101] op_sel_hi:[1,0]
	v_pk_mul_f32 v[84:85], v[82:83], v[100:101] op_sel_hi:[1,0]
	v_cvt_pk_bf16_f32 v82, v86, v87
	v_cvt_pk_bf16_f32 v83, v88, v89
	v_cvt_pk_bf16_f32 v84, v84, v85
	v_cvt_pk_bf16_f32 v85, v90, v91
	global_store_dwordx4 v[94:95], v[82:85], off offset:256
	s_nop 1
	v_or_b32_e32 v82, 48, v142
	v_ashrrev_i32_e32 v83, 31, v82
	v_lshl_add_u64 v[84:85], v[82:83], 2, s[38:39]
	s_waitcnt vmcnt(10)
	v_mov_b32_e32 v84, v222
	v_pk_mul_f32 v[78:79], v[78:79], v[84:85] op_sel_hi:[1,0]
	v_pk_mul_f32 v[86:87], v[76:77], v[84:85] op_sel_hi:[1,0]
	v_pk_mul_f32 v[76:77], v[74:75], v[84:85] op_sel_hi:[1,0]
	v_cvt_pk_bf16_f32 v74, v78, v79
	v_lshlrev_b64 v[78:79], 12, v[82:83]
	v_pk_mul_f32 v[80:81], v[80:81], v[84:85] op_sel_hi:[1,0]
	v_lshl_add_u64 v[78:79], s[56:57], 0, v[78:79]
	v_cvt_pk_bf16_f32 v75, v80, v81
	v_cvt_pk_bf16_f32 v76, v76, v77
	v_cvt_pk_bf16_f32 v77, v86, v87
	v_lshl_add_u64 v[78:79], v[78:79], 0, v[124:125]
	global_store_dwordx4 v[78:79], v[74:77], off
	v_pk_mul_f32 v[72:73], v[72:73], v[84:85] op_sel_hi:[1,0]
	v_pk_mul_f32 v[70:71], v[70:71], v[84:85] op_sel_hi:[1,0]
	v_pk_mul_f32 v[74:75], v[68:69], v[84:85] op_sel_hi:[1,0]
	v_pk_mul_f32 v[68:69], v[66:67], v[84:85] op_sel_hi:[1,0]
	v_cvt_pk_bf16_f32 v66, v70, v71
	v_cvt_pk_bf16_f32 v67, v72, v73
	v_cvt_pk_bf16_f32 v68, v68, v69
	v_cvt_pk_bf16_f32 v69, v74, v75
	global_store_dwordx4 v[78:79], v[66:69], off offset:256
	s_waitcnt vmcnt(11)
	v_mov_b32_e32 v66, v224
	v_pk_mul_f32 v[64:65], v[64:65], v[66:67] op_sel_hi:[1,0]
	v_pk_mul_f32 v[62:63], v[62:63], v[66:67] op_sel_hi:[1,0]
	v_pk_mul_f32 v[68:69], v[60:61], v[66:67] op_sel_hi:[1,0]
	v_pk_mul_f32 v[60:61], v[58:59], v[66:67] op_sel_hi:[1,0]
	v_cvt_pk_bf16_f32 v59, v64, v65
	v_add_co_u32_e32 v64, vcc, s2, v122
	v_cvt_pk_bf16_f32 v58, v62, v63
	v_cvt_pk_bf16_f32 v60, v60, v61
	v_cvt_pk_bf16_f32 v61, v68, v69
	v_addc_co_u32_e32 v65, vcc, 0, v123, vcc
	global_store_dwordx4 v[64:65], v[58:61], off
	v_pk_mul_f32 v[56:57], v[56:57], v[66:67] op_sel_hi:[1,0]
	v_pk_mul_f32 v[54:55], v[54:55], v[66:67] op_sel_hi:[1,0]
	v_pk_mul_f32 v[58:59], v[52:53], v[66:67] op_sel_hi:[1,0]
	v_pk_mul_f32 v[52:53], v[50:51], v[66:67] op_sel_hi:[1,0]
	v_lshl_add_u64 v[62:63], v[122:123], 0, s[4:5]
	v_cvt_pk_bf16_f32 v50, v54, v55
	v_cvt_pk_bf16_f32 v51, v56, v57
	v_cvt_pk_bf16_f32 v52, v52, v53
	v_cvt_pk_bf16_f32 v53, v58, v59
	global_store_dwordx4 v[62:63], v[50:53], off offset:256
	s_mov_b32 s2, 0x90000
	s_mov_b64 s[4:5], 0x90000
	s_waitcnt vmcnt(12)
	v_mov_b32_e32 v50, v226
	v_pk_mul_f32 v[48:49], v[48:49], v[50:51] op_sel_hi:[1,0]
	v_pk_mul_f32 v[46:47], v[46:47], v[50:51] op_sel_hi:[1,0]
	v_pk_mul_f32 v[52:53], v[44:45], v[50:51] op_sel_hi:[1,0]
	v_pk_mul_f32 v[44:45], v[42:43], v[50:51] op_sel_hi:[1,0]
	v_cvt_pk_bf16_f32 v43, v48, v49
	v_add_co_u32_e32 v48, vcc, s2, v122
	v_cvt_pk_bf16_f32 v42, v46, v47
	v_cvt_pk_bf16_f32 v44, v44, v45
	v_cvt_pk_bf16_f32 v45, v52, v53
	v_addc_co_u32_e32 v49, vcc, 0, v123, vcc
	global_store_dwordx4 v[48:49], v[42:45], off
	v_pk_mul_f32 v[40:41], v[40:41], v[50:51] op_sel_hi:[1,0]
	v_pk_mul_f32 v[38:39], v[38:39], v[50:51] op_sel_hi:[1,0]
	v_pk_mul_f32 v[42:43], v[36:37], v[50:51] op_sel_hi:[1,0]
	v_pk_mul_f32 v[36:37], v[34:35], v[50:51] op_sel_hi:[1,0]
	v_lshl_add_u64 v[46:47], v[122:123], 0, s[4:5]
	v_cvt_pk_bf16_f32 v34, v38, v39
	v_cvt_pk_bf16_f32 v35, v40, v41
	v_cvt_pk_bf16_f32 v36, v36, v37
	v_cvt_pk_bf16_f32 v37, v42, v43
	global_store_dwordx4 v[46:47], v[34:37], off offset:256
	s_mov_b32 s2, 0xa0000
	s_mov_b64 s[4:5], 0xa0000
	s_waitcnt vmcnt(13)
	v_mov_b32_e32 v34, v228
	v_pk_mul_f32 v[32:33], v[32:33], v[34:35] op_sel_hi:[1,0]
	v_pk_mul_f32 v[30:31], v[30:31], v[34:35] op_sel_hi:[1,0]
	v_pk_mul_f32 v[36:37], v[28:29], v[34:35] op_sel_hi:[1,0]
	v_pk_mul_f32 v[28:29], v[26:27], v[34:35] op_sel_hi:[1,0]
	v_cvt_pk_bf16_f32 v27, v32, v33
	v_add_co_u32_e32 v32, vcc, s2, v122
	v_cvt_pk_bf16_f32 v26, v30, v31
	v_cvt_pk_bf16_f32 v28, v28, v29
	v_cvt_pk_bf16_f32 v29, v36, v37
	v_addc_co_u32_e32 v33, vcc, 0, v123, vcc
	global_store_dwordx4 v[32:33], v[26:29], off
	v_pk_mul_f32 v[24:25], v[24:25], v[34:35] op_sel_hi:[1,0]
	v_pk_mul_f32 v[22:23], v[22:23], v[34:35] op_sel_hi:[1,0]
	v_pk_mul_f32 v[26:27], v[20:21], v[34:35] op_sel_hi:[1,0]
	v_pk_mul_f32 v[20:21], v[18:19], v[34:35] op_sel_hi:[1,0]
	v_lshl_add_u64 v[30:31], v[122:123], 0, s[4:5]
	v_cvt_pk_bf16_f32 v18, v22, v23
	v_cvt_pk_bf16_f32 v19, v24, v25
	v_cvt_pk_bf16_f32 v20, v20, v21
	v_cvt_pk_bf16_f32 v21, v26, v27
	global_store_dwordx4 v[30:31], v[18:21], off offset:256
	s_mov_b32 s2, 0xb0000
	s_mov_b64 s[4:5], 0xb0000
	s_waitcnt vmcnt(14)
	v_mov_b32_e32 v18, v230
	v_pk_mul_f32 v[16:17], v[16:17], v[18:19] op_sel_hi:[1,0]
	v_pk_mul_f32 v[14:15], v[14:15], v[18:19] op_sel_hi:[1,0]
	v_pk_mul_f32 v[20:21], v[12:13], v[18:19] op_sel_hi:[1,0]
	v_pk_mul_f32 v[12:13], v[10:11], v[18:19] op_sel_hi:[1,0]
	v_cvt_pk_bf16_f32 v11, v16, v17
	v_add_co_u32_e32 v16, vcc, s2, v122
	v_cvt_pk_bf16_f32 v10, v14, v15
	v_cvt_pk_bf16_f32 v12, v12, v13
	v_cvt_pk_bf16_f32 v13, v20, v21
	v_addc_co_u32_e32 v17, vcc, 0, v123, vcc
	global_store_dwordx4 v[16:17], v[10:13], off
	v_pk_mul_f32 v[8:9], v[8:9], v[18:19] op_sel_hi:[1,0]
	v_pk_mul_f32 v[6:7], v[6:7], v[18:19] op_sel_hi:[1,0]
	v_pk_mul_f32 v[10:11], v[4:5], v[18:19] op_sel_hi:[1,0]
	v_pk_mul_f32 v[4:5], v[2:3], v[18:19] op_sel_hi:[1,0]
	v_lshl_add_u64 v[14:15], v[122:123], 0, s[4:5]
	v_cvt_pk_bf16_f32 v2, v6, v7
	v_cvt_pk_bf16_f32 v3, v8, v9
	v_cvt_pk_bf16_f32 v4, v4, v5
	v_cvt_pk_bf16_f32 v5, v10, v11
	s_and_b64 vcc, exec, s[6:7]
	global_store_dwordx4 v[14:15], v[2:5], off offset:256
	s_cbranch_vccz .LBB0_473
	v_readlane_b32 s4, v254, 12
	s_waitcnt vmcnt(0)
	v_readlane_b32 s5, v254, 13
	v_readlane_b32 s84, v251, 38
	v_readlane_b32 s18, v253, 0
	s_andn2_b64 vcc, exec, s[4:5]
	v_readlane_b32 s85, v251, 39
	v_readlane_b32 s86, v251, 40
	v_readlane_b32 s87, v251, 41
	v_readlane_b32 s14, v250, 63
	v_readlane_b32 s19, v253, 1
	s_cbranch_vccnz .LBB0_486
	s_barrier

.LBB0_500:
	s_add_u32 s2, s6, 0xfffe0080
	s_addc_u32 s17, s7, -1
	s_add_i32 s26, 0, 0x10000
	v_add_u32_e32 v156, s26, v145
	ds_read_b128 v[140:143], v156
	ds_read_b128 v[148:151], v156 offset:1024
	ds_read_b128 v[152:155], v156 offset:2048
	ds_read_b128 v[156:159], v156 offset:3072
	s_cmp_eq_u32 s44, 4
	s_cselect_b32 s81, s11, s17
	s_cselect_b32 s80, s24, s2
	s_cselect_b32 s79, s75, s46
	s_cselect_b32 s78, s74, s25
	v_lshl_add_u64 v[164:165], s[6:7], 0, v[136:137]
	s_add_i32 m0, s58, 0xc000
	ds_read_b128 v[160:163], v147
	ds_read_b128 v[188:191], v147 offset:1024
	ds_read_b128 v[192:195], v147 offset:2048
	ds_read_b128 v[196:199], v147 offset:3072
	ds_read_b128 v[200:203], v147 offset:4096
	ds_read_b128 v[216:219], v147 offset:5120
	ds_read_b128 v[220:223], v147 offset:6144
	ds_read_b128 v[224:227], v147 offset:7168
	global_load_lds_dwordx4 v[164:165], off
	v_lshl_add_u64 v[164:165], s[6:7], 0, v[138:139]
	s_add_i32 m0, s58, 0xe000
	s_nop 0
	global_load_lds_dwordx4 v[164:165], off
	s_waitcnt lgkmcnt(8)
	s_barrier
	s_waitcnt lgkmcnt(12)
	s_waitcnt lgkmcnt(12)
	s_waitcnt lgkmcnt(7)
	v_mfma_f32_16x16x32_bf16 v[126:129], v[140:143], v[160:163], v[126:129]
	v_mfma_f32_16x16x32_bf16 v[122:125], v[152:155], v[160:163], v[122:125]
	s_waitcnt lgkmcnt(5)
	v_mfma_f32_16x16x32_bf16 v[110:113], v[140:143], v[192:195], v[110:113]
	v_mfma_f32_16x16x32_bf16 v[106:109], v[152:155], v[192:195], v[106:109]
	s_waitcnt lgkmcnt(3)
	v_mfma_f32_16x16x32_bf16 v[94:97], v[140:143], v[200:203], v[94:97]
	v_mfma_f32_16x16x32_bf16 v[90:93], v[152:155], v[200:203], v[90:93]
	s_waitcnt lgkmcnt(1)
	v_mfma_f32_16x16x32_bf16 v[78:81], v[140:143], v[220:223], v[78:81]
	v_mfma_f32_16x16x32_bf16 v[74:77], v[152:155], v[220:223], v[74:77]
	v_mfma_f32_16x16x32_bf16 v[126:129], v[148:151], v[188:191], v[126:129]
	v_mfma_f32_16x16x32_bf16 v[122:125], v[156:159], v[188:191], v[122:125]
	v_mfma_f32_16x16x32_bf16 v[110:113], v[148:151], v[196:199], v[110:113]
	v_mfma_f32_16x16x32_bf16 v[106:109], v[156:159], v[196:199], v[106:109]
	v_mfma_f32_16x16x32_bf16 v[94:97], v[148:151], v[216:219], v[94:97]
	v_mfma_f32_16x16x32_bf16 v[90:93], v[156:159], v[216:219], v[90:93]
	s_waitcnt lgkmcnt(0)
	v_mfma_f32_16x16x32_bf16 v[78:81], v[148:151], v[224:227], v[78:81]
	v_mfma_f32_16x16x32_bf16 v[74:77], v[156:159], v[224:227], v[74:77]
	s_barrier
	s_add_i32 s2, 0, 0x14000
	v_add_u32_e32 v164, s2, v145
	s_add_i32 s17, s26, s3
	ds_read_b128 v[228:231], v164
	ds_read_b128 v[232:235], v164 offset:1024
	ds_read_b128 v[236:239], v164 offset:2048
	ds_read_b128 v[240:243], v164 offset:3072
	v_lshl_add_u64 v[164:165], s[78:79], 0, v[0:1]
	s_mov_b32 m0, s17
	v_lshl_add_u64 v[204:205], s[78:79], 0, v[130:131]
	global_load_lds_dwordx4 v[164:165], off
	s_add_i32 m0, s17, 0x2000
	s_nop 0
	global_load_lds_dwordx4 v[204:205], off
	s_barrier
	s_waitcnt lgkmcnt(4)
	s_waitcnt lgkmcnt(4)
	s_waitcnt lgkmcnt(3)
	v_mfma_f32_16x16x32_bf16 v[118:121], v[228:231], v[160:163], v[118:121]
	s_waitcnt lgkmcnt(1)
	v_mfma_f32_16x16x32_bf16 v[114:117], v[236:239], v[160:163], v[114:117]
	v_mfma_f32_16x16x32_bf16 v[102:105], v[228:231], v[192:195], v[102:105]
	v_mfma_f32_16x16x32_bf16 v[98:101], v[236:239], v[192:195], v[98:101]
	v_mfma_f32_16x16x32_bf16 v[86:89], v[228:231], v[200:203], v[86:89]
	v_mfma_f32_16x16x32_bf16 v[82:85], v[236:239], v[200:203], v[82:85]
	v_mfma_f32_16x16x32_bf16 v[70:73], v[228:231], v[220:223], v[70:73]
	v_mfma_f32_16x16x32_bf16 v[66:69], v[236:239], v[220:223], v[66:69]
	v_mfma_f32_16x16x32_bf16 v[118:121], v[232:235], v[188:191], v[118:121]
	s_waitcnt lgkmcnt(0)
	v_mfma_f32_16x16x32_bf16 v[114:117], v[240:243], v[188:191], v[114:117]
	v_mfma_f32_16x16x32_bf16 v[102:105], v[232:235], v[196:199], v[102:105]
	v_mfma_f32_16x16x32_bf16 v[98:101], v[240:243], v[196:199], v[98:101]
	v_mfma_f32_16x16x32_bf16 v[86:89], v[232:235], v[216:219], v[86:89]
	v_mfma_f32_16x16x32_bf16 v[82:85], v[240:243], v[216:219], v[82:85]
	v_mfma_f32_16x16x32_bf16 v[70:73], v[232:235], v[224:227], v[70:73]
	v_mfma_f32_16x16x32_bf16 v[66:69], v[240:243], v[224:227], v[66:69]
	s_mov_b32 m0, s58
	v_lshl_add_u64 v[244:245], s[80:81], 0, v[134:135]
	s_barrier
	ds_read_b128 v[160:163], v147 offset:16384
	ds_read_b128 v[188:191], v147 offset:17408
	ds_read_b128 v[192:195], v147 offset:18432
	ds_read_b128 v[196:199], v147 offset:19456
	ds_read_b128 v[200:203], v147 offset:20480
	ds_read_b128 v[216:219], v147 offset:21504
	ds_read_b128 v[220:223], v147 offset:22528
	ds_read_b128 v[224:227], v147 offset:23552
	global_load_lds_dwordx4 v[244:245], off
	v_lshl_add_u64 v[246:247], s[80:81], 0, v[132:133]
	s_mov_b32 m0, s69
	s_nop 0
	global_load_lds_dwordx4 v[246:247], off
	s_barrier
	s_waitcnt lgkmcnt(8)
	s_waitcnt lgkmcnt(8)
	s_waitcnt lgkmcnt(7)
	v_mfma_f32_16x16x32_bf16 v[62:65], v[140:143], v[160:163], v[62:65]
	v_mfma_f32_16x16x32_bf16 v[58:61], v[152:155], v[160:163], v[58:61]
	s_waitcnt lgkmcnt(5)
	v_mfma_f32_16x16x32_bf16 v[54:57], v[140:143], v[192:195], v[54:57]
	v_mfma_f32_16x16x32_bf16 v[46:49], v[152:155], v[192:195], v[46:49]
	s_waitcnt lgkmcnt(3)
	v_mfma_f32_16x16x32_bf16 v[38:41], v[140:143], v[200:203], v[38:41]
	v_mfma_f32_16x16x32_bf16 v[30:33], v[152:155], v[200:203], v[30:33]
	s_waitcnt lgkmcnt(1)
	v_mfma_f32_16x16x32_bf16 v[22:25], v[140:143], v[220:223], v[22:25]
	v_mfma_f32_16x16x32_bf16 v[14:17], v[152:155], v[220:223], v[14:17]
	v_mfma_f32_16x16x32_bf16 v[62:65], v[148:151], v[188:191], v[62:65]
	v_mfma_f32_16x16x32_bf16 v[58:61], v[156:159], v[188:191], v[58:61]
	v_mfma_f32_16x16x32_bf16 v[54:57], v[148:151], v[196:199], v[54:57]
	v_mfma_f32_16x16x32_bf16 v[46:49], v[156:159], v[196:199], v[46:49]
	v_mfma_f32_16x16x32_bf16 v[38:41], v[148:151], v[216:219], v[38:41]
	v_mfma_f32_16x16x32_bf16 v[30:33], v[156:159], v[216:219], v[30:33]
	s_waitcnt lgkmcnt(0)
	v_mfma_f32_16x16x32_bf16 v[22:25], v[148:151], v[224:227], v[22:25]
	v_mfma_f32_16x16x32_bf16 v[14:17], v[156:159], v[224:227], v[14:17]
	s_barrier
	s_add_u32 s26, s78, 0xd0000
	s_addc_u32 s27, s79, 0
	s_add_i32 s2, s2, s3
	v_lshl_add_u64 v[140:141], s[26:27], 0, v[0:1]
	s_mov_b32 m0, s2
	s_nop 0
	global_load_lds_dwordx4 v[140:141], off
	v_lshl_add_u64 v[140:141], s[26:27], 0, v[130:131]
	s_add_i32 m0, s2, 0x2000
	s_nop 0
	global_load_lds_dwordx4 v[140:141], off
	s_waitcnt vmcnt(6)
	s_barrier
	v_mfma_f32_16x16x32_bf16 v[50:53], v[228:231], v[160:163], v[50:53]
	v_mfma_f32_16x16x32_bf16 v[42:45], v[236:239], v[160:163], v[42:45]
	v_mfma_f32_16x16x32_bf16 v[34:37], v[228:231], v[192:195], v[34:37]
	v_mfma_f32_16x16x32_bf16 v[26:29], v[236:239], v[192:195], v[26:29]
	v_mfma_f32_16x16x32_bf16 v[18:21], v[228:231], v[200:203], v[18:21]
	v_mfma_f32_16x16x32_bf16 v[10:13], v[236:239], v[200:203], v[10:13]
	v_mfma_f32_16x16x32_bf16 v[6:9], v[228:231], v[220:223], v[6:9]
	v_mfma_f32_16x16x32_bf16 v[2:5], v[236:239], v[220:223], v[2:5]
	v_mfma_f32_16x16x32_bf16 v[50:53], v[232:235], v[188:191], v[50:53]
	v_mfma_f32_16x16x32_bf16 v[42:45], v[240:243], v[188:191], v[42:45]
	v_mfma_f32_16x16x32_bf16 v[34:37], v[232:235], v[196:199], v[34:37]
	v_mfma_f32_16x16x32_bf16 v[26:29], v[240:243], v[196:199], v[26:29]
	v_mfma_f32_16x16x32_bf16 v[18:21], v[232:235], v[216:219], v[18:21]
	v_mfma_f32_16x16x32_bf16 v[10:13], v[240:243], v[216:219], v[10:13]
	v_mfma_f32_16x16x32_bf16 v[6:9], v[232:235], v[224:227], v[6:9]
	v_mfma_f32_16x16x32_bf16 v[2:5], v[240:243], v[224:227], v[2:5]
	s_add_i32 s2, 0, 0x18000
	v_add_u32_e32 v156, s2, v145
	s_barrier
	ds_read_b128 v[140:143], v156
	ds_read_b128 v[148:151], v156 offset:1024
	ds_read_b128 v[152:155], v156 offset:2048
	ds_read_b128 v[156:159], v156 offset:3072
	s_add_u32 s26, s80, 0x20000
	s_addc_u32 s27, s81, 0
	s_mov_b32 m0, s70
	v_lshl_add_u64 v[228:229], s[26:27], 0, v[134:135]
	ds_read_b128 v[160:163], v147 offset:32768
	ds_read_b128 v[188:191], v147 offset:33792
	ds_read_b128 v[192:195], v147 offset:34816
	ds_read_b128 v[196:199], v147 offset:35840
	ds_read_b128 v[200:203], v147 offset:36864
	ds_read_b128 v[216:219], v147 offset:37888
	ds_read_b128 v[220:223], v147 offset:38912
	ds_read_b128 v[224:227], v147 offset:39936
	global_load_lds_dwordx4 v[228:229], off
	v_lshl_add_u64 v[228:229], s[26:27], 0, v[132:133]
	s_mov_b32 m0, s71
	s_nop 0
	global_load_lds_dwordx4 v[228:229], off
	s_waitcnt lgkmcnt(8)
	s_barrier
	s_waitcnt lgkmcnt(12)
	s_waitcnt lgkmcnt(12)
	s_waitcnt lgkmcnt(7)
	v_mfma_f32_16x16x32_bf16 v[126:129], v[140:143], v[160:163], v[126:129]
	v_mfma_f32_16x16x32_bf16 v[122:125], v[152:155], v[160:163], v[122:125]
	s_waitcnt lgkmcnt(5)
	v_mfma_f32_16x16x32_bf16 v[110:113], v[140:143], v[192:195], v[110:113]
	v_mfma_f32_16x16x32_bf16 v[106:109], v[152:155], v[192:195], v[106:109]
	s_waitcnt lgkmcnt(3)
	v_mfma_f32_16x16x32_bf16 v[94:97], v[140:143], v[200:203], v[94:97]
	v_mfma_f32_16x16x32_bf16 v[90:93], v[152:155], v[200:203], v[90:93]
	s_waitcnt lgkmcnt(1)
	v_mfma_f32_16x16x32_bf16 v[78:81], v[140:143], v[220:223], v[78:81]
	v_mfma_f32_16x16x32_bf16 v[74:77], v[152:155], v[220:223], v[74:77]
	v_mfma_f32_16x16x32_bf16 v[126:129], v[148:151], v[188:191], v[126:129]
	v_mfma_f32_16x16x32_bf16 v[122:125], v[156:159], v[188:191], v[122:125]
	v_mfma_f32_16x16x32_bf16 v[110:113], v[148:151], v[196:199], v[110:113]
	v_mfma_f32_16x16x32_bf16 v[106:109], v[156:159], v[196:199], v[106:109]
	v_mfma_f32_16x16x32_bf16 v[94:97], v[148:151], v[216:219], v[94:97]
	v_mfma_f32_16x16x32_bf16 v[90:93], v[156:159], v[216:219], v[90:93]
	s_waitcnt lgkmcnt(0)
	v_mfma_f32_16x16x32_bf16 v[78:81], v[148:151], v[224:227], v[78:81]
	v_mfma_f32_16x16x32_bf16 v[74:77], v[156:159], v[224:227], v[74:77]
	s_barrier
	s_add_i32 s17, 0, 0x1c000
	s_add_i32 s2, s2, s3
	v_add_u32_e32 v206, s17, v145
	v_lshl_add_u64 v[164:165], v[164:165], 0, s[28:29]
	s_mov_b32 m0, s2
	ds_read_b128 v[228:231], v206
	ds_read_b128 v[232:235], v206 offset:1024
	ds_read_b128 v[236:239], v206 offset:2048
	ds_read_b128 v[240:243], v206 offset:3072
	global_load_lds_dwordx4 v[164:165], off
	v_lshl_add_u64 v[164:165], v[204:205], 0, s[28:29]
	s_add_i32 m0, s2, 0x2000
	s_nop 0
	global_load_lds_dwordx4 v[164:165], off
	s_barrier
	s_waitcnt lgkmcnt(4)
	s_waitcnt lgkmcnt(4)
	s_waitcnt lgkmcnt(3)
	v_mfma_f32_16x16x32_bf16 v[118:121], v[228:231], v[160:163], v[118:121]
	s_waitcnt lgkmcnt(1)
	v_mfma_f32_16x16x32_bf16 v[114:117], v[236:239], v[160:163], v[114:117]
	v_mfma_f32_16x16x32_bf16 v[102:105], v[228:231], v[192:195], v[102:105]
	v_mfma_f32_16x16x32_bf16 v[98:101], v[236:239], v[192:195], v[98:101]
	v_mfma_f32_16x16x32_bf16 v[86:89], v[228:231], v[200:203], v[86:89]
	v_mfma_f32_16x16x32_bf16 v[82:85], v[236:239], v[200:203], v[82:85]
	v_mfma_f32_16x16x32_bf16 v[70:73], v[228:231], v[220:223], v[70:73]
	v_mfma_f32_16x16x32_bf16 v[66:69], v[236:239], v[220:223], v[66:69]
	v_mfma_f32_16x16x32_bf16 v[118:121], v[232:235], v[188:191], v[118:121]
	s_waitcnt lgkmcnt(0)
	v_mfma_f32_16x16x32_bf16 v[114:117], v[240:243], v[188:191], v[114:117]
	v_mfma_f32_16x16x32_bf16 v[102:105], v[232:235], v[196:199], v[102:105]
	v_mfma_f32_16x16x32_bf16 v[98:101], v[240:243], v[196:199], v[98:101]
	v_mfma_f32_16x16x32_bf16 v[86:89], v[232:235], v[216:219], v[86:89]
	v_mfma_f32_16x16x32_bf16 v[82:85], v[240:243], v[216:219], v[82:85]
	v_mfma_f32_16x16x32_bf16 v[70:73], v[232:235], v[224:227], v[70:73]
	v_mfma_f32_16x16x32_bf16 v[66:69], v[240:243], v[224:227], v[66:69]
	s_mov_b32 m0, s72
	v_lshl_add_u64 v[164:165], v[244:245], 0, s[28:29]
	s_barrier
	ds_read_b128 v[160:163], v147 offset:49152
	ds_read_b128 v[188:191], v147 offset:50176
	ds_read_b128 v[192:195], v147 offset:51200
	ds_read_b128 v[196:199], v147 offset:52224
	ds_read_b128 v[200:203], v147 offset:53248
	ds_read_b128 v[216:219], v147 offset:54272
	ds_read_b128 v[220:223], v147 offset:55296
	ds_read_b128 v[224:227], v147 offset:56320
	global_load_lds_dwordx4 v[164:165], off
	v_lshl_add_u64 v[164:165], v[246:247], 0, s[28:29]
	s_mov_b32 m0, s73
	s_nop 0
	global_load_lds_dwordx4 v[164:165], off
	s_barrier
	s_waitcnt lgkmcnt(8)
	s_waitcnt lgkmcnt(8)
	s_waitcnt lgkmcnt(7)
	v_mfma_f32_16x16x32_bf16 v[62:65], v[140:143], v[160:163], v[62:65]
	v_mfma_f32_16x16x32_bf16 v[58:61], v[152:155], v[160:163], v[58:61]
	s_waitcnt lgkmcnt(5)
	v_mfma_f32_16x16x32_bf16 v[54:57], v[140:143], v[192:195], v[54:57]
	v_mfma_f32_16x16x32_bf16 v[46:49], v[152:155], v[192:195], v[46:49]
	s_waitcnt lgkmcnt(3)
	v_mfma_f32_16x16x32_bf16 v[38:41], v[140:143], v[200:203], v[38:41]
	v_mfma_f32_16x16x32_bf16 v[30:33], v[152:155], v[200:203], v[30:33]
	s_waitcnt lgkmcnt(1)
	v_mfma_f32_16x16x32_bf16 v[22:25], v[140:143], v[220:223], v[22:25]
	v_mfma_f32_16x16x32_bf16 v[14:17], v[152:155], v[220:223], v[14:17]
	v_mfma_f32_16x16x32_bf16 v[62:65], v[148:151], v[188:191], v[62:65]
	v_mfma_f32_16x16x32_bf16 v[58:61], v[156:159], v[188:191], v[58:61]
	v_mfma_f32_16x16x32_bf16 v[54:57], v[148:151], v[196:199], v[54:57]
	v_mfma_f32_16x16x32_bf16 v[46:49], v[156:159], v[196:199], v[46:49]
	v_mfma_f32_16x16x32_bf16 v[38:41], v[148:151], v[216:219], v[38:41]
	v_mfma_f32_16x16x32_bf16 v[30:33], v[156:159], v[216:219], v[30:33]
	s_waitcnt lgkmcnt(0)
	v_mfma_f32_16x16x32_bf16 v[22:25], v[148:151], v[224:227], v[22:25]
	v_mfma_f32_16x16x32_bf16 v[14:17], v[156:159], v[224:227], v[14:17]
	s_barrier
	s_add_u32 s26, s78, 0xd0080
	s_addc_u32 s27, s79, 0
	s_add_i32 s2, s17, s3
	v_lshl_add_u64 v[140:141], s[26:27], 0, v[0:1]
	s_mov_b32 m0, s2
	s_nop 0
	global_load_lds_dwordx4 v[140:141], off
	v_lshl_add_u64 v[140:141], s[26:27], 0, v[130:131]
	s_add_i32 m0, s2, 0x2000
	s_nop 0
	global_load_lds_dwordx4 v[140:141], off
	s_waitcnt vmcnt(6)
	s_barrier
	v_mfma_f32_16x16x32_bf16 v[50:53], v[228:231], v[160:163], v[50:53]
	v_mfma_f32_16x16x32_bf16 v[42:45], v[236:239], v[160:163], v[42:45]
	v_mfma_f32_16x16x32_bf16 v[34:37], v[228:231], v[192:195], v[34:37]
	v_mfma_f32_16x16x32_bf16 v[26:29], v[236:239], v[192:195], v[26:29]
	v_mfma_f32_16x16x32_bf16 v[18:21], v[228:231], v[200:203], v[18:21]
	v_mfma_f32_16x16x32_bf16 v[10:13], v[236:239], v[200:203], v[10:13]
	v_mfma_f32_16x16x32_bf16 v[6:9], v[228:231], v[220:223], v[6:9]
	v_mfma_f32_16x16x32_bf16 v[2:5], v[236:239], v[220:223], v[2:5]
	v_mfma_f32_16x16x32_bf16 v[50:53], v[232:235], v[188:191], v[50:53]
	v_mfma_f32_16x16x32_bf16 v[42:45], v[240:243], v[188:191], v[42:45]
	v_mfma_f32_16x16x32_bf16 v[34:37], v[232:235], v[196:199], v[34:37]
	v_mfma_f32_16x16x32_bf16 v[26:29], v[240:243], v[196:199], v[26:29]
	v_mfma_f32_16x16x32_bf16 v[18:21], v[232:235], v[216:219], v[18:21]
	v_mfma_f32_16x16x32_bf16 v[10:13], v[240:243], v[216:219], v[10:13]
	v_mfma_f32_16x16x32_bf16 v[6:9], v[232:235], v[224:227], v[6:9]
	v_mfma_f32_16x16x32_bf16 v[2:5], v[240:243], v[224:227], v[2:5]
	s_add_i32 s44, s44, 2
	s_add_u32 s6, s6, 0x100
	s_addc_u32 s7, s7, 0
	s_add_u32 s25, s25, 0x100
	s_addc_u32 s46, s46, 0
	s_cmp_gt_u32 s44, 5
	s_barrier
	s_cbranch_scc0 .LBB0_500
	v_lshl_or_b32 v156, s62, 8, v146
	v_ashrrev_i32_e32 v157, 31, v156
	v_lshl_add_u64 v[140:141], v[156:157], 2, s[38:39]
	global_load_dwordx4 v[200:203], v[140:141], off offset:16
	global_load_dwordx4 v[220:223], v[140:141], off
	global_load_dwordx4 v[228:231], v[140:141], off offset:528
	global_load_dwordx4 v[236:239], v[140:141], off offset:512
	v_lshl_add_u32 v142, s63, 8, v144
	v_ashrrev_i32_e32 v143, 31, v142
	s_mov_b32 s2, 0x400000
	s_mov_b64 s[6:7], 0x400000
	s_mov_b32 s62, s41
	s_mov_b32 s63, s10
	s_mov_b64 s[78:79], s[74:75]
	s_mov_b64 s[80:81], s[76:77]
	s_waitcnt vmcnt(0)
	v_mov_b32_e32 v148, v200
	v_mov_b32_e32 v149, v201
	v_mov_b32_e32 v150, v202
	v_mov_b32_e32 v151, v203
	v_mov_b32_e32 v152, v220
	v_mov_b32_e32 v153, v221
	v_mov_b32_e32 v154, v222
	v_mov_b32_e32 v155, v223
	v_pk_mul_f32 v[122:123], v[122:123], v[148:149]
	v_pk_mul_f32 v[126:127], v[126:127], v[152:153]
	v_pk_mul_f32 v[124:125], v[124:125], v[150:151]
	v_cvt_pk_bf16_f32 v150, v122, v123
	v_lshlrev_b64 v[122:123], 15, v[142:143]
	v_pk_mul_f32 v[128:129], v[128:129], v[154:155]
	v_cvt_pk_bf16_f32 v148, v126, v127
	v_cvt_pk_bf16_f32 v151, v124, v125
	v_lshl_add_u64 v[122:123], s[60:61], 0, v[122:123]
	v_lshlrev_b64 v[126:127], 1, v[156:157]
	v_or_b32_e32 v124, 0x80, v156
	v_cvt_pk_bf16_f32 v149, v128, v129
	v_lshl_add_u64 v[122:123], v[122:123], 0, v[126:127]
	v_ashrrev_i32_e32 v125, 31, v124
	global_store_dwordx4 v[122:123], v[148:151], off
	v_lshl_add_u64 v[124:125], v[124:125], 2, s[38:39]
	s_nop 1
	v_mov_b32_e32 v148, v228
	v_mov_b32_e32 v149, v229
	v_mov_b32_e32 v150, v230
	v_mov_b32_e32 v151, v231
	s_nop 1
	v_mov_b32_e32 v152, v236
	v_mov_b32_e32 v153, v237
	v_mov_b32_e32 v154, v238
	v_mov_b32_e32 v155, v239
	s_nop 0
	v_pk_mul_f32 v[128:129], v[116:117], v[150:151]
	v_pk_mul_f32 v[120:121], v[120:121], v[154:155]
	v_pk_mul_f32 v[118:119], v[118:119], v[152:153]
	v_pk_mul_f32 v[116:117], v[114:115], v[148:149]
	v_cvt_pk_bf16_f32 v114, v118, v119
	v_cvt_pk_bf16_f32 v115, v120, v121
	v_cvt_pk_bf16_f32 v116, v116, v117
	v_cvt_pk_bf16_f32 v117, v128, v129
	global_store_dwordx4 v[122:123], v[114:117], off offset:256
	s_nop 1
	v_mov_b32_e32 v114, v200
	v_mov_b32_e32 v115, v201
	v_mov_b32_e32 v116, v202
	v_mov_b32_e32 v117, v203
	s_nop 0
	s_nop 1
	v_mov_b32_e32 v118, v220
	v_mov_b32_e32 v119, v221
	v_mov_b32_e32 v120, v222
	v_mov_b32_e32 v121, v223
	v_or_b32_e32 v128, 16, v142
	v_ashrrev_i32_e32 v129, 31, v128
	s_nop 0
	v_pk_mul_f32 v[116:117], v[108:109], v[116:117]
	v_pk_mul_f32 v[110:111], v[110:111], v[118:119]
	v_pk_mul_f32 v[108:109], v[106:107], v[114:115]
	v_cvt_pk_bf16_f32 v106, v110, v111
	v_lshlrev_b64 v[110:111], 15, v[128:129]
	v_pk_mul_f32 v[112:113], v[112:113], v[120:121]
	v_lshl_add_u64 v[110:111], s[60:61], 0, v[110:111]
	v_cvt_pk_bf16_f32 v107, v112, v113
	v_cvt_pk_bf16_f32 v108, v108, v109
	v_cvt_pk_bf16_f32 v109, v116, v117
	v_lshl_add_u64 v[114:115], v[110:111], 0, v[126:127]
	global_store_dwordx4 v[114:115], v[106:109], off
	s_nop 1
	v_mov_b32_e32 v106, v228
	v_mov_b32_e32 v107, v229
	v_mov_b32_e32 v108, v230
	v_mov_b32_e32 v109, v231
	s_nop 0
	s_nop 1
	v_mov_b32_e32 v110, v236
	v_mov_b32_e32 v111, v237
	v_mov_b32_e32 v112, v238
	v_mov_b32_e32 v113, v239
	s_nop 0
	v_pk_mul_f32 v[108:109], v[100:101], v[108:109]
	v_pk_mul_f32 v[104:105], v[104:105], v[112:113]
	v_pk_mul_f32 v[102:103], v[102:103], v[110:111]
	v_pk_mul_f32 v[100:101], v[98:99], v[106:107]
	v_cvt_pk_bf16_f32 v98, v102, v103
	v_cvt_pk_bf16_f32 v99, v104, v105
	v_cvt_pk_bf16_f32 v100, v100, v101
	v_cvt_pk_bf16_f32 v101, v108, v109
	global_store_dwordx4 v[114:115], v[98:101], off offset:256
	s_nop 1
	v_mov_b32_e32 v98, v200
	v_mov_b32_e32 v99, v201
	v_mov_b32_e32 v100, v202
	v_mov_b32_e32 v101, v203
	s_nop 0
	s_nop 1
	v_mov_b32_e32 v102, v220
	v_mov_b32_e32 v103, v221
	v_mov_b32_e32 v104, v222
	v_mov_b32_e32 v105, v223
	v_or_b32_e32 v106, 32, v142
	v_ashrrev_i32_e32 v107, 31, v106
	s_nop 0
	v_pk_mul_f32 v[100:101], v[92:93], v[100:101]
	v_pk_mul_f32 v[94:95], v[94:95], v[102:103]
	v_pk_mul_f32 v[92:93], v[90:91], v[98:99]
	v_cvt_pk_bf16_f32 v90, v94, v95
	v_lshlrev_b64 v[94:95], 15, v[106:107]
	v_pk_mul_f32 v[96:97], v[96:97], v[104:105]
	v_lshl_add_u64 v[94:95], s[60:61], 0, v[94:95]
	v_cvt_pk_bf16_f32 v91, v96, v97
	v_cvt_pk_bf16_f32 v92, v92, v93
	v_cvt_pk_bf16_f32 v93, v100, v101
	v_lshl_add_u64 v[98:99], v[94:95], 0, v[126:127]
	global_store_dwordx4 v[98:99], v[90:93], off
	s_nop 1
	v_mov_b32_e32 v90, v228
	v_mov_b32_e32 v91, v229
	v_mov_b32_e32 v92, v230
	v_mov_b32_e32 v93, v231
	s_nop 0
	s_nop 1
	v_mov_b32_e32 v94, v236
	v_mov_b32_e32 v95, v237
	v_mov_b32_e32 v96, v238
	v_mov_b32_e32 v97, v239
	s_nop 0
	v_pk_mul_f32 v[92:93], v[84:85], v[92:93]
	v_pk_mul_f32 v[88:89], v[88:89], v[96:97]
	v_pk_mul_f32 v[86:87], v[86:87], v[94:95]
	v_pk_mul_f32 v[84:85], v[82:83], v[90:91]
	v_cvt_pk_bf16_f32 v82, v86, v87
	v_cvt_pk_bf16_f32 v83, v88, v89
	v_cvt_pk_bf16_f32 v84, v84, v85
	v_cvt_pk_bf16_f32 v85, v92, v93
	global_store_dwordx4 v[98:99], v[82:85], off offset:256
	s_nop 1
	v_mov_b32_e32 v82, v200
	v_mov_b32_e32 v83, v201
	v_mov_b32_e32 v84, v202
	v_mov_b32_e32 v85, v203
	s_nop 0
	s_nop 1
	v_mov_b32_e32 v86, v220
	v_mov_b32_e32 v87, v221
	v_mov_b32_e32 v88, v222
	v_mov_b32_e32 v89, v223
	v_or_b32_e32 v90, 48, v142
	v_ashrrev_i32_e32 v91, 31, v90
	s_nop 0
	v_pk_mul_f32 v[84:85], v[76:77], v[84:85]
	v_pk_mul_f32 v[78:79], v[78:79], v[86:87]
	v_pk_mul_f32 v[76:77], v[74:75], v[82:83]
	v_cvt_pk_bf16_f32 v74, v78, v79
	v_lshlrev_b64 v[78:79], 15, v[90:91]
	v_pk_mul_f32 v[80:81], v[80:81], v[88:89]
	v_lshl_add_u64 v[78:79], s[60:61], 0, v[78:79]
	v_cvt_pk_bf16_f32 v75, v80, v81
	v_cvt_pk_bf16_f32 v76, v76, v77
	v_cvt_pk_bf16_f32 v77, v84, v85
	v_lshl_add_u64 v[82:83], v[78:79], 0, v[126:127]
	global_store_dwordx4 v[82:83], v[74:77], off
	s_nop 1
	v_mov_b32_e32 v74, v228
	v_mov_b32_e32 v75, v229
	v_mov_b32_e32 v76, v230
	v_mov_b32_e32 v77, v231
	s_nop 0
	s_nop 1
	v_mov_b32_e32 v78, v236
	v_mov_b32_e32 v79, v237
	v_mov_b32_e32 v80, v238
	v_mov_b32_e32 v81, v239
	s_nop 0
	v_pk_mul_f32 v[76:77], v[68:69], v[76:77]
	v_pk_mul_f32 v[72:73], v[72:73], v[80:81]
	v_pk_mul_f32 v[70:71], v[70:71], v[78:79]
	v_pk_mul_f32 v[68:69], v[66:67], v[74:75]
	v_cvt_pk_bf16_f32 v66, v70, v71
	v_cvt_pk_bf16_f32 v67, v72, v73
	v_cvt_pk_bf16_f32 v68, v68, v69
	v_cvt_pk_bf16_f32 v69, v76, v77
	global_store_dwordx4 v[82:83], v[66:69], off offset:256
	s_nop 1
	v_mov_b32_e32 v66, v200
	v_mov_b32_e32 v67, v201
	v_mov_b32_e32 v68, v202
	v_mov_b32_e32 v69, v203
	s_nop 0
	s_nop 1
	v_mov_b32_e32 v70, v220
	v_mov_b32_e32 v71, v221
	v_mov_b32_e32 v72, v222
	v_mov_b32_e32 v73, v223
	s_nop 0
	v_pk_mul_f32 v[68:69], v[60:61], v[68:69]
	v_pk_mul_f32 v[62:63], v[62:63], v[70:71]
	v_pk_mul_f32 v[64:65], v[64:65], v[72:73]
	v_pk_mul_f32 v[60:61], v[58:59], v[66:67]
	v_cvt_pk_bf16_f32 v58, v62, v63
	v_add_co_u32_e32 v62, vcc, s2, v122
	v_cvt_pk_bf16_f32 v59, v64, v65
	v_cvt_pk_bf16_f32 v60, v60, v61
	v_cvt_pk_bf16_f32 v61, v68, v69
	v_addc_co_u32_e32 v63, vcc, 0, v123, vcc
	global_store_dwordx4 v[62:63], v[58:61], off
	s_nop 1
	v_mov_b32_e32 v58, v228
	v_mov_b32_e32 v59, v229
	v_mov_b32_e32 v60, v230
	v_mov_b32_e32 v61, v231
	s_nop 0
	s_nop 1
	v_mov_b32_e32 v62, v236
	v_mov_b32_e32 v63, v237
	v_mov_b32_e32 v64, v238
	v_mov_b32_e32 v65, v239
	v_lshl_add_u64 v[66:67], v[122:123], 0, s[6:7]
	s_mov_b32 s2, 0x480000
	s_mov_b64 s[6:7], 0x480000
	s_nop 0
	v_pk_mul_f32 v[60:61], v[44:45], v[60:61]
	v_pk_mul_f32 v[52:53], v[52:53], v[64:65]
	v_pk_mul_f32 v[50:51], v[50:51], v[62:63]
	v_pk_mul_f32 v[44:45], v[42:43], v[58:59]
	v_cvt_pk_bf16_f32 v42, v50, v51
	v_cvt_pk_bf16_f32 v43, v52, v53
	v_cvt_pk_bf16_f32 v44, v44, v45
	v_cvt_pk_bf16_f32 v45, v60, v61
	global_store_dwordx4 v[66:67], v[42:45], off offset:256
	s_nop 1
	v_mov_b32_e32 v42, v200
	v_mov_b32_e32 v43, v201
	v_mov_b32_e32 v44, v202
	v_mov_b32_e32 v45, v203
	s_nop 0
	s_nop 1
	v_mov_b32_e32 v50, v220
	v_mov_b32_e32 v51, v221
	v_mov_b32_e32 v52, v222
	v_mov_b32_e32 v53, v223
	s_nop 0
	v_pk_mul_f32 v[48:49], v[48:49], v[44:45]
	v_pk_mul_f32 v[52:53], v[56:57], v[52:53]
	v_pk_mul_f32 v[50:51], v[54:55], v[50:51]
	v_pk_mul_f32 v[44:45], v[46:47], v[42:43]
	v_add_co_u32_e32 v46, vcc, s2, v122
	v_cvt_pk_bf16_f32 v42, v50, v51
	v_cvt_pk_bf16_f32 v43, v52, v53
	v_cvt_pk_bf16_f32 v44, v44, v45
	v_cvt_pk_bf16_f32 v45, v48, v49
	v_addc_co_u32_e32 v47, vcc, 0, v123, vcc
	global_store_dwordx4 v[46:47], v[42:45], off
	s_nop 1
	v_mov_b32_e32 v42, v228
	v_mov_b32_e32 v43, v229
	v_mov_b32_e32 v44, v230
	v_mov_b32_e32 v45, v231
	s_nop 0
	s_nop 1
	v_mov_b32_e32 v46, v236
	v_mov_b32_e32 v47, v237
	v_mov_b32_e32 v48, v238
	v_mov_b32_e32 v49, v239
	v_lshl_add_u64 v[50:51], v[122:123], 0, s[6:7]
	s_mov_b32 s2, 0x500000
	s_mov_b64 s[6:7], 0x500000
	s_nop 0
	v_pk_mul_f32 v[44:45], v[28:29], v[44:45]
	v_pk_mul_f32 v[36:37], v[36:37], v[48:49]
	v_pk_mul_f32 v[34:35], v[34:35], v[46:47]
	v_pk_mul_f32 v[28:29], v[26:27], v[42:43]
	v_cvt_pk_bf16_f32 v26, v34, v35
	v_cvt_pk_bf16_f32 v27, v36, v37
	v_cvt_pk_bf16_f32 v28, v28, v29
	v_cvt_pk_bf16_f32 v29, v44, v45
	global_store_dwordx4 v[50:51], v[26:29], off offset:256
	s_nop 1
	v_mov_b32_e32 v26, v200
	v_mov_b32_e32 v27, v201
	v_mov_b32_e32 v28, v202
	v_mov_b32_e32 v29, v203
	s_nop 0
	s_nop 1
	v_mov_b32_e32 v34, v220
	v_mov_b32_e32 v35, v221
	v_mov_b32_e32 v36, v222
	v_mov_b32_e32 v37, v223
	s_nop 0
	v_pk_mul_f32 v[32:33], v[32:33], v[28:29]
	v_pk_mul_f32 v[36:37], v[40:41], v[36:37]
	v_pk_mul_f32 v[34:35], v[38:39], v[34:35]
	v_pk_mul_f32 v[28:29], v[30:31], v[26:27]
	v_add_co_u32_e32 v30, vcc, s2, v122
	v_cvt_pk_bf16_f32 v26, v34, v35
	v_cvt_pk_bf16_f32 v27, v36, v37
	v_cvt_pk_bf16_f32 v28, v28, v29
	v_cvt_pk_bf16_f32 v29, v32, v33
	v_addc_co_u32_e32 v31, vcc, 0, v123, vcc
	global_store_dwordx4 v[30:31], v[26:29], off
	s_nop 1
	v_mov_b32_e32 v26, v228
	v_mov_b32_e32 v27, v229
	v_mov_b32_e32 v28, v230
	v_mov_b32_e32 v29, v231
	s_nop 0
	s_nop 1
	v_mov_b32_e32 v30, v236
	v_mov_b32_e32 v31, v237
	v_mov_b32_e32 v32, v238
	v_mov_b32_e32 v33, v239
	v_lshl_add_u64 v[34:35], v[122:123], 0, s[6:7]
	s_mov_b32 s2, 0x580000
	s_mov_b64 s[6:7], 0x580000
	s_nop 0
	v_pk_mul_f32 v[28:29], v[12:13], v[28:29]
	v_pk_mul_f32 v[20:21], v[20:21], v[32:33]
	v_pk_mul_f32 v[18:19], v[18:19], v[30:31]
	v_pk_mul_f32 v[12:13], v[10:11], v[26:27]
	v_cvt_pk_bf16_f32 v10, v18, v19
	v_cvt_pk_bf16_f32 v11, v20, v21
	v_cvt_pk_bf16_f32 v12, v12, v13
	v_cvt_pk_bf16_f32 v13, v28, v29
	global_store_dwordx4 v[34:35], v[10:13], off offset:256
	s_nop 1
	v_mov_b32_e32 v10, v200
	v_mov_b32_e32 v11, v201
	v_mov_b32_e32 v12, v202
	v_mov_b32_e32 v13, v203
	s_nop 0
	s_nop 1
	v_mov_b32_e32 v18, v220
	v_mov_b32_e32 v19, v221
	v_mov_b32_e32 v20, v222
	v_mov_b32_e32 v21, v223
	s_nop 0
	v_pk_mul_f32 v[16:17], v[16:17], v[12:13]
	v_pk_mul_f32 v[20:21], v[24:25], v[20:21]
	v_pk_mul_f32 v[18:19], v[22:23], v[18:19]
	v_pk_mul_f32 v[12:13], v[14:15], v[10:11]
	v_add_co_u32_e32 v14, vcc, s2, v122
	v_cvt_pk_bf16_f32 v10, v18, v19
	v_cvt_pk_bf16_f32 v11, v20, v21
	v_cvt_pk_bf16_f32 v12, v12, v13
	v_cvt_pk_bf16_f32 v13, v16, v17
	v_addc_co_u32_e32 v15, vcc, 0, v123, vcc
	global_store_dwordx4 v[14:15], v[10:13], off
	s_nop 1
	v_mov_b32_e32 v10, v228
	v_mov_b32_e32 v11, v229
	v_mov_b32_e32 v12, v230
	v_mov_b32_e32 v13, v231
	s_nop 0
	s_nop 1
	v_mov_b32_e32 v14, v236
	v_mov_b32_e32 v15, v237
	v_mov_b32_e32 v16, v238
	v_mov_b32_e32 v17, v239
	v_lshl_add_u64 v[18:19], v[122:123], 0, s[6:7]
	s_and_b64 vcc, exec, s[0:1]
	s_nop 0
	v_pk_mul_f32 v[12:13], v[4:5], v[12:13]
	v_pk_mul_f32 v[8:9], v[8:9], v[16:17]
	v_pk_mul_f32 v[6:7], v[6:7], v[14:15]
	v_pk_mul_f32 v[4:5], v[2:3], v[10:11]
	v_cvt_pk_bf16_f32 v2, v6, v7
	v_cvt_pk_bf16_f32 v3, v8, v9
	v_cvt_pk_bf16_f32 v4, v4, v5
	v_cvt_pk_bf16_f32 v5, v12, v13
	global_store_dwordx4 v[18:19], v[2:5], off offset:256
	s_cbranch_vccz .LBB0_491
	v_readlane_b32 s0, v254, 12
	s_waitcnt vmcnt(0)
	v_readlane_b32 s1, v254, 13
	v_readlane_b32 s84, v251, 38
	v_readlane_b32 s18, v253, 0
	s_andn2_b64 vcc, exec, s[0:1]
	v_readlane_b32 s85, v251, 39
	v_readlane_b32 s86, v251, 40
	v_readlane_b32 s87, v251, 41
	v_readlane_b32 s14, v250, 63
	v_readlane_b32 s19, v253, 1
	s_cbranch_vccnz .LBB0_504
	s_barrier

.LBB0_655:
	s_add_u32 s2, s68, 0xfff80080
	s_addc_u32 s17, s69, -1
	s_add_i32 s26, 0, 0x10000
	v_add_u32_e32 v156, s26, v141
	ds_read_b128 v[144:147], v156
	ds_read_b128 v[148:151], v156 offset:1024
	ds_read_b128 v[152:155], v156 offset:2048
	ds_read_b128 v[156:159], v156 offset:3072
	s_cmp_eq_u32 s44, 28
	s_cselect_b32 s73, s55, s17
	s_cselect_b32 s72, s83, s2
	s_cselect_b32 s71, s24, s92
	s_cselect_b32 s70, s25, s43
	v_lshl_add_u64 v[164:165], s[68:69], 0, v[136:137]
	s_add_i32 m0, s58, 0xc000
	ds_read_b128 v[160:163], v143
	ds_read_b128 v[188:191], v143 offset:1024
	ds_read_b128 v[192:195], v143 offset:2048
	ds_read_b128 v[196:199], v143 offset:3072
	ds_read_b128 v[200:203], v143 offset:4096
	ds_read_b128 v[216:219], v143 offset:5120
	ds_read_b128 v[220:223], v143 offset:6144
	ds_read_b128 v[224:227], v143 offset:7168
	global_load_lds_dwordx4 v[164:165], off
	v_lshl_add_u64 v[164:165], s[68:69], 0, v[138:139]
	s_add_i32 m0, s58, 0xe000
	s_nop 0
	global_load_lds_dwordx4 v[164:165], off
	s_waitcnt lgkmcnt(8)
	s_barrier
	s_waitcnt lgkmcnt(12)
	s_waitcnt lgkmcnt(12)
	s_waitcnt lgkmcnt(7)
	v_mfma_f32_16x16x32_bf16 v[126:129], v[144:147], v[160:163], v[126:129]
	v_mfma_f32_16x16x32_bf16 v[122:125], v[152:155], v[160:163], v[122:125]
	s_waitcnt lgkmcnt(5)
	v_mfma_f32_16x16x32_bf16 v[118:121], v[144:147], v[192:195], v[118:121]
	v_mfma_f32_16x16x32_bf16 v[114:117], v[152:155], v[192:195], v[114:117]
	s_waitcnt lgkmcnt(3)
	v_mfma_f32_16x16x32_bf16 v[102:105], v[144:147], v[200:203], v[102:105]
	v_mfma_f32_16x16x32_bf16 v[98:101], v[152:155], v[200:203], v[98:101]
	s_waitcnt lgkmcnt(1)
	v_mfma_f32_16x16x32_bf16 v[86:89], v[144:147], v[220:223], v[86:89]
	v_mfma_f32_16x16x32_bf16 v[82:85], v[152:155], v[220:223], v[82:85]
	v_mfma_f32_16x16x32_bf16 v[126:129], v[148:151], v[188:191], v[126:129]
	v_mfma_f32_16x16x32_bf16 v[122:125], v[156:159], v[188:191], v[122:125]
	v_mfma_f32_16x16x32_bf16 v[118:121], v[148:151], v[196:199], v[118:121]
	v_mfma_f32_16x16x32_bf16 v[114:117], v[156:159], v[196:199], v[114:117]
	v_mfma_f32_16x16x32_bf16 v[102:105], v[148:151], v[216:219], v[102:105]
	v_mfma_f32_16x16x32_bf16 v[98:101], v[156:159], v[216:219], v[98:101]
	s_waitcnt lgkmcnt(0)
	v_mfma_f32_16x16x32_bf16 v[86:89], v[148:151], v[224:227], v[86:89]
	v_mfma_f32_16x16x32_bf16 v[82:85], v[156:159], v[224:227], v[82:85]
	s_barrier
	s_add_i32 s2, 0, 0x14000
	v_add_u32_e32 v164, s2, v141
	s_add_i32 s17, s26, s3
	ds_read_b128 v[228:231], v164
	ds_read_b128 v[232:235], v164 offset:1024
	ds_read_b128 v[236:239], v164 offset:2048
	ds_read_b128 v[240:243], v164 offset:3072
	v_lshl_add_u64 v[164:165], s[70:71], 0, v[0:1]
	s_mov_b32 m0, s17
	v_lshl_add_u64 v[204:205], s[70:71], 0, v[130:131]
	global_load_lds_dwordx4 v[164:165], off
	s_add_i32 m0, s17, 0x2000
	s_nop 0
	global_load_lds_dwordx4 v[204:205], off
	s_barrier
	s_waitcnt lgkmcnt(4)
	s_waitcnt lgkmcnt(4)
	s_waitcnt lgkmcnt(3)
	v_mfma_f32_16x16x32_bf16 v[110:113], v[228:231], v[160:163], v[110:113]
	s_waitcnt lgkmcnt(1)
	v_mfma_f32_16x16x32_bf16 v[106:109], v[236:239], v[160:163], v[106:109]
	v_mfma_f32_16x16x32_bf16 v[94:97], v[228:231], v[192:195], v[94:97]
	v_mfma_f32_16x16x32_bf16 v[90:93], v[236:239], v[192:195], v[90:93]
	v_mfma_f32_16x16x32_bf16 v[78:81], v[228:231], v[200:203], v[78:81]
	v_mfma_f32_16x16x32_bf16 v[74:77], v[236:239], v[200:203], v[74:77]
	v_mfma_f32_16x16x32_bf16 v[70:73], v[228:231], v[220:223], v[70:73]
	v_mfma_f32_16x16x32_bf16 v[66:69], v[236:239], v[220:223], v[66:69]
	v_mfma_f32_16x16x32_bf16 v[110:113], v[232:235], v[188:191], v[110:113]
	s_waitcnt lgkmcnt(0)
	v_mfma_f32_16x16x32_bf16 v[106:109], v[240:243], v[188:191], v[106:109]
	v_mfma_f32_16x16x32_bf16 v[94:97], v[232:235], v[196:199], v[94:97]
	v_mfma_f32_16x16x32_bf16 v[90:93], v[240:243], v[196:199], v[90:93]
	v_mfma_f32_16x16x32_bf16 v[78:81], v[232:235], v[216:219], v[78:81]
	v_mfma_f32_16x16x32_bf16 v[74:77], v[240:243], v[216:219], v[74:77]
	v_mfma_f32_16x16x32_bf16 v[70:73], v[232:235], v[224:227], v[70:73]
	v_mfma_f32_16x16x32_bf16 v[66:69], v[240:243], v[224:227], v[66:69]
	s_mov_b32 m0, s58
	v_lshl_add_u64 v[244:245], s[72:73], 0, v[134:135]
	s_barrier
	ds_read_b128 v[160:163], v143 offset:16384
	ds_read_b128 v[188:191], v143 offset:17408
	ds_read_b128 v[192:195], v143 offset:18432
	ds_read_b128 v[196:199], v143 offset:19456
	ds_read_b128 v[200:203], v143 offset:20480
	ds_read_b128 v[216:219], v143 offset:21504
	ds_read_b128 v[220:223], v143 offset:22528
	ds_read_b128 v[224:227], v143 offset:23552
	global_load_lds_dwordx4 v[244:245], off
	v_lshl_add_u64 v[246:247], s[72:73], 0, v[132:133]
	s_mov_b32 m0, s74
	s_nop 0
	global_load_lds_dwordx4 v[246:247], off
	s_barrier
	s_waitcnt lgkmcnt(8)
	s_waitcnt lgkmcnt(8)
	s_waitcnt lgkmcnt(7)
	v_mfma_f32_16x16x32_bf16 v[62:65], v[144:147], v[160:163], v[62:65]
	v_mfma_f32_16x16x32_bf16 v[58:61], v[152:155], v[160:163], v[58:61]
	s_waitcnt lgkmcnt(5)
	v_mfma_f32_16x16x32_bf16 v[54:57], v[144:147], v[192:195], v[54:57]
	v_mfma_f32_16x16x32_bf16 v[50:53], v[152:155], v[192:195], v[50:53]
	s_waitcnt lgkmcnt(3)
	v_mfma_f32_16x16x32_bf16 v[38:41], v[144:147], v[200:203], v[38:41]
	v_mfma_f32_16x16x32_bf16 v[34:37], v[152:155], v[200:203], v[34:37]
	s_waitcnt lgkmcnt(1)
	v_mfma_f32_16x16x32_bf16 v[22:25], v[144:147], v[220:223], v[22:25]
	v_mfma_f32_16x16x32_bf16 v[18:21], v[152:155], v[220:223], v[18:21]
	v_mfma_f32_16x16x32_bf16 v[62:65], v[148:151], v[188:191], v[62:65]
	v_mfma_f32_16x16x32_bf16 v[58:61], v[156:159], v[188:191], v[58:61]
	v_mfma_f32_16x16x32_bf16 v[54:57], v[148:151], v[196:199], v[54:57]
	v_mfma_f32_16x16x32_bf16 v[50:53], v[156:159], v[196:199], v[50:53]
	v_mfma_f32_16x16x32_bf16 v[38:41], v[148:151], v[216:219], v[38:41]
	v_mfma_f32_16x16x32_bf16 v[34:37], v[156:159], v[216:219], v[34:37]
	s_waitcnt lgkmcnt(0)
	v_mfma_f32_16x16x32_bf16 v[22:25], v[148:151], v[224:227], v[22:25]
	v_mfma_f32_16x16x32_bf16 v[18:21], v[156:159], v[224:227], v[18:21]
	s_barrier
	s_add_u32 s26, s70, 0x80000
	s_addc_u32 s27, s71, 0
	s_add_i32 s2, s2, s3
	v_lshl_add_u64 v[144:145], s[26:27], 0, v[0:1]
	s_mov_b32 m0, s2
	s_nop 0
	global_load_lds_dwordx4 v[144:145], off
	v_lshl_add_u64 v[144:145], s[26:27], 0, v[130:131]
	s_add_i32 m0, s2, 0x2000
	s_nop 0
	global_load_lds_dwordx4 v[144:145], off
	s_waitcnt vmcnt(6)
	s_barrier
	v_mfma_f32_16x16x32_bf16 v[46:49], v[228:231], v[160:163], v[46:49]
	v_mfma_f32_16x16x32_bf16 v[42:45], v[236:239], v[160:163], v[42:45]
	v_mfma_f32_16x16x32_bf16 v[30:33], v[228:231], v[192:195], v[30:33]
	v_mfma_f32_16x16x32_bf16 v[26:29], v[236:239], v[192:195], v[26:29]
	v_mfma_f32_16x16x32_bf16 v[14:17], v[228:231], v[200:203], v[14:17]
	v_mfma_f32_16x16x32_bf16 v[10:13], v[236:239], v[200:203], v[10:13]
	v_mfma_f32_16x16x32_bf16 v[6:9], v[228:231], v[220:223], v[6:9]
	v_mfma_f32_16x16x32_bf16 v[2:5], v[236:239], v[220:223], v[2:5]
	v_mfma_f32_16x16x32_bf16 v[46:49], v[232:235], v[188:191], v[46:49]
	v_mfma_f32_16x16x32_bf16 v[42:45], v[240:243], v[188:191], v[42:45]
	v_mfma_f32_16x16x32_bf16 v[30:33], v[232:235], v[196:199], v[30:33]
	v_mfma_f32_16x16x32_bf16 v[26:29], v[240:243], v[196:199], v[26:29]
	v_mfma_f32_16x16x32_bf16 v[14:17], v[232:235], v[216:219], v[14:17]
	v_mfma_f32_16x16x32_bf16 v[10:13], v[240:243], v[216:219], v[10:13]
	v_mfma_f32_16x16x32_bf16 v[6:9], v[232:235], v[224:227], v[6:9]
	v_mfma_f32_16x16x32_bf16 v[2:5], v[240:243], v[224:227], v[2:5]
	s_add_i32 s2, 0, 0x18000
	v_add_u32_e32 v156, s2, v141
	s_barrier
	ds_read_b128 v[144:147], v156
	ds_read_b128 v[148:151], v156 offset:1024
	ds_read_b128 v[152:155], v156 offset:2048
	ds_read_b128 v[156:159], v156 offset:3072
	s_add_u32 s26, s72, 0x80000
	s_addc_u32 s27, s73, 0
	s_mov_b32 m0, s75
	v_lshl_add_u64 v[228:229], s[26:27], 0, v[134:135]
	ds_read_b128 v[160:163], v143 offset:32768
	ds_read_b128 v[188:191], v143 offset:33792
	ds_read_b128 v[192:195], v143 offset:34816
	ds_read_b128 v[196:199], v143 offset:35840
	ds_read_b128 v[200:203], v143 offset:36864
	ds_read_b128 v[216:219], v143 offset:37888
	ds_read_b128 v[220:223], v143 offset:38912
	ds_read_b128 v[224:227], v143 offset:39936
	global_load_lds_dwordx4 v[228:229], off
	v_lshl_add_u64 v[228:229], s[26:27], 0, v[132:133]
	s_mov_b32 m0, s79
	s_nop 0
	global_load_lds_dwordx4 v[228:229], off
	s_waitcnt lgkmcnt(8)
	s_barrier
	s_waitcnt lgkmcnt(12)
	s_waitcnt lgkmcnt(12)
	s_waitcnt lgkmcnt(7)
	v_mfma_f32_16x16x32_bf16 v[126:129], v[144:147], v[160:163], v[126:129]
	v_mfma_f32_16x16x32_bf16 v[122:125], v[152:155], v[160:163], v[122:125]
	s_waitcnt lgkmcnt(5)
	v_mfma_f32_16x16x32_bf16 v[118:121], v[144:147], v[192:195], v[118:121]
	v_mfma_f32_16x16x32_bf16 v[114:117], v[152:155], v[192:195], v[114:117]
	s_waitcnt lgkmcnt(3)
	v_mfma_f32_16x16x32_bf16 v[102:105], v[144:147], v[200:203], v[102:105]
	v_mfma_f32_16x16x32_bf16 v[98:101], v[152:155], v[200:203], v[98:101]
	s_waitcnt lgkmcnt(1)
	v_mfma_f32_16x16x32_bf16 v[86:89], v[144:147], v[220:223], v[86:89]
	v_mfma_f32_16x16x32_bf16 v[82:85], v[152:155], v[220:223], v[82:85]
	v_mfma_f32_16x16x32_bf16 v[126:129], v[148:151], v[188:191], v[126:129]
	v_mfma_f32_16x16x32_bf16 v[122:125], v[156:159], v[188:191], v[122:125]
	v_mfma_f32_16x16x32_bf16 v[118:121], v[148:151], v[196:199], v[118:121]
	v_mfma_f32_16x16x32_bf16 v[114:117], v[156:159], v[196:199], v[114:117]
	v_mfma_f32_16x16x32_bf16 v[102:105], v[148:151], v[216:219], v[102:105]
	v_mfma_f32_16x16x32_bf16 v[98:101], v[156:159], v[216:219], v[98:101]
	s_waitcnt lgkmcnt(0)
	v_mfma_f32_16x16x32_bf16 v[86:89], v[148:151], v[224:227], v[86:89]
	v_mfma_f32_16x16x32_bf16 v[82:85], v[156:159], v[224:227], v[82:85]
	s_barrier
	s_add_i32 s17, 0, 0x1c000
	s_add_i32 s2, s2, s3
	v_add_u32_e32 v206, s17, v141
	v_lshl_add_u64 v[164:165], v[164:165], 0, s[28:29]
	s_mov_b32 m0, s2
	ds_read_b128 v[228:231], v206
	ds_read_b128 v[232:235], v206 offset:1024
	ds_read_b128 v[236:239], v206 offset:2048
	ds_read_b128 v[240:243], v206 offset:3072
	global_load_lds_dwordx4 v[164:165], off
	v_lshl_add_u64 v[164:165], v[204:205], 0, s[28:29]
	s_add_i32 m0, s2, 0x2000
	s_nop 0
	global_load_lds_dwordx4 v[164:165], off
	s_barrier
	s_waitcnt lgkmcnt(4)
	s_waitcnt lgkmcnt(4)
	s_waitcnt lgkmcnt(3)
	v_mfma_f32_16x16x32_bf16 v[110:113], v[228:231], v[160:163], v[110:113]
	s_waitcnt lgkmcnt(1)
	v_mfma_f32_16x16x32_bf16 v[106:109], v[236:239], v[160:163], v[106:109]
	v_mfma_f32_16x16x32_bf16 v[94:97], v[228:231], v[192:195], v[94:97]
	v_mfma_f32_16x16x32_bf16 v[90:93], v[236:239], v[192:195], v[90:93]
	v_mfma_f32_16x16x32_bf16 v[78:81], v[228:231], v[200:203], v[78:81]
	v_mfma_f32_16x16x32_bf16 v[74:77], v[236:239], v[200:203], v[74:77]
	v_mfma_f32_16x16x32_bf16 v[70:73], v[228:231], v[220:223], v[70:73]
	v_mfma_f32_16x16x32_bf16 v[66:69], v[236:239], v[220:223], v[66:69]
	v_mfma_f32_16x16x32_bf16 v[110:113], v[232:235], v[188:191], v[110:113]
	s_waitcnt lgkmcnt(0)
	v_mfma_f32_16x16x32_bf16 v[106:109], v[240:243], v[188:191], v[106:109]
	v_mfma_f32_16x16x32_bf16 v[94:97], v[232:235], v[196:199], v[94:97]
	v_mfma_f32_16x16x32_bf16 v[90:93], v[240:243], v[196:199], v[90:93]
	v_mfma_f32_16x16x32_bf16 v[78:81], v[232:235], v[216:219], v[78:81]
	v_mfma_f32_16x16x32_bf16 v[74:77], v[240:243], v[216:219], v[74:77]
	v_mfma_f32_16x16x32_bf16 v[70:73], v[232:235], v[224:227], v[70:73]
	v_mfma_f32_16x16x32_bf16 v[66:69], v[240:243], v[224:227], v[66:69]
	s_mov_b32 m0, s80
	v_lshl_add_u64 v[164:165], v[244:245], 0, s[28:29]
	s_barrier
	ds_read_b128 v[160:163], v143 offset:49152
	ds_read_b128 v[188:191], v143 offset:50176
	ds_read_b128 v[192:195], v143 offset:51200
	ds_read_b128 v[196:199], v143 offset:52224
	ds_read_b128 v[200:203], v143 offset:53248
	ds_read_b128 v[216:219], v143 offset:54272
	ds_read_b128 v[220:223], v143 offset:55296
	ds_read_b128 v[224:227], v143 offset:56320
	global_load_lds_dwordx4 v[164:165], off
	v_lshl_add_u64 v[164:165], v[246:247], 0, s[28:29]
	s_mov_b32 m0, s81
	s_nop 0
	global_load_lds_dwordx4 v[164:165], off
	s_barrier
	s_waitcnt lgkmcnt(8)
	s_waitcnt lgkmcnt(8)
	s_waitcnt lgkmcnt(7)
	v_mfma_f32_16x16x32_bf16 v[62:65], v[144:147], v[160:163], v[62:65]
	v_mfma_f32_16x16x32_bf16 v[58:61], v[152:155], v[160:163], v[58:61]
	s_waitcnt lgkmcnt(5)
	v_mfma_f32_16x16x32_bf16 v[54:57], v[144:147], v[192:195], v[54:57]
	v_mfma_f32_16x16x32_bf16 v[50:53], v[152:155], v[192:195], v[50:53]
	s_waitcnt lgkmcnt(3)
	v_mfma_f32_16x16x32_bf16 v[38:41], v[144:147], v[200:203], v[38:41]
	v_mfma_f32_16x16x32_bf16 v[34:37], v[152:155], v[200:203], v[34:37]
	s_waitcnt lgkmcnt(1)
	v_mfma_f32_16x16x32_bf16 v[22:25], v[144:147], v[220:223], v[22:25]
	v_mfma_f32_16x16x32_bf16 v[18:21], v[152:155], v[220:223], v[18:21]
	v_mfma_f32_16x16x32_bf16 v[62:65], v[148:151], v[188:191], v[62:65]
	v_mfma_f32_16x16x32_bf16 v[58:61], v[156:159], v[188:191], v[58:61]
	v_mfma_f32_16x16x32_bf16 v[54:57], v[148:151], v[196:199], v[54:57]
	v_mfma_f32_16x16x32_bf16 v[50:53], v[156:159], v[196:199], v[50:53]
	v_mfma_f32_16x16x32_bf16 v[38:41], v[148:151], v[216:219], v[38:41]
	v_mfma_f32_16x16x32_bf16 v[34:37], v[156:159], v[216:219], v[34:37]
	s_waitcnt lgkmcnt(0)
	v_mfma_f32_16x16x32_bf16 v[22:25], v[148:151], v[224:227], v[22:25]
	v_mfma_f32_16x16x32_bf16 v[18:21], v[156:159], v[224:227], v[18:21]
	s_barrier
	s_add_u32 s26, s70, 0x80080
	s_addc_u32 s27, s71, 0
	s_add_i32 s2, s17, s3
	v_lshl_add_u64 v[144:145], s[26:27], 0, v[0:1]
	s_mov_b32 m0, s2
	s_nop 0
	global_load_lds_dwordx4 v[144:145], off
	v_lshl_add_u64 v[144:145], s[26:27], 0, v[130:131]
	s_add_i32 m0, s2, 0x2000
	s_nop 0
	global_load_lds_dwordx4 v[144:145], off
	s_waitcnt vmcnt(6)
	s_barrier
	v_mfma_f32_16x16x32_bf16 v[46:49], v[228:231], v[160:163], v[46:49]
	v_mfma_f32_16x16x32_bf16 v[42:45], v[236:239], v[160:163], v[42:45]
	v_mfma_f32_16x16x32_bf16 v[30:33], v[228:231], v[192:195], v[30:33]
	v_mfma_f32_16x16x32_bf16 v[26:29], v[236:239], v[192:195], v[26:29]
	v_mfma_f32_16x16x32_bf16 v[14:17], v[228:231], v[200:203], v[14:17]
	v_mfma_f32_16x16x32_bf16 v[10:13], v[236:239], v[200:203], v[10:13]
	v_mfma_f32_16x16x32_bf16 v[6:9], v[228:231], v[220:223], v[6:9]
	v_mfma_f32_16x16x32_bf16 v[2:5], v[236:239], v[220:223], v[2:5]
	v_mfma_f32_16x16x32_bf16 v[46:49], v[232:235], v[188:191], v[46:49]
	v_mfma_f32_16x16x32_bf16 v[42:45], v[240:243], v[188:191], v[42:45]
	v_mfma_f32_16x16x32_bf16 v[30:33], v[232:235], v[196:199], v[30:33]
	v_mfma_f32_16x16x32_bf16 v[26:29], v[240:243], v[196:199], v[26:29]
	v_mfma_f32_16x16x32_bf16 v[14:17], v[232:235], v[216:219], v[14:17]
	v_mfma_f32_16x16x32_bf16 v[10:13], v[240:243], v[216:219], v[10:13]
	v_mfma_f32_16x16x32_bf16 v[6:9], v[232:235], v[224:227], v[6:9]
	v_mfma_f32_16x16x32_bf16 v[2:5], v[240:243], v[224:227], v[2:5]
	s_add_i32 s44, s44, 2
	s_add_u32 s68, s68, 0x100
	s_addc_u32 s69, s69, 0
	s_add_u32 s43, s43, 0x100
	s_addc_u32 s92, s92, 0
	s_cmp_gt_u32 s44, 29
	s_barrier
	s_cbranch_scc0 .LBB0_655
	v_lshl_add_u32 v144, s47, 8, v140
	v_lshl_or_b32 v146, s46, 8, v142
	v_ashrrev_i32_e32 v145, 31, v144
	v_cvt_pk_bf16_f32 v126, v126, v127
	v_cvt_pk_bf16_f32 v127, v128, v129
	v_cvt_pk_bf16_f32 v128, v122, v123
	v_lshlrev_b64 v[122:123], 12, v[144:145]
	v_ashrrev_i32_e32 v147, 31, v146
	v_cvt_pk_bf16_f32 v129, v124, v125
	v_lshl_add_u64 v[122:123], s[22:23], 0, v[122:123]
	v_lshlrev_b64 v[124:125], 1, v[146:147]
	v_lshl_add_u64 v[122:123], v[122:123], 0, v[124:125]
	v_cvt_pk_bf16_f32 v110, v110, v111
	v_cvt_pk_bf16_f32 v111, v112, v113
	v_cvt_pk_bf16_f32 v112, v106, v107
	v_cvt_pk_bf16_f32 v113, v108, v109
	global_store_dwordx4 v[122:123], v[110:113], off offset:256
	v_cvt_pk_bf16_f32 v94, v94, v95
	v_cvt_pk_bf16_f32 v95, v96, v97
	v_or_b32_e32 v110, 16, v144
	v_ashrrev_i32_e32 v111, 31, v110
	v_lshlrev_b64 v[110:111], 12, v[110:111]
	v_lshl_add_u64 v[110:111], s[22:23], 0, v[110:111]
	v_lshl_add_u64 v[110:111], v[110:111], 0, v[124:125]
	v_cvt_pk_bf16_f32 v96, v90, v91
	v_cvt_pk_bf16_f32 v97, v92, v93
	global_store_dwordx4 v[110:111], v[94:97], off offset:256
	s_mov_b32 s2, 0x80000
	v_cvt_pk_bf16_f32 v62, v62, v63
	v_or_b32_e32 v94, 32, v144
	v_ashrrev_i32_e32 v95, 31, v94
	v_cvt_pk_bf16_f32 v63, v64, v65
	v_cvt_pk_bf16_f32 v65, v60, v61
	s_mov_b64 s[4:5], 0x80000
	v_add_co_u32_e32 v60, vcc, s2, v122
	v_lshlrev_b64 v[94:95], 12, v[94:95]
	v_cvt_pk_bf16_f32 v64, v58, v59
	v_lshl_add_u64 v[58:59], v[122:123], 0, s[4:5]
	v_addc_co_u32_e32 v61, vcc, 0, v123, vcc
	v_cvt_pk_bf16_f32 v46, v46, v47
	v_cvt_pk_bf16_f32 v47, v48, v49
	v_cvt_pk_bf16_f32 v48, v42, v43
	v_cvt_pk_bf16_f32 v49, v44, v45
	s_mov_b32 s2, 0x90000
	v_lshl_add_u64 v[94:95], s[22:23], 0, v[94:95]
	global_store_dwordx4 v[58:59], v[46:49], off offset:256
	s_mov_b64 s[4:5], 0x90000
	v_lshl_add_u64 v[94:95], v[94:95], 0, v[124:125]
	v_add_co_u32_e32 v48, vcc, s2, v122
	v_cvt_pk_bf16_f32 v78, v78, v79
	v_cvt_pk_bf16_f32 v79, v80, v81
	v_cvt_pk_bf16_f32 v80, v74, v75
	v_cvt_pk_bf16_f32 v81, v76, v77
	v_lshl_add_u64 v[46:47], v[122:123], 0, s[4:5]
	v_addc_co_u32_e32 v49, vcc, 0, v123, vcc
	v_cvt_pk_bf16_f32 v30, v30, v31
	v_cvt_pk_bf16_f32 v31, v32, v33
	v_cvt_pk_bf16_f32 v32, v26, v27
	v_cvt_pk_bf16_f32 v33, v28, v29
	s_mov_b32 s2, 0xa0000
	global_store_dwordx4 v[94:95], v[78:81], off offset:256
	global_store_dwordx4 v[46:47], v[30:33], off offset:256
	s_mov_b64 s[4:5], 0xa0000
	v_or_b32_e32 v78, 48, v144
	v_add_co_u32_e32 v32, vcc, s2, v122
	v_ashrrev_i32_e32 v79, 31, v78
	v_lshl_add_u64 v[30:31], v[122:123], 0, s[4:5]
	v_addc_co_u32_e32 v33, vcc, 0, v123, vcc
	v_cvt_pk_bf16_f32 v14, v14, v15
	v_cvt_pk_bf16_f32 v15, v16, v17
	v_cvt_pk_bf16_f32 v16, v10, v11
	v_cvt_pk_bf16_f32 v17, v12, v13
	s_mov_b32 s2, 0xb0000
	v_lshlrev_b64 v[78:79], 12, v[78:79]
	global_store_dwordx4 v[30:31], v[14:17], off offset:256
	v_lshl_add_u64 v[78:79], s[22:23], 0, v[78:79]
	s_mov_b64 s[4:5], 0xb0000
	v_add_co_u32_e32 v16, vcc, s2, v122
	v_cvt_pk_bf16_f32 v106, v118, v119
	s_nop 0
	v_addc_co_u32_e32 v17, vcc, 0, v123, vcc
	v_cvt_pk_bf16_f32 v107, v120, v121
	v_cvt_pk_bf16_f32 v108, v114, v115
	v_cvt_pk_bf16_f32 v109, v116, v117
	v_cvt_pk_bf16_f32 v90, v102, v103
	v_cvt_pk_bf16_f32 v91, v104, v105
	v_cvt_pk_bf16_f32 v92, v98, v99
	v_cvt_pk_bf16_f32 v93, v100, v101
	v_cvt_pk_bf16_f32 v74, v86, v87
	v_cvt_pk_bf16_f32 v75, v88, v89
	v_cvt_pk_bf16_f32 v76, v82, v83
	v_cvt_pk_bf16_f32 v77, v84, v85
	v_lshl_add_u64 v[78:79], v[78:79], 0, v[124:125]
	v_cvt_pk_bf16_f32 v70, v70, v71
	v_cvt_pk_bf16_f32 v71, v72, v73
	v_cvt_pk_bf16_f32 v72, v66, v67
	v_cvt_pk_bf16_f32 v73, v68, v69
	v_cvt_pk_bf16_f32 v42, v54, v55
	v_cvt_pk_bf16_f32 v43, v56, v57
	v_cvt_pk_bf16_f32 v44, v50, v51
	v_cvt_pk_bf16_f32 v45, v52, v53
	v_cvt_pk_bf16_f32 v26, v38, v39
	v_cvt_pk_bf16_f32 v27, v40, v41
	v_cvt_pk_bf16_f32 v28, v34, v35
	v_cvt_pk_bf16_f32 v29, v36, v37
	v_cvt_pk_bf16_f32 v10, v22, v23
	v_cvt_pk_bf16_f32 v11, v24, v25
	v_cvt_pk_bf16_f32 v12, v18, v19
	v_cvt_pk_bf16_f32 v13, v20, v21
	v_lshl_add_u64 v[14:15], v[122:123], 0, s[4:5]
	v_cvt_pk_bf16_f32 v6, v6, v7
	v_cvt_pk_bf16_f32 v7, v8, v9
	v_cvt_pk_bf16_f32 v8, v2, v3
	v_cvt_pk_bf16_f32 v9, v4, v5
	s_and_b64 vcc, exec, s[0:1]
	s_mov_b32 s46, s42
	s_mov_b32 s47, s54
	s_mov_b64 s[70:71], s[64:65]
	s_mov_b64 s[68:69], s[62:63]
	global_store_dwordx4 v[122:123], v[126:129], off
	global_store_dwordx4 v[110:111], v[106:109], off
	global_store_dwordx4 v[94:95], v[90:93], off
	global_store_dwordx4 v[78:79], v[74:77], off
	global_store_dwordx4 v[78:79], v[70:73], off offset:256
	global_store_dwordx4 v[60:61], v[62:65], off
	global_store_dwordx4 v[48:49], v[42:45], off
	global_store_dwordx4 v[32:33], v[26:29], off
	global_store_dwordx4 v[16:17], v[10:13], off
	global_store_dwordx4 v[14:15], v[6:9], off offset:256
	s_cbranch_vccz .LBB0_652
	v_readlane_b32 s0, v254, 12
	s_waitcnt vmcnt(0)
	v_readlane_b32 s1, v254, 13
	v_readlane_b32 s84, v251, 38
	s_andn2_b64 vcc, exec, s[0:1]
	v_readlane_b32 s85, v251, 39
	v_readlane_b32 s86, v251, 40
	v_readlane_b32 s87, v251, 41
	s_cbranch_vccnz .LBB0_659
	s_barrier

.LBB0_724:
	s_add_u32 s2, s68, 0xfff80080
	s_addc_u32 s17, s69, -1
	s_add_i32 s26, 0, 0x10000
	v_add_u32_e32 v156, s26, v141
	ds_read_b128 v[144:147], v156
	ds_read_b128 v[148:151], v156 offset:1024
	ds_read_b128 v[152:155], v156 offset:2048
	ds_read_b128 v[156:159], v156 offset:3072
	s_cmp_eq_u32 s83, 28
	s_cselect_b32 s73, s55, s17
	s_cselect_b32 s72, s81, s2
	s_cselect_b32 s71, s24, s82
	s_cselect_b32 s70, s25, s43
	v_lshl_add_u64 v[164:165], s[68:69], 0, v[136:137]
	s_add_i32 m0, s58, 0xc000
	ds_read_b128 v[160:163], v143
	ds_read_b128 v[188:191], v143 offset:1024
	ds_read_b128 v[192:195], v143 offset:2048
	ds_read_b128 v[196:199], v143 offset:3072
	ds_read_b128 v[200:203], v143 offset:4096
	ds_read_b128 v[216:219], v143 offset:5120
	ds_read_b128 v[220:223], v143 offset:6144
	ds_read_b128 v[224:227], v143 offset:7168
	global_load_lds_dwordx4 v[164:165], off
	v_lshl_add_u64 v[164:165], s[68:69], 0, v[138:139]
	s_add_i32 m0, s58, 0xe000
	s_nop 0
	global_load_lds_dwordx4 v[164:165], off
	s_waitcnt lgkmcnt(8)
	s_barrier
	s_waitcnt lgkmcnt(12)
	s_waitcnt lgkmcnt(12)
	s_waitcnt lgkmcnt(7)
	v_mfma_f32_16x16x32_bf16 v[126:129], v[144:147], v[160:163], v[126:129]
	v_mfma_f32_16x16x32_bf16 v[122:125], v[152:155], v[160:163], v[122:125]
	s_waitcnt lgkmcnt(5)
	v_mfma_f32_16x16x32_bf16 v[118:121], v[144:147], v[192:195], v[118:121]
	v_mfma_f32_16x16x32_bf16 v[114:117], v[152:155], v[192:195], v[114:117]
	s_waitcnt lgkmcnt(3)
	v_mfma_f32_16x16x32_bf16 v[102:105], v[144:147], v[200:203], v[102:105]
	v_mfma_f32_16x16x32_bf16 v[98:101], v[152:155], v[200:203], v[98:101]
	s_waitcnt lgkmcnt(1)
	v_mfma_f32_16x16x32_bf16 v[86:89], v[144:147], v[220:223], v[86:89]
	v_mfma_f32_16x16x32_bf16 v[82:85], v[152:155], v[220:223], v[82:85]
	v_mfma_f32_16x16x32_bf16 v[126:129], v[148:151], v[188:191], v[126:129]
	v_mfma_f32_16x16x32_bf16 v[122:125], v[156:159], v[188:191], v[122:125]
	v_mfma_f32_16x16x32_bf16 v[118:121], v[148:151], v[196:199], v[118:121]
	v_mfma_f32_16x16x32_bf16 v[114:117], v[156:159], v[196:199], v[114:117]
	v_mfma_f32_16x16x32_bf16 v[102:105], v[148:151], v[216:219], v[102:105]
	v_mfma_f32_16x16x32_bf16 v[98:101], v[156:159], v[216:219], v[98:101]
	s_waitcnt lgkmcnt(0)
	v_mfma_f32_16x16x32_bf16 v[86:89], v[148:151], v[224:227], v[86:89]
	v_mfma_f32_16x16x32_bf16 v[82:85], v[156:159], v[224:227], v[82:85]
	s_barrier
	s_add_i32 s2, 0, 0x14000
	v_add_u32_e32 v164, s2, v141
	s_add_i32 s17, s26, s3
	ds_read_b128 v[228:231], v164
	ds_read_b128 v[232:235], v164 offset:1024
	ds_read_b128 v[236:239], v164 offset:2048
	ds_read_b128 v[240:243], v164 offset:3072
	v_lshl_add_u64 v[164:165], s[70:71], 0, v[0:1]
	s_mov_b32 m0, s17
	v_lshl_add_u64 v[204:205], s[70:71], 0, v[130:131]
	global_load_lds_dwordx4 v[164:165], off
	s_add_i32 m0, s17, 0x2000
	s_nop 0
	global_load_lds_dwordx4 v[204:205], off
	s_barrier
	s_waitcnt lgkmcnt(4)
	s_waitcnt lgkmcnt(4)
	s_waitcnt lgkmcnt(3)
	v_mfma_f32_16x16x32_bf16 v[110:113], v[228:231], v[160:163], v[110:113]
	s_waitcnt lgkmcnt(1)
	v_mfma_f32_16x16x32_bf16 v[106:109], v[236:239], v[160:163], v[106:109]
	v_mfma_f32_16x16x32_bf16 v[94:97], v[228:231], v[192:195], v[94:97]
	v_mfma_f32_16x16x32_bf16 v[90:93], v[236:239], v[192:195], v[90:93]
	v_mfma_f32_16x16x32_bf16 v[78:81], v[228:231], v[200:203], v[78:81]
	v_mfma_f32_16x16x32_bf16 v[74:77], v[236:239], v[200:203], v[74:77]
	v_mfma_f32_16x16x32_bf16 v[70:73], v[228:231], v[220:223], v[70:73]
	v_mfma_f32_16x16x32_bf16 v[66:69], v[236:239], v[220:223], v[66:69]
	v_mfma_f32_16x16x32_bf16 v[110:113], v[232:235], v[188:191], v[110:113]
	s_waitcnt lgkmcnt(0)
	v_mfma_f32_16x16x32_bf16 v[106:109], v[240:243], v[188:191], v[106:109]
	v_mfma_f32_16x16x32_bf16 v[94:97], v[232:235], v[196:199], v[94:97]
	v_mfma_f32_16x16x32_bf16 v[90:93], v[240:243], v[196:199], v[90:93]
	v_mfma_f32_16x16x32_bf16 v[78:81], v[232:235], v[216:219], v[78:81]
	v_mfma_f32_16x16x32_bf16 v[74:77], v[240:243], v[216:219], v[74:77]
	v_mfma_f32_16x16x32_bf16 v[70:73], v[232:235], v[224:227], v[70:73]
	v_mfma_f32_16x16x32_bf16 v[66:69], v[240:243], v[224:227], v[66:69]
	s_mov_b32 m0, s58
	v_lshl_add_u64 v[244:245], s[72:73], 0, v[134:135]
	s_barrier
	ds_read_b128 v[160:163], v143 offset:16384
	ds_read_b128 v[188:191], v143 offset:17408
	ds_read_b128 v[192:195], v143 offset:18432
	ds_read_b128 v[196:199], v143 offset:19456
	ds_read_b128 v[200:203], v143 offset:20480
	ds_read_b128 v[216:219], v143 offset:21504
	ds_read_b128 v[220:223], v143 offset:22528
	ds_read_b128 v[224:227], v143 offset:23552
	global_load_lds_dwordx4 v[244:245], off
	v_lshl_add_u64 v[246:247], s[72:73], 0, v[132:133]
	s_mov_b32 m0, s74
	s_nop 0
	global_load_lds_dwordx4 v[246:247], off
	s_barrier
	s_waitcnt lgkmcnt(8)
	s_waitcnt lgkmcnt(8)
	s_waitcnt lgkmcnt(7)
	v_mfma_f32_16x16x32_bf16 v[62:65], v[144:147], v[160:163], v[62:65]
	v_mfma_f32_16x16x32_bf16 v[58:61], v[152:155], v[160:163], v[58:61]
	s_waitcnt lgkmcnt(5)
	v_mfma_f32_16x16x32_bf16 v[54:57], v[144:147], v[192:195], v[54:57]
	v_mfma_f32_16x16x32_bf16 v[50:53], v[152:155], v[192:195], v[50:53]
	s_waitcnt lgkmcnt(3)
	v_mfma_f32_16x16x32_bf16 v[38:41], v[144:147], v[200:203], v[38:41]
	v_mfma_f32_16x16x32_bf16 v[34:37], v[152:155], v[200:203], v[34:37]
	s_waitcnt lgkmcnt(1)
	v_mfma_f32_16x16x32_bf16 v[22:25], v[144:147], v[220:223], v[22:25]
	v_mfma_f32_16x16x32_bf16 v[18:21], v[152:155], v[220:223], v[18:21]
	v_mfma_f32_16x16x32_bf16 v[62:65], v[148:151], v[188:191], v[62:65]
	v_mfma_f32_16x16x32_bf16 v[58:61], v[156:159], v[188:191], v[58:61]
	v_mfma_f32_16x16x32_bf16 v[54:57], v[148:151], v[196:199], v[54:57]
	v_mfma_f32_16x16x32_bf16 v[50:53], v[156:159], v[196:199], v[50:53]
	v_mfma_f32_16x16x32_bf16 v[38:41], v[148:151], v[216:219], v[38:41]
	v_mfma_f32_16x16x32_bf16 v[34:37], v[156:159], v[216:219], v[34:37]
	s_waitcnt lgkmcnt(0)
	v_mfma_f32_16x16x32_bf16 v[22:25], v[148:151], v[224:227], v[22:25]
	v_mfma_f32_16x16x32_bf16 v[18:21], v[156:159], v[224:227], v[18:21]
	s_barrier
	s_add_u32 s44, s70, 0x80000
	s_addc_u32 s45, s71, 0
	s_add_i32 s2, s2, s3
	v_lshl_add_u64 v[144:145], s[44:45], 0, v[0:1]
	s_mov_b32 m0, s2
	s_nop 0
	global_load_lds_dwordx4 v[144:145], off
	v_lshl_add_u64 v[144:145], s[44:45], 0, v[130:131]
	s_add_i32 m0, s2, 0x2000
	s_nop 0
	global_load_lds_dwordx4 v[144:145], off
	s_waitcnt vmcnt(6)
	s_barrier
	v_mfma_f32_16x16x32_bf16 v[46:49], v[228:231], v[160:163], v[46:49]
	v_mfma_f32_16x16x32_bf16 v[42:45], v[236:239], v[160:163], v[42:45]
	v_mfma_f32_16x16x32_bf16 v[30:33], v[228:231], v[192:195], v[30:33]
	v_mfma_f32_16x16x32_bf16 v[26:29], v[236:239], v[192:195], v[26:29]
	v_mfma_f32_16x16x32_bf16 v[14:17], v[228:231], v[200:203], v[14:17]
	v_mfma_f32_16x16x32_bf16 v[10:13], v[236:239], v[200:203], v[10:13]
	v_mfma_f32_16x16x32_bf16 v[6:9], v[228:231], v[220:223], v[6:9]
	v_mfma_f32_16x16x32_bf16 v[2:5], v[236:239], v[220:223], v[2:5]
	v_mfma_f32_16x16x32_bf16 v[46:49], v[232:235], v[188:191], v[46:49]
	v_mfma_f32_16x16x32_bf16 v[42:45], v[240:243], v[188:191], v[42:45]
	v_mfma_f32_16x16x32_bf16 v[30:33], v[232:235], v[196:199], v[30:33]
	v_mfma_f32_16x16x32_bf16 v[26:29], v[240:243], v[196:199], v[26:29]
	v_mfma_f32_16x16x32_bf16 v[14:17], v[232:235], v[216:219], v[14:17]
	v_mfma_f32_16x16x32_bf16 v[10:13], v[240:243], v[216:219], v[10:13]
	v_mfma_f32_16x16x32_bf16 v[6:9], v[232:235], v[224:227], v[6:9]
	v_mfma_f32_16x16x32_bf16 v[2:5], v[240:243], v[224:227], v[2:5]
	s_add_i32 s2, 0, 0x18000
	v_add_u32_e32 v156, s2, v141
	s_barrier
	ds_read_b128 v[144:147], v156
	ds_read_b128 v[148:151], v156 offset:1024
	ds_read_b128 v[152:155], v156 offset:2048
	ds_read_b128 v[156:159], v156 offset:3072
	s_add_u32 s44, s72, 0x80000
	s_addc_u32 s45, s73, 0
	s_mov_b32 m0, s75
	v_lshl_add_u64 v[228:229], s[44:45], 0, v[134:135]
	ds_read_b128 v[160:163], v143 offset:32768
	ds_read_b128 v[188:191], v143 offset:33792
	ds_read_b128 v[192:195], v143 offset:34816
	ds_read_b128 v[196:199], v143 offset:35840
	ds_read_b128 v[200:203], v143 offset:36864
	ds_read_b128 v[216:219], v143 offset:37888
	ds_read_b128 v[220:223], v143 offset:38912
	ds_read_b128 v[224:227], v143 offset:39936
	global_load_lds_dwordx4 v[228:229], off
	v_lshl_add_u64 v[228:229], s[44:45], 0, v[132:133]
	s_mov_b32 m0, s77
	s_nop 0
	global_load_lds_dwordx4 v[228:229], off
	s_waitcnt lgkmcnt(8)
	s_barrier
	s_waitcnt lgkmcnt(12)
	s_waitcnt lgkmcnt(12)
	s_waitcnt lgkmcnt(7)
	v_mfma_f32_16x16x32_bf16 v[126:129], v[144:147], v[160:163], v[126:129]
	v_mfma_f32_16x16x32_bf16 v[122:125], v[152:155], v[160:163], v[122:125]
	s_waitcnt lgkmcnt(5)
	v_mfma_f32_16x16x32_bf16 v[118:121], v[144:147], v[192:195], v[118:121]
	v_mfma_f32_16x16x32_bf16 v[114:117], v[152:155], v[192:195], v[114:117]
	s_waitcnt lgkmcnt(3)
	v_mfma_f32_16x16x32_bf16 v[102:105], v[144:147], v[200:203], v[102:105]
	v_mfma_f32_16x16x32_bf16 v[98:101], v[152:155], v[200:203], v[98:101]
	s_waitcnt lgkmcnt(1)
	v_mfma_f32_16x16x32_bf16 v[86:89], v[144:147], v[220:223], v[86:89]
	v_mfma_f32_16x16x32_bf16 v[82:85], v[152:155], v[220:223], v[82:85]
	v_mfma_f32_16x16x32_bf16 v[126:129], v[148:151], v[188:191], v[126:129]
	v_mfma_f32_16x16x32_bf16 v[122:125], v[156:159], v[188:191], v[122:125]
	v_mfma_f32_16x16x32_bf16 v[118:121], v[148:151], v[196:199], v[118:121]
	v_mfma_f32_16x16x32_bf16 v[114:117], v[156:159], v[196:199], v[114:117]
	v_mfma_f32_16x16x32_bf16 v[102:105], v[148:151], v[216:219], v[102:105]
	v_mfma_f32_16x16x32_bf16 v[98:101], v[156:159], v[216:219], v[98:101]
	s_waitcnt lgkmcnt(0)
	v_mfma_f32_16x16x32_bf16 v[86:89], v[148:151], v[224:227], v[86:89]
	v_mfma_f32_16x16x32_bf16 v[82:85], v[156:159], v[224:227], v[82:85]
	s_barrier
	s_add_i32 s17, 0, 0x1c000
	s_add_i32 s2, s2, s3
	v_add_u32_e32 v206, s17, v141
	v_lshl_add_u64 v[164:165], v[164:165], 0, s[28:29]
	s_mov_b32 m0, s2
	ds_read_b128 v[228:231], v206
	ds_read_b128 v[232:235], v206 offset:1024
	ds_read_b128 v[236:239], v206 offset:2048
	ds_read_b128 v[240:243], v206 offset:3072
	global_load_lds_dwordx4 v[164:165], off
	v_lshl_add_u64 v[164:165], v[204:205], 0, s[28:29]
	s_add_i32 m0, s2, 0x2000
	s_nop 0
	global_load_lds_dwordx4 v[164:165], off
	s_barrier
	s_waitcnt lgkmcnt(4)
	s_waitcnt lgkmcnt(4)
	s_waitcnt lgkmcnt(3)
	v_mfma_f32_16x16x32_bf16 v[110:113], v[228:231], v[160:163], v[110:113]
	s_waitcnt lgkmcnt(1)
	v_mfma_f32_16x16x32_bf16 v[106:109], v[236:239], v[160:163], v[106:109]
	v_mfma_f32_16x16x32_bf16 v[94:97], v[228:231], v[192:195], v[94:97]
	v_mfma_f32_16x16x32_bf16 v[90:93], v[236:239], v[192:195], v[90:93]
	v_mfma_f32_16x16x32_bf16 v[78:81], v[228:231], v[200:203], v[78:81]
	v_mfma_f32_16x16x32_bf16 v[74:77], v[236:239], v[200:203], v[74:77]
	v_mfma_f32_16x16x32_bf16 v[70:73], v[228:231], v[220:223], v[70:73]
	v_mfma_f32_16x16x32_bf16 v[66:69], v[236:239], v[220:223], v[66:69]
	v_mfma_f32_16x16x32_bf16 v[110:113], v[232:235], v[188:191], v[110:113]
	s_waitcnt lgkmcnt(0)
	v_mfma_f32_16x16x32_bf16 v[106:109], v[240:243], v[188:191], v[106:109]
	v_mfma_f32_16x16x32_bf16 v[94:97], v[232:235], v[196:199], v[94:97]
	v_mfma_f32_16x16x32_bf16 v[90:93], v[240:243], v[196:199], v[90:93]
	v_mfma_f32_16x16x32_bf16 v[78:81], v[232:235], v[216:219], v[78:81]
	v_mfma_f32_16x16x32_bf16 v[74:77], v[240:243], v[216:219], v[74:77]
	v_mfma_f32_16x16x32_bf16 v[70:73], v[232:235], v[224:227], v[70:73]
	v_mfma_f32_16x16x32_bf16 v[66:69], v[240:243], v[224:227], v[66:69]
	s_mov_b32 m0, s78
	v_lshl_add_u64 v[164:165], v[244:245], 0, s[28:29]
	s_barrier
	ds_read_b128 v[160:163], v143 offset:49152
	ds_read_b128 v[188:191], v143 offset:50176
	ds_read_b128 v[192:195], v143 offset:51200
	ds_read_b128 v[196:199], v143 offset:52224
	ds_read_b128 v[200:203], v143 offset:53248
	ds_read_b128 v[216:219], v143 offset:54272
	ds_read_b128 v[220:223], v143 offset:55296
	ds_read_b128 v[224:227], v143 offset:56320
	global_load_lds_dwordx4 v[164:165], off
	v_lshl_add_u64 v[164:165], v[246:247], 0, s[28:29]
	s_mov_b32 m0, s79
	s_nop 0
	global_load_lds_dwordx4 v[164:165], off
	s_barrier
	s_waitcnt lgkmcnt(8)
	s_waitcnt lgkmcnt(8)
	s_waitcnt lgkmcnt(7)
	v_mfma_f32_16x16x32_bf16 v[62:65], v[144:147], v[160:163], v[62:65]
	v_mfma_f32_16x16x32_bf16 v[58:61], v[152:155], v[160:163], v[58:61]
	s_waitcnt lgkmcnt(5)
	v_mfma_f32_16x16x32_bf16 v[54:57], v[144:147], v[192:195], v[54:57]
	v_mfma_f32_16x16x32_bf16 v[50:53], v[152:155], v[192:195], v[50:53]
	s_waitcnt lgkmcnt(3)
	v_mfma_f32_16x16x32_bf16 v[38:41], v[144:147], v[200:203], v[38:41]
	v_mfma_f32_16x16x32_bf16 v[34:37], v[152:155], v[200:203], v[34:37]
	s_waitcnt lgkmcnt(1)
	v_mfma_f32_16x16x32_bf16 v[22:25], v[144:147], v[220:223], v[22:25]
	v_mfma_f32_16x16x32_bf16 v[18:21], v[152:155], v[220:223], v[18:21]
	v_mfma_f32_16x16x32_bf16 v[62:65], v[148:151], v[188:191], v[62:65]
	v_mfma_f32_16x16x32_bf16 v[58:61], v[156:159], v[188:191], v[58:61]
	v_mfma_f32_16x16x32_bf16 v[54:57], v[148:151], v[196:199], v[54:57]
	v_mfma_f32_16x16x32_bf16 v[50:53], v[156:159], v[196:199], v[50:53]
	v_mfma_f32_16x16x32_bf16 v[38:41], v[148:151], v[216:219], v[38:41]
	v_mfma_f32_16x16x32_bf16 v[34:37], v[156:159], v[216:219], v[34:37]
	s_waitcnt lgkmcnt(0)
	v_mfma_f32_16x16x32_bf16 v[22:25], v[148:151], v[224:227], v[22:25]
	v_mfma_f32_16x16x32_bf16 v[18:21], v[156:159], v[224:227], v[18:21]
	s_barrier
	s_add_u32 s44, s70, 0x80080
	s_addc_u32 s45, s71, 0
	s_add_i32 s2, s17, s3
	v_lshl_add_u64 v[144:145], s[44:45], 0, v[0:1]
	s_mov_b32 m0, s2
	s_nop 0
	global_load_lds_dwordx4 v[144:145], off
	v_lshl_add_u64 v[144:145], s[44:45], 0, v[130:131]
	s_add_i32 m0, s2, 0x2000
	s_nop 0
	global_load_lds_dwordx4 v[144:145], off
	s_waitcnt vmcnt(6)
	s_barrier
	v_mfma_f32_16x16x32_bf16 v[46:49], v[228:231], v[160:163], v[46:49]
	v_mfma_f32_16x16x32_bf16 v[42:45], v[236:239], v[160:163], v[42:45]
	v_mfma_f32_16x16x32_bf16 v[30:33], v[228:231], v[192:195], v[30:33]
	v_mfma_f32_16x16x32_bf16 v[26:29], v[236:239], v[192:195], v[26:29]
	v_mfma_f32_16x16x32_bf16 v[14:17], v[228:231], v[200:203], v[14:17]
	v_mfma_f32_16x16x32_bf16 v[10:13], v[236:239], v[200:203], v[10:13]
	v_mfma_f32_16x16x32_bf16 v[6:9], v[228:231], v[220:223], v[6:9]
	v_mfma_f32_16x16x32_bf16 v[2:5], v[236:239], v[220:223], v[2:5]
	v_mfma_f32_16x16x32_bf16 v[46:49], v[232:235], v[188:191], v[46:49]
	v_mfma_f32_16x16x32_bf16 v[42:45], v[240:243], v[188:191], v[42:45]
	v_mfma_f32_16x16x32_bf16 v[30:33], v[232:235], v[196:199], v[30:33]
	v_mfma_f32_16x16x32_bf16 v[26:29], v[240:243], v[196:199], v[26:29]
	v_mfma_f32_16x16x32_bf16 v[14:17], v[232:235], v[216:219], v[14:17]
	v_mfma_f32_16x16x32_bf16 v[10:13], v[240:243], v[216:219], v[10:13]
	v_mfma_f32_16x16x32_bf16 v[6:9], v[232:235], v[224:227], v[6:9]
	v_mfma_f32_16x16x32_bf16 v[2:5], v[240:243], v[224:227], v[2:5]
	s_add_i32 s83, s83, 2
	s_add_u32 s68, s68, 0x100
	s_addc_u32 s69, s69, 0
	s_add_u32 s43, s43, 0x100
	s_addc_u32 s82, s82, 0
	s_cmp_gt_u32 s83, 29
	s_barrier
	s_cbranch_scc0 .LBB0_724
	v_lshl_add_u32 v146, s47, 8, v140
	v_lshl_or_b32 v144, s46, 8, v142
	v_cvt_pk_bf16_f32 v126, v126, v127
	v_cvt_pk_bf16_f32 v127, v128, v129
	v_cvt_pk_bf16_f32 v128, v122, v123
	v_mov_b64_e32 v[122:123], s[22:23]
	v_ashrrev_i32_e32 v145, 31, v144
	v_cvt_pk_bf16_f32 v70, v70, v71
	v_cvt_pk_bf16_f32 v71, v72, v73
	v_cvt_pk_bf16_f32 v72, v66, v67
	v_add_u32_e32 v66, 0x80, v146
	v_cvt_pk_bf16_f32 v129, v124, v125
	v_mad_i64_i32 v[124:125], s[24:25], v146, s48, v[122:123]
	v_lshlrev_b64 v[144:145], 1, v[144:145]
	v_cvt_pk_bf16_f32 v62, v62, v63
	v_cvt_pk_bf16_f32 v63, v64, v65
	v_cvt_pk_bf16_f32 v64, v58, v59
	v_mad_i64_i32 v[58:59], s[24:25], v66, s48, v[122:123]
	v_lshl_add_u64 v[124:125], v[124:125], 0, v[144:145]
	v_cvt_pk_bf16_f32 v110, v110, v111
	v_cvt_pk_bf16_f32 v111, v112, v113
	v_cvt_pk_bf16_f32 v112, v106, v107
	v_cvt_pk_bf16_f32 v113, v108, v109
	v_lshl_add_u64 v[58:59], v[58:59], 0, v[144:145]
	v_cvt_pk_bf16_f32 v46, v46, v47
	v_cvt_pk_bf16_f32 v47, v48, v49
	v_cvt_pk_bf16_f32 v48, v42, v43
	v_cvt_pk_bf16_f32 v49, v44, v45
	global_store_dwordx4 v[124:125], v[110:113], off offset:256
	global_store_dwordx4 v[58:59], v[46:49], off offset:256
	v_cvt_pk_bf16_f32 v94, v94, v95
	v_or_b32_e32 v110, 16, v146
	v_add_u32_e32 v46, 0x90, v146
	v_mad_i64_i32 v[110:111], s[24:25], v110, s48, v[122:123]
	v_mad_i64_i32 v[46:47], s[24:25], v46, s48, v[122:123]
	v_lshl_add_u64 v[110:111], v[110:111], 0, v[144:145]
	v_cvt_pk_bf16_f32 v95, v96, v97
	v_cvt_pk_bf16_f32 v96, v90, v91
	v_cvt_pk_bf16_f32 v97, v92, v93
	v_lshl_add_u64 v[46:47], v[46:47], 0, v[144:145]
	v_cvt_pk_bf16_f32 v30, v30, v31
	v_cvt_pk_bf16_f32 v31, v32, v33
	v_cvt_pk_bf16_f32 v32, v26, v27
	v_cvt_pk_bf16_f32 v33, v28, v29
	global_store_dwordx4 v[110:111], v[94:97], off offset:256
	global_store_dwordx4 v[46:47], v[30:33], off offset:256
	v_cvt_pk_bf16_f32 v78, v78, v79
	v_or_b32_e32 v94, 32, v146
	v_add_u32_e32 v30, 0xa0, v146
	v_mad_i64_i32 v[94:95], s[24:25], v94, s48, v[122:123]
	v_mad_i64_i32 v[30:31], s[24:25], v30, s48, v[122:123]
	v_lshl_add_u64 v[94:95], v[94:95], 0, v[144:145]
	v_cvt_pk_bf16_f32 v79, v80, v81
	v_cvt_pk_bf16_f32 v80, v74, v75
	v_cvt_pk_bf16_f32 v81, v76, v77
	v_lshl_add_u64 v[30:31], v[30:31], 0, v[144:145]
	v_cvt_pk_bf16_f32 v14, v14, v15
	v_cvt_pk_bf16_f32 v15, v16, v17
	v_cvt_pk_bf16_f32 v16, v10, v11
	v_cvt_pk_bf16_f32 v17, v12, v13
	global_store_dwordx4 v[94:95], v[78:81], off offset:256
	global_store_dwordx4 v[30:31], v[14:17], off offset:256
	v_cvt_pk_bf16_f32 v106, v118, v119
	v_or_b32_e32 v78, 48, v146
	v_add_u32_e32 v14, 0xb0, v146
	v_mad_i64_i32 v[78:79], s[24:25], v78, s48, v[122:123]
	v_mad_i64_i32 v[14:15], s[24:25], v14, s48, v[122:123]
	v_cvt_pk_bf16_f32 v107, v120, v121
	v_cvt_pk_bf16_f32 v108, v114, v115
	v_cvt_pk_bf16_f32 v109, v116, v117
	v_cvt_pk_bf16_f32 v90, v102, v103
	v_cvt_pk_bf16_f32 v91, v104, v105
	v_cvt_pk_bf16_f32 v92, v98, v99
	v_cvt_pk_bf16_f32 v93, v100, v101
	v_cvt_pk_bf16_f32 v74, v86, v87
	v_cvt_pk_bf16_f32 v75, v88, v89
	v_cvt_pk_bf16_f32 v76, v82, v83
	v_cvt_pk_bf16_f32 v77, v84, v85
	v_lshl_add_u64 v[78:79], v[78:79], 0, v[144:145]
	v_cvt_pk_bf16_f32 v73, v68, v69
	v_cvt_pk_bf16_f32 v65, v60, v61
	v_cvt_pk_bf16_f32 v42, v54, v55
	v_cvt_pk_bf16_f32 v43, v56, v57
	v_cvt_pk_bf16_f32 v44, v50, v51
	v_cvt_pk_bf16_f32 v45, v52, v53
	v_cvt_pk_bf16_f32 v26, v38, v39
	v_cvt_pk_bf16_f32 v27, v40, v41
	v_cvt_pk_bf16_f32 v28, v34, v35
	v_cvt_pk_bf16_f32 v29, v36, v37
	v_cvt_pk_bf16_f32 v10, v22, v23
	v_cvt_pk_bf16_f32 v11, v24, v25
	v_cvt_pk_bf16_f32 v12, v18, v19
	v_cvt_pk_bf16_f32 v13, v20, v21
	v_lshl_add_u64 v[14:15], v[14:15], 0, v[144:145]
	v_cvt_pk_bf16_f32 v6, v6, v7
	v_cvt_pk_bf16_f32 v7, v8, v9
	v_cvt_pk_bf16_f32 v8, v2, v3
	v_cvt_pk_bf16_f32 v9, v4, v5
	s_and_b64 vcc, exec, s[0:1]
	s_mov_b32 s46, s42
	s_mov_b32 s47, s54
	s_mov_b64 s[70:71], s[64:65]
	s_mov_b64 s[68:69], s[62:63]
	global_store_dwordx4 v[124:125], v[126:129], off
	global_store_dwordx4 v[110:111], v[106:109], off
	global_store_dwordx4 v[94:95], v[90:93], off
	global_store_dwordx4 v[78:79], v[74:77], off
	global_store_dwordx4 v[78:79], v[70:73], off offset:256
	global_store_dwordx4 v[58:59], v[62:65], off
	global_store_dwordx4 v[46:47], v[42:45], off
	global_store_dwordx4 v[30:31], v[26:29], off
	global_store_dwordx4 v[14:15], v[10:13], off
	global_store_dwordx4 v[14:15], v[6:9], off offset:256
	s_cbranch_vccz .LBB0_721
	v_readlane_b32 s0, v254, 12
	s_waitcnt vmcnt(0)
	v_readlane_b32 s1, v254, 13
	s_andn2_b64 vcc, exec, s[0:1]
	s_cbranch_vccnz .LBB0_728
	s_barrier

.LBB0_977:
	s_add_u32 s2, s70, 0xfffc0080
	s_addc_u32 s17, s71, -1
	s_add_i32 s26, 0, 0x10000
	v_add_u32_e32 v152, s26, v163
	ds_read_b128 v[130:133], v152
	ds_read_b128 v[134:137], v152 offset:1024
	ds_read_b128 v[148:151], v152 offset:2048
	ds_read_b128 v[152:155], v152 offset:3072
	s_cmp_eq_u32 s44, 12
	s_cselect_b32 s75, s41, s17
	s_cselect_b32 s74, s24, s2
	s_cselect_b32 s73, s25, vcc_hi
	s_cselect_b32 s72, s93, vcc_lo
	v_lshl_add_u64 v[160:161], s[70:71], 0, v[144:145]
	s_add_i32 m0, s58, 0xc000
	ds_read_b128 v[156:159], v165
	ds_read_b128 v[188:191], v165 offset:1024
	ds_read_b128 v[192:195], v165 offset:2048
	ds_read_b128 v[196:199], v165 offset:3072
	ds_read_b128 v[200:203], v165 offset:4096
	ds_read_b128 v[216:219], v165 offset:5120
	ds_read_b128 v[220:223], v165 offset:6144
	ds_read_b128 v[224:227], v165 offset:7168
	global_load_lds_dwordx4 v[160:161], off
	v_lshl_add_u64 v[160:161], s[70:71], 0, v[146:147]
	s_add_i32 m0, s58, 0xe000
	s_nop 0
	global_load_lds_dwordx4 v[160:161], off
	s_waitcnt lgkmcnt(8)
	s_barrier
	s_waitcnt lgkmcnt(12)
	s_waitcnt lgkmcnt(12)
	s_waitcnt lgkmcnt(7)
	v_mfma_f32_16x16x32_bf16 v[126:129], v[130:133], v[156:159], v[126:129]
	v_mfma_f32_16x16x32_bf16 v[122:125], v[148:151], v[156:159], v[122:125]
	s_waitcnt lgkmcnt(5)
	v_mfma_f32_16x16x32_bf16 v[110:113], v[130:133], v[192:195], v[110:113]
	v_mfma_f32_16x16x32_bf16 v[106:109], v[148:151], v[192:195], v[106:109]
	s_waitcnt lgkmcnt(3)
	v_mfma_f32_16x16x32_bf16 v[94:97], v[130:133], v[200:203], v[94:97]
	v_mfma_f32_16x16x32_bf16 v[90:93], v[148:151], v[200:203], v[90:93]
	s_waitcnt lgkmcnt(1)
	v_mfma_f32_16x16x32_bf16 v[78:81], v[130:133], v[220:223], v[78:81]
	v_mfma_f32_16x16x32_bf16 v[74:77], v[148:151], v[220:223], v[74:77]
	v_mfma_f32_16x16x32_bf16 v[126:129], v[134:137], v[188:191], v[126:129]
	v_mfma_f32_16x16x32_bf16 v[122:125], v[152:155], v[188:191], v[122:125]
	v_mfma_f32_16x16x32_bf16 v[110:113], v[134:137], v[196:199], v[110:113]
	v_mfma_f32_16x16x32_bf16 v[106:109], v[152:155], v[196:199], v[106:109]
	v_mfma_f32_16x16x32_bf16 v[94:97], v[134:137], v[216:219], v[94:97]
	v_mfma_f32_16x16x32_bf16 v[90:93], v[152:155], v[216:219], v[90:93]
	s_waitcnt lgkmcnt(0)
	v_mfma_f32_16x16x32_bf16 v[78:81], v[134:137], v[224:227], v[78:81]
	v_mfma_f32_16x16x32_bf16 v[74:77], v[152:155], v[224:227], v[74:77]
	s_barrier
	s_add_i32 s2, 0, 0x14000
	v_add_u32_e32 v160, s2, v163
	s_add_i32 s17, s26, s3
	ds_read_b128 v[228:231], v160
	ds_read_b128 v[232:235], v160 offset:1024
	ds_read_b128 v[236:239], v160 offset:2048
	ds_read_b128 v[240:243], v160 offset:3072
	v_lshl_add_u64 v[160:161], s[72:73], 0, v[0:1]
	s_mov_b32 m0, s17
	v_lshl_add_u64 v[204:205], s[72:73], 0, v[138:139]
	global_load_lds_dwordx4 v[160:161], off
	s_add_i32 m0, s17, 0x2000
	s_nop 0
	global_load_lds_dwordx4 v[204:205], off
	s_barrier
	s_waitcnt lgkmcnt(4)
	s_waitcnt lgkmcnt(4)
	s_waitcnt lgkmcnt(3)
	v_mfma_f32_16x16x32_bf16 v[118:121], v[228:231], v[156:159], v[118:121]
	s_waitcnt lgkmcnt(1)
	v_mfma_f32_16x16x32_bf16 v[114:117], v[236:239], v[156:159], v[114:117]
	v_mfma_f32_16x16x32_bf16 v[102:105], v[228:231], v[192:195], v[102:105]
	v_mfma_f32_16x16x32_bf16 v[98:101], v[236:239], v[192:195], v[98:101]
	v_mfma_f32_16x16x32_bf16 v[86:89], v[228:231], v[200:203], v[86:89]
	v_mfma_f32_16x16x32_bf16 v[82:85], v[236:239], v[200:203], v[82:85]
	v_mfma_f32_16x16x32_bf16 v[70:73], v[228:231], v[220:223], v[70:73]
	v_mfma_f32_16x16x32_bf16 v[66:69], v[236:239], v[220:223], v[66:69]
	v_mfma_f32_16x16x32_bf16 v[118:121], v[232:235], v[188:191], v[118:121]
	s_waitcnt lgkmcnt(0)
	v_mfma_f32_16x16x32_bf16 v[114:117], v[240:243], v[188:191], v[114:117]
	v_mfma_f32_16x16x32_bf16 v[102:105], v[232:235], v[196:199], v[102:105]
	v_mfma_f32_16x16x32_bf16 v[98:101], v[240:243], v[196:199], v[98:101]
	v_mfma_f32_16x16x32_bf16 v[86:89], v[232:235], v[216:219], v[86:89]
	v_mfma_f32_16x16x32_bf16 v[82:85], v[240:243], v[216:219], v[82:85]
	v_mfma_f32_16x16x32_bf16 v[70:73], v[232:235], v[224:227], v[70:73]
	v_mfma_f32_16x16x32_bf16 v[66:69], v[240:243], v[224:227], v[66:69]
	s_mov_b32 m0, s58
	v_lshl_add_u64 v[244:245], s[74:75], 0, v[142:143]
	s_barrier
	ds_read_b128 v[156:159], v165 offset:16384
	ds_read_b128 v[188:191], v165 offset:17408
	ds_read_b128 v[192:195], v165 offset:18432
	ds_read_b128 v[196:199], v165 offset:19456
	ds_read_b128 v[200:203], v165 offset:20480
	ds_read_b128 v[216:219], v165 offset:21504
	ds_read_b128 v[220:223], v165 offset:22528
	ds_read_b128 v[224:227], v165 offset:23552
	global_load_lds_dwordx4 v[244:245], off
	v_lshl_add_u64 v[246:247], s[74:75], 0, v[140:141]
	s_mov_b32 m0, s76
	s_nop 0
	global_load_lds_dwordx4 v[246:247], off
	s_barrier
	s_waitcnt lgkmcnt(8)
	s_waitcnt lgkmcnt(8)
	s_waitcnt lgkmcnt(7)
	v_mfma_f32_16x16x32_bf16 v[62:65], v[130:133], v[156:159], v[62:65]
	v_mfma_f32_16x16x32_bf16 v[58:61], v[148:151], v[156:159], v[58:61]
	s_waitcnt lgkmcnt(5)
	v_mfma_f32_16x16x32_bf16 v[46:49], v[130:133], v[192:195], v[46:49]
	v_mfma_f32_16x16x32_bf16 v[42:45], v[148:151], v[192:195], v[42:45]
	s_waitcnt lgkmcnt(3)
	v_mfma_f32_16x16x32_bf16 v[30:33], v[130:133], v[200:203], v[30:33]
	v_mfma_f32_16x16x32_bf16 v[26:29], v[148:151], v[200:203], v[26:29]
	s_waitcnt lgkmcnt(1)
	v_mfma_f32_16x16x32_bf16 v[14:17], v[130:133], v[220:223], v[14:17]
	v_mfma_f32_16x16x32_bf16 v[10:13], v[148:151], v[220:223], v[10:13]
	v_mfma_f32_16x16x32_bf16 v[62:65], v[134:137], v[188:191], v[62:65]
	v_mfma_f32_16x16x32_bf16 v[58:61], v[152:155], v[188:191], v[58:61]
	v_mfma_f32_16x16x32_bf16 v[46:49], v[134:137], v[196:199], v[46:49]
	v_mfma_f32_16x16x32_bf16 v[42:45], v[152:155], v[196:199], v[42:45]
	v_mfma_f32_16x16x32_bf16 v[30:33], v[134:137], v[216:219], v[30:33]
	v_mfma_f32_16x16x32_bf16 v[26:29], v[152:155], v[216:219], v[26:29]
	s_waitcnt lgkmcnt(0)
	v_mfma_f32_16x16x32_bf16 v[14:17], v[134:137], v[224:227], v[14:17]
	v_mfma_f32_16x16x32_bf16 v[10:13], v[152:155], v[224:227], v[10:13]
	s_barrier
	s_add_u32 s26, s72, 0x40000
	s_addc_u32 s27, s73, 0
	s_add_i32 s2, s2, s3
	v_lshl_add_u64 v[130:131], s[26:27], 0, v[0:1]
	s_mov_b32 m0, s2
	s_nop 0
	global_load_lds_dwordx4 v[130:131], off
	v_lshl_add_u64 v[130:131], s[26:27], 0, v[138:139]
	s_add_i32 m0, s2, 0x2000
	s_nop 0
	global_load_lds_dwordx4 v[130:131], off
	s_waitcnt vmcnt(6)
	s_barrier
	v_mfma_f32_16x16x32_bf16 v[54:57], v[228:231], v[156:159], v[54:57]
	v_mfma_f32_16x16x32_bf16 v[50:53], v[236:239], v[156:159], v[50:53]
	v_mfma_f32_16x16x32_bf16 v[38:41], v[228:231], v[192:195], v[38:41]
	v_mfma_f32_16x16x32_bf16 v[34:37], v[236:239], v[192:195], v[34:37]
	v_mfma_f32_16x16x32_bf16 v[22:25], v[228:231], v[200:203], v[22:25]
	v_mfma_f32_16x16x32_bf16 v[18:21], v[236:239], v[200:203], v[18:21]
	v_mfma_f32_16x16x32_bf16 v[6:9], v[228:231], v[220:223], v[6:9]
	v_mfma_f32_16x16x32_bf16 v[2:5], v[236:239], v[220:223], v[2:5]
	v_mfma_f32_16x16x32_bf16 v[54:57], v[232:235], v[188:191], v[54:57]
	v_mfma_f32_16x16x32_bf16 v[50:53], v[240:243], v[188:191], v[50:53]
	v_mfma_f32_16x16x32_bf16 v[38:41], v[232:235], v[196:199], v[38:41]
	v_mfma_f32_16x16x32_bf16 v[34:37], v[240:243], v[196:199], v[34:37]
	v_mfma_f32_16x16x32_bf16 v[22:25], v[232:235], v[216:219], v[22:25]
	v_mfma_f32_16x16x32_bf16 v[18:21], v[240:243], v[216:219], v[18:21]
	v_mfma_f32_16x16x32_bf16 v[6:9], v[232:235], v[224:227], v[6:9]
	v_mfma_f32_16x16x32_bf16 v[2:5], v[240:243], v[224:227], v[2:5]
	s_add_i32 s2, 0, 0x18000
	v_add_u32_e32 v152, s2, v163
	s_barrier
	ds_read_b128 v[130:133], v152
	ds_read_b128 v[134:137], v152 offset:1024
	ds_read_b128 v[148:151], v152 offset:2048
	ds_read_b128 v[152:155], v152 offset:3072
	s_add_u32 s26, s74, 0x40000
	s_addc_u32 s27, s75, 0
	s_mov_b32 m0, s77
	v_lshl_add_u64 v[228:229], s[26:27], 0, v[142:143]
	ds_read_b128 v[156:159], v165 offset:32768
	ds_read_b128 v[188:191], v165 offset:33792
	ds_read_b128 v[192:195], v165 offset:34816
	ds_read_b128 v[196:199], v165 offset:35840
	ds_read_b128 v[200:203], v165 offset:36864
	ds_read_b128 v[216:219], v165 offset:37888
	ds_read_b128 v[220:223], v165 offset:38912
	ds_read_b128 v[224:227], v165 offset:39936
	global_load_lds_dwordx4 v[228:229], off
	v_lshl_add_u64 v[228:229], s[26:27], 0, v[140:141]
	s_mov_b32 m0, s78
	s_nop 0
	global_load_lds_dwordx4 v[228:229], off
	s_waitcnt lgkmcnt(8)
	s_barrier
	s_waitcnt lgkmcnt(12)
	s_waitcnt lgkmcnt(12)
	s_waitcnt lgkmcnt(7)
	v_mfma_f32_16x16x32_bf16 v[126:129], v[130:133], v[156:159], v[126:129]
	v_mfma_f32_16x16x32_bf16 v[122:125], v[148:151], v[156:159], v[122:125]
	s_waitcnt lgkmcnt(5)
	v_mfma_f32_16x16x32_bf16 v[110:113], v[130:133], v[192:195], v[110:113]
	v_mfma_f32_16x16x32_bf16 v[106:109], v[148:151], v[192:195], v[106:109]
	s_waitcnt lgkmcnt(3)
	v_mfma_f32_16x16x32_bf16 v[94:97], v[130:133], v[200:203], v[94:97]
	v_mfma_f32_16x16x32_bf16 v[90:93], v[148:151], v[200:203], v[90:93]
	s_waitcnt lgkmcnt(1)
	v_mfma_f32_16x16x32_bf16 v[78:81], v[130:133], v[220:223], v[78:81]
	v_mfma_f32_16x16x32_bf16 v[74:77], v[148:151], v[220:223], v[74:77]
	v_mfma_f32_16x16x32_bf16 v[126:129], v[134:137], v[188:191], v[126:129]
	v_mfma_f32_16x16x32_bf16 v[122:125], v[152:155], v[188:191], v[122:125]
	v_mfma_f32_16x16x32_bf16 v[110:113], v[134:137], v[196:199], v[110:113]
	v_mfma_f32_16x16x32_bf16 v[106:109], v[152:155], v[196:199], v[106:109]
	v_mfma_f32_16x16x32_bf16 v[94:97], v[134:137], v[216:219], v[94:97]
	v_mfma_f32_16x16x32_bf16 v[90:93], v[152:155], v[216:219], v[90:93]
	s_waitcnt lgkmcnt(0)
	v_mfma_f32_16x16x32_bf16 v[78:81], v[134:137], v[224:227], v[78:81]
	v_mfma_f32_16x16x32_bf16 v[74:77], v[152:155], v[224:227], v[74:77]
	s_barrier
	s_add_i32 s17, 0, 0x1c000
	s_add_i32 s2, s2, s3
	v_add_u32_e32 v206, s17, v163
	v_lshl_add_u64 v[160:161], v[160:161], 0, s[28:29]
	s_mov_b32 m0, s2
	ds_read_b128 v[228:231], v206
	ds_read_b128 v[232:235], v206 offset:1024
	ds_read_b128 v[236:239], v206 offset:2048
	ds_read_b128 v[240:243], v206 offset:3072
	global_load_lds_dwordx4 v[160:161], off
	v_lshl_add_u64 v[160:161], v[204:205], 0, s[28:29]
	s_add_i32 m0, s2, 0x2000
	s_nop 0
	global_load_lds_dwordx4 v[160:161], off
	s_barrier
	s_waitcnt lgkmcnt(4)
	s_waitcnt lgkmcnt(4)
	s_waitcnt lgkmcnt(3)
	v_mfma_f32_16x16x32_bf16 v[118:121], v[228:231], v[156:159], v[118:121]
	s_waitcnt lgkmcnt(1)
	v_mfma_f32_16x16x32_bf16 v[114:117], v[236:239], v[156:159], v[114:117]
	v_mfma_f32_16x16x32_bf16 v[102:105], v[228:231], v[192:195], v[102:105]
	v_mfma_f32_16x16x32_bf16 v[98:101], v[236:239], v[192:195], v[98:101]
	v_mfma_f32_16x16x32_bf16 v[86:89], v[228:231], v[200:203], v[86:89]
	v_mfma_f32_16x16x32_bf16 v[82:85], v[236:239], v[200:203], v[82:85]
	v_mfma_f32_16x16x32_bf16 v[70:73], v[228:231], v[220:223], v[70:73]
	v_mfma_f32_16x16x32_bf16 v[66:69], v[236:239], v[220:223], v[66:69]
	v_mfma_f32_16x16x32_bf16 v[118:121], v[232:235], v[188:191], v[118:121]
	s_waitcnt lgkmcnt(0)
	v_mfma_f32_16x16x32_bf16 v[114:117], v[240:243], v[188:191], v[114:117]
	v_mfma_f32_16x16x32_bf16 v[102:105], v[232:235], v[196:199], v[102:105]
	v_mfma_f32_16x16x32_bf16 v[98:101], v[240:243], v[196:199], v[98:101]
	v_mfma_f32_16x16x32_bf16 v[86:89], v[232:235], v[216:219], v[86:89]
	v_mfma_f32_16x16x32_bf16 v[82:85], v[240:243], v[216:219], v[82:85]
	v_mfma_f32_16x16x32_bf16 v[70:73], v[232:235], v[224:227], v[70:73]
	v_mfma_f32_16x16x32_bf16 v[66:69], v[240:243], v[224:227], v[66:69]
	s_mov_b32 m0, s79
	v_lshl_add_u64 v[160:161], v[244:245], 0, s[28:29]
	s_barrier
	ds_read_b128 v[156:159], v165 offset:49152
	ds_read_b128 v[188:191], v165 offset:50176
	ds_read_b128 v[192:195], v165 offset:51200
	ds_read_b128 v[196:199], v165 offset:52224
	ds_read_b128 v[200:203], v165 offset:53248
	ds_read_b128 v[216:219], v165 offset:54272
	ds_read_b128 v[220:223], v165 offset:55296
	ds_read_b128 v[224:227], v165 offset:56320
	global_load_lds_dwordx4 v[160:161], off
	v_lshl_add_u64 v[160:161], v[246:247], 0, s[28:29]
	s_mov_b32 m0, s83
	s_nop 0
	global_load_lds_dwordx4 v[160:161], off
	s_barrier
	s_waitcnt lgkmcnt(8)
	s_waitcnt lgkmcnt(8)
	s_waitcnt lgkmcnt(7)
	v_mfma_f32_16x16x32_bf16 v[62:65], v[130:133], v[156:159], v[62:65]
	v_mfma_f32_16x16x32_bf16 v[58:61], v[148:151], v[156:159], v[58:61]
	s_waitcnt lgkmcnt(5)
	v_mfma_f32_16x16x32_bf16 v[46:49], v[130:133], v[192:195], v[46:49]
	v_mfma_f32_16x16x32_bf16 v[42:45], v[148:151], v[192:195], v[42:45]
	s_waitcnt lgkmcnt(3)
	v_mfma_f32_16x16x32_bf16 v[30:33], v[130:133], v[200:203], v[30:33]
	v_mfma_f32_16x16x32_bf16 v[26:29], v[148:151], v[200:203], v[26:29]
	s_waitcnt lgkmcnt(1)
	v_mfma_f32_16x16x32_bf16 v[14:17], v[130:133], v[220:223], v[14:17]
	v_mfma_f32_16x16x32_bf16 v[10:13], v[148:151], v[220:223], v[10:13]
	v_mfma_f32_16x16x32_bf16 v[62:65], v[134:137], v[188:191], v[62:65]
	v_mfma_f32_16x16x32_bf16 v[58:61], v[152:155], v[188:191], v[58:61]
	v_mfma_f32_16x16x32_bf16 v[46:49], v[134:137], v[196:199], v[46:49]
	v_mfma_f32_16x16x32_bf16 v[42:45], v[152:155], v[196:199], v[42:45]
	v_mfma_f32_16x16x32_bf16 v[30:33], v[134:137], v[216:219], v[30:33]
	v_mfma_f32_16x16x32_bf16 v[26:29], v[152:155], v[216:219], v[26:29]
	s_waitcnt lgkmcnt(0)
	v_mfma_f32_16x16x32_bf16 v[14:17], v[134:137], v[224:227], v[14:17]
	v_mfma_f32_16x16x32_bf16 v[10:13], v[152:155], v[224:227], v[10:13]
	s_barrier
	s_add_u32 s26, s72, 0x40080
	s_addc_u32 s27, s73, 0
	s_add_i32 s2, s17, s3
	v_lshl_add_u64 v[130:131], s[26:27], 0, v[0:1]
	s_mov_b32 m0, s2
	s_nop 0
	global_load_lds_dwordx4 v[130:131], off
	v_lshl_add_u64 v[130:131], s[26:27], 0, v[138:139]
	s_add_i32 m0, s2, 0x2000
	s_nop 0
	global_load_lds_dwordx4 v[130:131], off
	s_waitcnt vmcnt(6)
	s_barrier
	v_mfma_f32_16x16x32_bf16 v[54:57], v[228:231], v[156:159], v[54:57]
	v_mfma_f32_16x16x32_bf16 v[50:53], v[236:239], v[156:159], v[50:53]
	v_mfma_f32_16x16x32_bf16 v[38:41], v[228:231], v[192:195], v[38:41]
	v_mfma_f32_16x16x32_bf16 v[34:37], v[236:239], v[192:195], v[34:37]
	v_mfma_f32_16x16x32_bf16 v[22:25], v[228:231], v[200:203], v[22:25]
	v_mfma_f32_16x16x32_bf16 v[18:21], v[236:239], v[200:203], v[18:21]
	v_mfma_f32_16x16x32_bf16 v[6:9], v[228:231], v[220:223], v[6:9]
	v_mfma_f32_16x16x32_bf16 v[2:5], v[236:239], v[220:223], v[2:5]
	v_mfma_f32_16x16x32_bf16 v[54:57], v[232:235], v[188:191], v[54:57]
	v_mfma_f32_16x16x32_bf16 v[50:53], v[240:243], v[188:191], v[50:53]
	v_mfma_f32_16x16x32_bf16 v[38:41], v[232:235], v[196:199], v[38:41]
	v_mfma_f32_16x16x32_bf16 v[34:37], v[240:243], v[196:199], v[34:37]
	v_mfma_f32_16x16x32_bf16 v[22:25], v[232:235], v[216:219], v[22:25]
	v_mfma_f32_16x16x32_bf16 v[18:21], v[240:243], v[216:219], v[18:21]
	v_mfma_f32_16x16x32_bf16 v[6:9], v[232:235], v[224:227], v[6:9]
	v_mfma_f32_16x16x32_bf16 v[2:5], v[240:243], v[224:227], v[2:5]
	s_add_i32 s44, s44, 2
	s_add_u32 s70, s70, 0x100
	s_addc_u32 s71, s71, 0
	s_add_u32 vcc_lo, vcc_lo, 0x100
	s_addc_u32 vcc_hi, vcc_hi, 0
	s_cmp_gt_u32 s44, 13
	s_barrier
	s_cbranch_scc0 .LBB0_977
	v_lshl_add_u32 v152, s47, 8, v162
	v_lshl_or_b32 v130, s46, 8, v164
	v_ashrrev_i32_e32 v153, 31, v152
	v_lshlrev_b64 v[136:137], 11, v[152:153]
	v_ashrrev_i32_e32 v131, 31, v130
	v_lshl_add_u64 v[136:137], s[56:57], 0, v[136:137]
	v_lshlrev_b64 v[150:151], 1, v[130:131]
	v_mov_b64_e32 v[154:155], s[22:23]
	v_lshl_add_u64 v[156:157], v[136:137], 0, v[150:151]
	v_mad_i64_i32 v[136:137], s[24:25], v152, s48, v[154:155]
	v_lshl_add_u64 v[160:161], v[136:137], 0, s[94:95]
	v_lshl_add_u64 v[148:149], v[130:131], 2, s[54:55]
	v_lshl_add_u64 v[136:137], v[160:161], 0, v[150:151]
	global_load_dwordx4 v[132:135], v[148:149], off offset:16
	global_load_dwordx4 v[188:191], v[148:149], off
	global_load_dwordx4 v[192:195], v[156:157], off
	global_load_dwordx4 v[196:199], v[136:137], off
	s_and_b64 vcc, exec, s[6:7]
	s_mov_b32 s46, s92
	s_mov_b32 s47, s40
	s_mov_b64 s[72:73], s[68:69]
	s_mov_b64 s[70:71], s[42:43]
	v_readlane_b32 s93, v251, 60
	s_waitcnt vmcnt(0)
	v_add_f32_e32 v122, v122, v132
	v_add_f32_e32 v126, v126, v188
	v_add_f32_e32 v127, v127, v189
	v_lshlrev_b32_e32 v158, 16, v196
	v_mul_f32_e32 v131, 0xbfb8aa3b, v158
	v_exp_f32_e32 v131, v131
	v_and_b32_e32 v159, 0xffff0000, v196
	v_mul_f32_e32 v126, 0xbfb8aa3b, v126
	v_mul_f32_e32 v127, 0xbfb8aa3b, v127
	v_add_f32_e32 v131, 1.0, v131
	v_rcp_f32_e32 v188, v131
	v_mul_f32_e32 v131, 0xbfb8aa3b, v159
	v_exp_f32_e32 v126, v126
	v_exp_f32_e32 v127, v127
	v_exp_f32_e32 v131, v131
	v_lshlrev_b32_e32 v136, 16, v192
	v_add_f32_e32 v126, 1.0, v126
	v_add_f32_e32 v127, 1.0, v127
	v_add_f32_e32 v131, 1.0, v131
	v_rcp_f32_e32 v126, v126
	v_rcp_f32_e32 v127, v127
	v_rcp_f32_e32 v189, v131
	v_and_b32_e32 v137, 0xffff0000, v192
	v_add_f32_e32 v123, v123, v133
	v_pk_mul_f32 v[126:127], v[126:127], v[136:137]
	v_pk_mul_f32 v[136:137], v[188:189], v[158:159]
	v_mul_f32_e32 v122, 0xbfb8aa3b, v122
	v_pk_mul_f32 v[126:127], v[126:127], v[136:137]
	v_lshlrev_b32_e32 v136, 16, v198
	v_mul_f32_e32 v131, 0xbfb8aa3b, v136
	v_exp_f32_e32 v131, v131
	v_and_b32_e32 v137, 0xffff0000, v198
	v_mul_f32_e32 v123, 0xbfb8aa3b, v123
	v_exp_f32_e32 v122, v122
	v_add_f32_e32 v131, 1.0, v131
	v_rcp_f32_e32 v158, v131
	v_mul_f32_e32 v131, 0xbfb8aa3b, v137
	v_exp_f32_e32 v123, v123
	v_exp_f32_e32 v131, v131
	v_add_f32_e32 v122, 1.0, v122
	v_rcp_f32_e32 v122, v122
	v_add_f32_e32 v123, 1.0, v123
	v_add_f32_e32 v131, 1.0, v131
	v_rcp_f32_e32 v123, v123
	v_rcp_f32_e32 v159, v131
	v_lshlrev_b32_e32 v132, 16, v194
	v_and_b32_e32 v133, 0xffff0000, v194
	v_pk_mul_f32 v[122:123], v[122:123], v[132:133]
	v_pk_mul_f32 v[132:133], v[158:159], v[136:137]
	v_lshlrev_b32_e32 v136, 16, v197
	v_pk_mul_f32 v[132:133], v[122:123], v[132:133]
	v_add_f32_e32 v123, v124, v134
	v_mul_f32_e32 v123, 0xbfb8aa3b, v123
	v_exp_f32_e32 v123, v123
	v_add_f32_e32 v122, v128, v190
	v_mul_f32_e32 v122, 0xbfb8aa3b, v122
	v_exp_f32_e32 v122, v122
	v_add_f32_e32 v123, 1.0, v123
	v_rcp_f32_e32 v124, v123
	v_add_f32_e32 v123, v129, v191
	v_mul_f32_e32 v123, 0xbfb8aa3b, v123
	v_exp_f32_e32 v123, v123
	v_add_f32_e32 v122, 1.0, v122
	v_rcp_f32_e32 v122, v122
	v_lshlrev_b32_e32 v128, 16, v193
	v_add_f32_e32 v123, 1.0, v123
	v_rcp_f32_e32 v123, v123
	v_and_b32_e32 v129, 0xffff0000, v193
	v_and_b32_e32 v137, 0xffff0000, v197
	v_mul_f32_e32 v131, 0xbfb8aa3b, v136
	v_pk_mul_f32 v[122:123], v[122:123], v[128:129]
	v_mul_f32_e32 v128, 0xbfb8aa3b, v137
	v_exp_f32_e32 v131, v131
	v_exp_f32_e32 v128, v128
	v_lshlrev_b32_e32 v134, 16, v199
	v_add_f32_e32 v131, 1.0, v131
	v_add_f32_e32 v128, 1.0, v128
	v_rcp_f32_e32 v158, v131
	v_rcp_f32_e32 v159, v128
	v_mul_f32_e32 v131, 0xbfb8aa3b, v134
	v_exp_f32_e32 v131, v131
	v_pk_mul_f32 v[128:129], v[158:159], v[136:137]
	s_nop 0
	v_pk_mul_f32 v[128:129], v[122:123], v[128:129]
	v_add_f32_e32 v122, v125, v135
	v_mul_f32_e32 v122, 0xbfb8aa3b, v122
	v_exp_f32_e32 v122, v122
	v_and_b32_e32 v123, 0xffff0000, v195
	v_and_b32_e32 v135, 0xffff0000, v199
	v_add_f32_e32 v131, 1.0, v131
	v_add_f32_e32 v122, 1.0, v122
	v_rcp_f32_e32 v125, v122
	v_lshlrev_b32_e32 v122, 16, v195
	v_rcp_f32_e32 v136, v131
	v_pk_mul_f32 v[122:123], v[124:125], v[122:123]
	v_mul_f32_e32 v124, 0xbfb8aa3b, v135
	v_exp_f32_e32 v124, v124
	s_nop 0
	v_add_f32_e32 v124, 1.0, v124
	v_rcp_f32_e32 v137, v124
	s_nop 0
	v_pk_mul_f32 v[124:125], v[136:137], v[134:135]
	s_nop 0
	v_pk_mul_f32 v[134:135], v[122:123], v[124:125]
	v_cvt_pk_bf16_f32 v122, v126, v127
	v_lshlrev_b64 v[126:127], 12, v[152:153]
	v_lshl_add_u64 v[126:127], s[36:37], 0, v[126:127]
	v_cvt_pk_bf16_f32 v123, v128, v129
	v_cvt_pk_bf16_f32 v124, v132, v133
	v_cvt_pk_bf16_f32 v125, v134, v135
	v_lshl_add_u64 v[158:159], v[126:127], 0, v[150:151]
	v_or_b32_e32 v126, 0x80, v130
	global_store_dwordx4 v[158:159], v[122:125], off offset:2048
	v_ashrrev_i32_e32 v127, 31, v126
	global_load_dwordx4 v[130:133], v[148:149], off offset:528
	global_load_dwordx4 v[134:137], v[148:149], off offset:512
	global_load_dwordx4 v[122:125], v[156:157], off offset:256
	v_lshlrev_b64 v[156:157], 1, v[126:127]
	v_lshl_add_u64 v[126:127], v[160:161], 0, v[156:157]
	global_load_dwordx4 v[126:129], v[126:127], off
	s_waitcnt vmcnt(0)
	v_add_f32_e32 v114, v114, v130
	v_add_f32_e32 v118, v118, v134
	v_add_f32_e32 v119, v119, v135
	v_lshlrev_b32_e32 v134, 16, v122
	v_and_b32_e32 v135, 0xffff0000, v122
	v_lshlrev_b32_e32 v160, 16, v126
	v_mul_f32_e32 v122, 0xbfb8aa3b, v160
	v_exp_f32_e32 v122, v122
	v_and_b32_e32 v161, 0xffff0000, v126
	v_mul_f32_e32 v118, 0xbfb8aa3b, v118
	v_mul_f32_e32 v119, 0xbfb8aa3b, v119
	v_add_f32_e32 v122, 1.0, v122
	v_rcp_f32_e32 v188, v122
	v_mul_f32_e32 v122, 0xbfb8aa3b, v161
	v_exp_f32_e32 v118, v118
	v_exp_f32_e32 v119, v119
	v_exp_f32_e32 v122, v122
	v_add_f32_e32 v120, v120, v136
	v_add_f32_e32 v118, 1.0, v118
	v_add_f32_e32 v119, 1.0, v119
	v_add_f32_e32 v122, 1.0, v122
	v_rcp_f32_e32 v118, v118
	v_rcp_f32_e32 v119, v119
	v_rcp_f32_e32 v189, v122
	v_add_f32_e32 v121, v121, v137
	v_mul_f32_e32 v120, 0xbfb8aa3b, v120
	v_pk_mul_f32 v[118:119], v[118:119], v[134:135]
	v_pk_mul_f32 v[134:135], v[188:189], v[160:161]
	v_mul_f32_e32 v121, 0xbfb8aa3b, v121
	v_pk_mul_f32 v[118:119], v[118:119], v[134:135]
	v_lshlrev_b32_e32 v134, 16, v128
	v_mul_f32_e32 v122, 0xbfb8aa3b, v134
	v_exp_f32_e32 v122, v122
	v_exp_f32_e32 v120, v120
	v_exp_f32_e32 v121, v121
	v_and_b32_e32 v135, 0xffff0000, v128
	v_add_f32_e32 v122, 1.0, v122
	v_rcp_f32_e32 v160, v122
	v_mul_f32_e32 v122, 0xbfb8aa3b, v135
	v_add_f32_e32 v115, v115, v131
	v_exp_f32_e32 v122, v122
	v_mul_f32_e32 v114, 0xbfb8aa3b, v114
	v_mul_f32_e32 v115, 0xbfb8aa3b, v115
	v_add_f32_e32 v120, 1.0, v120
	v_add_f32_e32 v121, 1.0, v121
	v_exp_f32_e32 v114, v114
	v_exp_f32_e32 v115, v115
	v_rcp_f32_e32 v120, v120
	v_rcp_f32_e32 v121, v121
	v_add_f32_e32 v122, 1.0, v122
	v_rcp_f32_e32 v161, v122
	v_lshlrev_b32_e32 v122, 16, v123
	v_and_b32_e32 v123, 0xffff0000, v123
	v_lshlrev_b32_e32 v126, 16, v127
	v_and_b32_e32 v127, 0xffff0000, v127
	v_add_f32_e32 v114, 1.0, v114
	v_add_f32_e32 v115, 1.0, v115
	v_lshlrev_b32_e32 v130, 16, v124
	v_and_b32_e32 v131, 0xffff0000, v124
	v_mul_f32_e32 v124, 0xbfb8aa3b, v126
	v_pk_mul_f32 v[120:121], v[120:121], v[122:123]
	v_mul_f32_e32 v122, 0xbfb8aa3b, v127
	v_rcp_f32_e32 v114, v114
	v_rcp_f32_e32 v115, v115
	v_add_f32_e32 v116, v116, v132
	v_exp_f32_e32 v124, v124
	v_exp_f32_e32 v122, v122
	v_add_f32_e32 v117, v117, v133
	v_mul_f32_e32 v116, 0xbfb8aa3b, v116
	v_mul_f32_e32 v117, 0xbfb8aa3b, v117
	v_exp_f32_e32 v116, v116
	v_exp_f32_e32 v117, v117
	v_pk_mul_f32 v[114:115], v[114:115], v[130:131]
	v_pk_mul_f32 v[130:131], v[160:161], v[134:135]
	v_add_f32_e32 v124, 1.0, v124
	v_add_f32_e32 v122, 1.0, v122
	v_pk_mul_f32 v[114:115], v[114:115], v[130:131]
	v_rcp_f32_e32 v130, v124
	v_rcp_f32_e32 v131, v122
	v_add_f32_e32 v116, 1.0, v116
	v_add_f32_e32 v117, 1.0, v117
	v_rcp_f32_e32 v116, v116
	v_rcp_f32_e32 v117, v117
	v_pk_mul_f32 v[122:123], v[130:131], v[126:127]
	v_lshlrev_b32_e32 v124, 16, v129
	v_pk_mul_f32 v[120:121], v[120:121], v[122:123]
	v_lshlrev_b32_e32 v122, 16, v125
	v_and_b32_e32 v123, 0xffff0000, v125
	v_and_b32_e32 v125, 0xffff0000, v129
	v_mul_f32_e32 v126, 0xbfb8aa3b, v124
	v_pk_mul_f32 v[116:117], v[116:117], v[122:123]
	v_mul_f32_e32 v122, 0xbfb8aa3b, v125
	v_exp_f32_e32 v126, v126
	v_exp_f32_e32 v122, v122
	v_or_b32_e32 v132, 16, v152
	v_ashrrev_i32_e32 v133, 31, v132
	v_add_f32_e32 v126, 1.0, v126
	v_add_f32_e32 v122, 1.0, v122
	v_rcp_f32_e32 v126, v126
	v_rcp_f32_e32 v127, v122
	s_nop 0
	v_pk_mul_f32 v[122:123], v[126:127], v[124:125]
	s_nop 0
	v_pk_mul_f32 v[122:123], v[116:117], v[122:123]
	v_cvt_pk_bf16_f32 v116, v118, v119
	v_cvt_pk_bf16_f32 v117, v120, v121
	v_cvt_pk_bf16_f32 v118, v114, v115
	v_cvt_pk_bf16_f32 v119, v122, v123
	global_store_dwordx4 v[158:159], v[116:119], off offset:2304
	global_load_dwordx4 v[114:117], v[148:149], off offset:16
	s_nop 0
	global_load_dwordx4 v[120:123], v[148:149], off
	v_lshlrev_b64 v[118:119], 11, v[132:133]
	v_lshl_add_u64 v[118:119], s[56:57], 0, v[118:119]
	v_lshl_add_u64 v[134:135], v[118:119], 0, v[150:151]
	v_mad_i64_i32 v[118:119], s[24:25], v132, s48, v[154:155]
	v_lshl_add_u64 v[118:119], v[118:119], 0, s[94:95]
	v_lshl_add_u64 v[128:129], v[118:119], 0, v[150:151]
	global_load_dwordx4 v[124:127], v[134:135], off
	v_lshl_add_u64 v[118:119], v[118:119], 0, v[156:157]
	global_load_dwordx4 v[128:131], v[128:129], off
	s_waitcnt vmcnt(0)
	v_add_f32_e32 v106, v106, v114
	v_add_f32_e32 v110, v110, v120
	v_add_f32_e32 v111, v111, v121
	v_mul_f32_e32 v110, 0xbfb8aa3b, v110
	v_mul_f32_e32 v111, 0xbfb8aa3b, v111
	v_exp_f32_e32 v110, v110
	v_exp_f32_e32 v111, v111
	v_add_f32_e32 v107, v107, v115
	v_mul_f32_e32 v106, 0xbfb8aa3b, v106
	v_mul_f32_e32 v107, 0xbfb8aa3b, v107
	v_exp_f32_e32 v106, v106
	v_lshlrev_b32_e32 v136, 16, v128
	v_mul_f32_e32 v114, 0xbfb8aa3b, v136
	v_exp_f32_e32 v114, v114
	v_and_b32_e32 v137, 0xffff0000, v128
	v_exp_f32_e32 v107, v107
	v_add_f32_e32 v110, 1.0, v110
	v_add_f32_e32 v114, 1.0, v114
	v_rcp_f32_e32 v158, v114
	v_mul_f32_e32 v114, 0xbfb8aa3b, v137
	v_exp_f32_e32 v114, v114
	v_add_f32_e32 v111, 1.0, v111
	v_rcp_f32_e32 v110, v110
	v_rcp_f32_e32 v111, v111
	v_add_f32_e32 v114, 1.0, v114
	v_rcp_f32_e32 v159, v114
	v_add_f32_e32 v106, 1.0, v106
	v_add_f32_e32 v107, 1.0, v107
	v_rcp_f32_e32 v106, v106
	v_rcp_f32_e32 v107, v107
	v_lshlrev_b32_e32 v120, 16, v124
	v_and_b32_e32 v121, 0xffff0000, v124
	v_pk_mul_f32 v[110:111], v[110:111], v[120:121]
	v_pk_mul_f32 v[120:121], v[158:159], v[136:137]
	v_lshlrev_b32_e32 v114, 16, v126
	v_pk_mul_f32 v[110:111], v[110:111], v[120:121]
	v_and_b32_e32 v115, 0xffff0000, v126
	v_lshlrev_b32_e32 v120, 16, v130
	v_and_b32_e32 v121, 0xffff0000, v130
	v_mul_f32_e32 v124, 0xbfb8aa3b, v120
	v_pk_mul_f32 v[106:107], v[106:107], v[114:115]
	v_mul_f32_e32 v114, 0xbfb8aa3b, v121
	v_exp_f32_e32 v124, v124
	v_exp_f32_e32 v114, v114
	v_add_f32_e32 v124, 1.0, v124
	v_add_f32_e32 v114, 1.0, v114
	v_rcp_f32_e32 v136, v124
	v_rcp_f32_e32 v137, v114
	s_nop 0
	v_pk_mul_f32 v[114:115], v[136:137], v[120:121]
	s_nop 0
	v_pk_mul_f32 v[114:115], v[106:107], v[114:115]
	v_add_f32_e32 v107, v108, v116
	v_mul_f32_e32 v107, 0xbfb8aa3b, v107
	v_exp_f32_e32 v107, v107
	v_add_f32_e32 v106, v112, v122
	v_mul_f32_e32 v106, 0xbfb8aa3b, v106
	v_exp_f32_e32 v106, v106
	v_add_f32_e32 v107, 1.0, v107
	v_rcp_f32_e32 v108, v107
	v_add_f32_e32 v107, v113, v123
	v_mul_f32_e32 v107, 0xbfb8aa3b, v107
	v_exp_f32_e32 v107, v107
	v_add_f32_e32 v106, 1.0, v106
	v_rcp_f32_e32 v106, v106
	v_lshlrev_b32_e32 v112, 16, v125
	v_add_f32_e32 v107, 1.0, v107
	v_rcp_f32_e32 v107, v107
	v_and_b32_e32 v113, 0xffff0000, v125
	v_lshlrev_b32_e32 v120, 16, v129
	v_and_b32_e32 v121, 0xffff0000, v129
	v_mul_f32_e32 v116, 0xbfb8aa3b, v120
	v_pk_mul_f32 v[106:107], v[106:107], v[112:113]
	v_mul_f32_e32 v112, 0xbfb8aa3b, v121
	v_exp_f32_e32 v116, v116
	v_exp_f32_e32 v112, v112
	v_add_f32_e32 v116, 1.0, v116
	v_add_f32_e32 v112, 1.0, v112
	v_rcp_f32_e32 v122, v116
	v_rcp_f32_e32 v123, v112
	v_lshlrev_b32_e32 v116, 16, v131
	v_pk_mul_f32 v[112:113], v[122:123], v[120:121]
	s_nop 0
	v_pk_mul_f32 v[112:113], v[106:107], v[112:113]
	v_add_f32_e32 v106, v109, v117
	v_mul_f32_e32 v106, 0xbfb8aa3b, v106
	v_exp_f32_e32 v106, v106
	v_and_b32_e32 v107, 0xffff0000, v127
	v_and_b32_e32 v117, 0xffff0000, v131
	v_mul_f32_e32 v120, 0xbfb8aa3b, v116
	v_add_f32_e32 v106, 1.0, v106
	v_rcp_f32_e32 v109, v106
	v_lshlrev_b32_e32 v106, 16, v127
	v_exp_f32_e32 v120, v120
	v_pk_mul_f32 v[106:107], v[108:109], v[106:107]
	v_mul_f32_e32 v108, 0xbfb8aa3b, v117
	v_exp_f32_e32 v108, v108
	v_add_f32_e32 v120, 1.0, v120
	v_rcp_f32_e32 v120, v120
	v_add_f32_e32 v108, 1.0, v108
	v_rcp_f32_e32 v121, v108
	s_nop 0
	v_pk_mul_f32 v[108:109], v[120:121], v[116:117]
	s_nop 0
	v_pk_mul_f32 v[116:117], v[106:107], v[108:109]
	v_cvt_pk_bf16_f32 v106, v110, v111
	v_lshlrev_b64 v[110:111], 12, v[132:133]
	v_lshl_add_u64 v[110:111], s[36:37], 0, v[110:111]
	v_cvt_pk_bf16_f32 v107, v112, v113
	v_cvt_pk_bf16_f32 v108, v114, v115
	v_cvt_pk_bf16_f32 v109, v116, v117
	v_lshl_add_u64 v[122:123], v[110:111], 0, v[150:151]
	global_store_dwordx4 v[122:123], v[106:109], off offset:2048
	global_load_dwordx4 v[110:113], v[148:149], off offset:528
	global_load_dwordx4 v[114:117], v[148:149], off offset:512
	s_nop 0
	global_load_dwordx4 v[106:109], v[134:135], off offset:256
	s_waitcnt vmcnt(0)
	v_add_f32_e32 v98, v98, v110
	global_load_dwordx4 v[118:121], v[118:119], off
	v_add_f32_e32 v102, v102, v114
	v_add_f32_e32 v103, v103, v115
	v_lshlrev_b32_e32 v114, 16, v106
	v_and_b32_e32 v115, 0xffff0000, v106
	v_mul_f32_e32 v102, 0xbfb8aa3b, v102
	v_mul_f32_e32 v103, 0xbfb8aa3b, v103
	v_exp_f32_e32 v102, v102
	v_exp_f32_e32 v103, v103
	v_add_f32_e32 v99, v99, v111
	v_mul_f32_e32 v98, 0xbfb8aa3b, v98
	v_add_f32_e32 v102, 1.0, v102
	v_add_f32_e32 v103, 1.0, v103
	v_rcp_f32_e32 v102, v102
	v_rcp_f32_e32 v103, v103
	v_mul_f32_e32 v99, 0xbfb8aa3b, v99
	v_exp_f32_e32 v98, v98
	v_exp_f32_e32 v99, v99
	v_pk_mul_f32 v[102:103], v[102:103], v[114:115]
	v_lshlrev_b32_e32 v110, 16, v108
	v_add_f32_e32 v98, 1.0, v98
	v_add_f32_e32 v99, 1.0, v99
	v_rcp_f32_e32 v98, v98
	v_rcp_f32_e32 v99, v99
	v_and_b32_e32 v111, 0xffff0000, v108
	v_pk_mul_f32 v[98:99], v[98:99], v[110:111]
	s_waitcnt vmcnt(0)
	v_lshlrev_b32_e32 v124, 16, v118
	v_mul_f32_e32 v106, 0xbfb8aa3b, v124
	v_exp_f32_e32 v106, v106
	v_and_b32_e32 v125, 0xffff0000, v118
	v_or_b32_e32 v118, 32, v152
	v_add_f32_e32 v106, 1.0, v106
	v_rcp_f32_e32 v126, v106
	v_mul_f32_e32 v106, 0xbfb8aa3b, v125
	v_exp_f32_e32 v106, v106
	s_nop 0
	v_add_f32_e32 v106, 1.0, v106
	v_rcp_f32_e32 v127, v106
	s_nop 0
	v_pk_mul_f32 v[114:115], v[126:127], v[124:125]
	s_nop 0
	v_pk_mul_f32 v[102:103], v[102:103], v[114:115]
	v_lshlrev_b32_e32 v114, 16, v120
	v_mul_f32_e32 v106, 0xbfb8aa3b, v114
	v_exp_f32_e32 v106, v106
	v_and_b32_e32 v115, 0xffff0000, v120
	v_add_f32_e32 v106, 1.0, v106
	v_rcp_f32_e32 v124, v106
	v_mul_f32_e32 v106, 0xbfb8aa3b, v115
	v_exp_f32_e32 v106, v106
	s_nop 0
	v_add_f32_e32 v106, 1.0, v106
	v_rcp_f32_e32 v125, v106
	v_lshlrev_b32_e32 v106, 16, v119
	v_mul_f32_e32 v108, 0xbfb8aa3b, v106
	v_exp_f32_e32 v108, v108
	v_pk_mul_f32 v[110:111], v[124:125], v[114:115]
	v_add_f32_e32 v108, 1.0, v108
	v_pk_mul_f32 v[110:111], v[98:99], v[110:111]
	v_add_f32_e32 v99, v100, v112
	v_mul_f32_e32 v99, 0xbfb8aa3b, v99
	v_exp_f32_e32 v99, v99
	v_add_f32_e32 v98, v104, v116
	v_mul_f32_e32 v98, 0xbfb8aa3b, v98
	v_exp_f32_e32 v98, v98
	v_add_f32_e32 v99, 1.0, v99
	v_rcp_f32_e32 v100, v99
	v_add_f32_e32 v99, v105, v117
	v_mul_f32_e32 v99, 0xbfb8aa3b, v99
	v_exp_f32_e32 v99, v99
	v_add_f32_e32 v98, 1.0, v98
	v_rcp_f32_e32 v98, v98
	v_lshlrev_b32_e32 v104, 16, v107
	v_add_f32_e32 v99, 1.0, v99
	v_rcp_f32_e32 v99, v99
	v_and_b32_e32 v105, 0xffff0000, v107
	v_and_b32_e32 v107, 0xffff0000, v119
	v_rcp_f32_e32 v114, v108
	v_pk_mul_f32 v[98:99], v[98:99], v[104:105]
	v_mul_f32_e32 v104, 0xbfb8aa3b, v107
	v_exp_f32_e32 v104, v104
	v_ashrrev_i32_e32 v119, 31, v118
	v_add_f32_e32 v104, 1.0, v104
	v_rcp_f32_e32 v115, v104
	s_nop 0
	v_pk_mul_f32 v[104:105], v[114:115], v[106:107]
	s_nop 0
	v_pk_mul_f32 v[104:105], v[98:99], v[104:105]
	v_add_f32_e32 v98, v101, v113
	v_mul_f32_e32 v98, 0xbfb8aa3b, v98
	v_exp_f32_e32 v98, v98
	v_and_b32_e32 v99, 0xffff0000, v109
	v_lshlrev_b32_e32 v106, 16, v121
	v_and_b32_e32 v107, 0xffff0000, v121
	v_add_f32_e32 v98, 1.0, v98
	v_rcp_f32_e32 v101, v98
	v_lshlrev_b32_e32 v98, 16, v109
	v_mul_f32_e32 v108, 0xbfb8aa3b, v106
	v_exp_f32_e32 v108, v108
	v_pk_mul_f32 v[98:99], v[100:101], v[98:99]
	v_mul_f32_e32 v100, 0xbfb8aa3b, v107
	v_exp_f32_e32 v100, v100
	v_add_f32_e32 v108, 1.0, v108
	v_rcp_f32_e32 v108, v108
	v_add_f32_e32 v100, 1.0, v100
	v_rcp_f32_e32 v109, v100
	s_nop 0
	v_pk_mul_f32 v[100:101], v[108:109], v[106:107]
	s_nop 0
	v_pk_mul_f32 v[106:107], v[98:99], v[100:101]
	v_cvt_pk_bf16_f32 v98, v102, v103
	v_cvt_pk_bf16_f32 v99, v104, v105
	v_cvt_pk_bf16_f32 v100, v110, v111
	v_cvt_pk_bf16_f32 v101, v106, v107
	global_store_dwordx4 v[122:123], v[98:101], off offset:2304
	global_load_dwordx4 v[102:105], v[148:149], off offset:16
	global_load_dwordx4 v[106:109], v[148:149], off
	v_lshlrev_b64 v[98:99], 11, v[118:119]
	v_lshl_add_u64 v[98:99], s[56:57], 0, v[98:99]
	v_lshl_add_u64 v[100:101], v[98:99], 0, v[150:151]
	v_mad_i64_i32 v[98:99], s[24:25], v118, s48, v[154:155]
	v_lshl_add_u64 v[98:99], v[98:99], 0, s[94:95]
	v_lshl_add_u64 v[114:115], v[98:99], 0, v[150:151]
	global_load_dwordx4 v[110:113], v[100:101], off
	v_lshl_add_u64 v[98:99], v[98:99], 0, v[156:157]
	global_load_dwordx4 v[114:117], v[114:115], off
	s_waitcnt vmcnt(0)
	v_add_f32_e32 v90, v90, v102
	v_add_f32_e32 v94, v94, v106
	v_add_f32_e32 v95, v95, v107
	v_mul_f32_e32 v94, 0xbfb8aa3b, v94
	v_mul_f32_e32 v95, 0xbfb8aa3b, v95
	v_exp_f32_e32 v94, v94
	v_exp_f32_e32 v95, v95
	v_add_f32_e32 v91, v91, v103
	v_mul_f32_e32 v90, 0xbfb8aa3b, v90
	v_mul_f32_e32 v91, 0xbfb8aa3b, v91
	v_exp_f32_e32 v90, v90
	v_lshlrev_b32_e32 v120, 16, v114
	v_mul_f32_e32 v102, 0xbfb8aa3b, v120
	v_exp_f32_e32 v102, v102
	v_and_b32_e32 v121, 0xffff0000, v114
	v_exp_f32_e32 v91, v91
	v_add_f32_e32 v94, 1.0, v94
	v_add_f32_e32 v102, 1.0, v102
	v_rcp_f32_e32 v122, v102
	v_mul_f32_e32 v102, 0xbfb8aa3b, v121
	v_exp_f32_e32 v102, v102
	v_add_f32_e32 v95, 1.0, v95
	v_rcp_f32_e32 v94, v94
	v_rcp_f32_e32 v95, v95
	v_add_f32_e32 v102, 1.0, v102
	v_rcp_f32_e32 v123, v102
	v_add_f32_e32 v90, 1.0, v90
	v_add_f32_e32 v91, 1.0, v91
	v_rcp_f32_e32 v90, v90
	v_rcp_f32_e32 v91, v91
	v_lshlrev_b32_e32 v106, 16, v110
	v_and_b32_e32 v107, 0xffff0000, v110
	v_pk_mul_f32 v[94:95], v[94:95], v[106:107]
	v_pk_mul_f32 v[106:107], v[122:123], v[120:121]
	v_lshlrev_b32_e32 v102, 16, v112
	v_pk_mul_f32 v[94:95], v[94:95], v[106:107]
	v_and_b32_e32 v103, 0xffff0000, v112
	v_lshlrev_b32_e32 v106, 16, v116
	v_and_b32_e32 v107, 0xffff0000, v116
	v_mul_f32_e32 v110, 0xbfb8aa3b, v106
	v_pk_mul_f32 v[90:91], v[90:91], v[102:103]
	v_mul_f32_e32 v102, 0xbfb8aa3b, v107
	v_exp_f32_e32 v110, v110
	v_exp_f32_e32 v102, v102
	v_add_f32_e32 v110, 1.0, v110
	v_add_f32_e32 v102, 1.0, v102
	v_rcp_f32_e32 v120, v110
	v_rcp_f32_e32 v121, v102
	s_nop 0
	v_pk_mul_f32 v[102:103], v[120:121], v[106:107]
	s_nop 0
	v_pk_mul_f32 v[102:103], v[90:91], v[102:103]
	v_add_f32_e32 v91, v92, v104
	v_mul_f32_e32 v91, 0xbfb8aa3b, v91
	v_exp_f32_e32 v91, v91
	v_add_f32_e32 v90, v96, v108
	v_mul_f32_e32 v90, 0xbfb8aa3b, v90
	v_exp_f32_e32 v90, v90
	v_add_f32_e32 v91, 1.0, v91
	v_rcp_f32_e32 v92, v91
	v_add_f32_e32 v91, v97, v109
	v_mul_f32_e32 v91, 0xbfb8aa3b, v91
	v_exp_f32_e32 v91, v91
	v_add_f32_e32 v90, 1.0, v90
	v_rcp_f32_e32 v90, v90
	v_lshlrev_b32_e32 v96, 16, v111
	v_add_f32_e32 v91, 1.0, v91
	v_rcp_f32_e32 v91, v91
	v_and_b32_e32 v97, 0xffff0000, v111
	v_lshlrev_b32_e32 v106, 16, v115
	v_and_b32_e32 v107, 0xffff0000, v115
	v_mul_f32_e32 v104, 0xbfb8aa3b, v106
	v_pk_mul_f32 v[90:91], v[90:91], v[96:97]
	v_mul_f32_e32 v96, 0xbfb8aa3b, v107
	v_exp_f32_e32 v104, v104
	v_exp_f32_e32 v96, v96
	v_add_f32_e32 v104, 1.0, v104
	v_add_f32_e32 v96, 1.0, v96
	v_rcp_f32_e32 v108, v104
	v_rcp_f32_e32 v109, v96
	v_lshlrev_b32_e32 v104, 16, v117
	v_pk_mul_f32 v[96:97], v[108:109], v[106:107]
	s_nop 0
	v_pk_mul_f32 v[96:97], v[90:91], v[96:97]
	v_add_f32_e32 v90, v93, v105
	v_mul_f32_e32 v90, 0xbfb8aa3b, v90
	v_exp_f32_e32 v90, v90
	v_and_b32_e32 v91, 0xffff0000, v113
	v_and_b32_e32 v105, 0xffff0000, v117
	v_mul_f32_e32 v106, 0xbfb8aa3b, v104
	v_add_f32_e32 v90, 1.0, v90
	v_rcp_f32_e32 v93, v90
	v_lshlrev_b32_e32 v90, 16, v113
	v_exp_f32_e32 v106, v106
	v_pk_mul_f32 v[90:91], v[92:93], v[90:91]
	v_mul_f32_e32 v92, 0xbfb8aa3b, v105
	v_exp_f32_e32 v92, v92
	v_add_f32_e32 v106, 1.0, v106
	v_rcp_f32_e32 v106, v106
	v_add_f32_e32 v92, 1.0, v92
	v_rcp_f32_e32 v107, v92
	s_nop 0
	v_pk_mul_f32 v[92:93], v[106:107], v[104:105]
	s_nop 0
	v_pk_mul_f32 v[104:105], v[90:91], v[92:93]
	v_cvt_pk_bf16_f32 v90, v94, v95
	v_lshlrev_b64 v[94:95], 12, v[118:119]
	v_lshl_add_u64 v[94:95], s[36:37], 0, v[94:95]
	v_cvt_pk_bf16_f32 v91, v96, v97
	v_cvt_pk_bf16_f32 v92, v102, v103
	v_cvt_pk_bf16_f32 v93, v104, v105
	v_lshl_add_u64 v[106:107], v[94:95], 0, v[150:151]
	global_store_dwordx4 v[106:107], v[90:93], off offset:2048
	global_load_dwordx4 v[90:93], v[148:149], off offset:528
	s_nop 0
	global_load_dwordx4 v[94:97], v[148:149], off offset:512
	global_load_dwordx4 v[102:105], v[100:101], off offset:256
	s_waitcnt vmcnt(0)
	v_add_f32_e32 v82, v82, v90
	global_load_dwordx4 v[98:101], v[98:99], off
	v_add_f32_e32 v86, v86, v94
	v_add_f32_e32 v87, v87, v95
	v_mul_f32_e32 v86, 0xbfb8aa3b, v86
	v_mul_f32_e32 v87, 0xbfb8aa3b, v87
	v_exp_f32_e32 v86, v86
	v_exp_f32_e32 v87, v87
	v_add_f32_e32 v83, v83, v91
	v_mul_f32_e32 v82, 0xbfb8aa3b, v82
	v_mul_f32_e32 v83, 0xbfb8aa3b, v83
	v_exp_f32_e32 v82, v82
	v_exp_f32_e32 v83, v83
	v_add_f32_e32 v86, 1.0, v86
	v_add_f32_e32 v87, 1.0, v87
	v_rcp_f32_e32 v86, v86
	v_rcp_f32_e32 v87, v87
	v_add_f32_e32 v82, 1.0, v82
	v_add_f32_e32 v83, 1.0, v83
	v_rcp_f32_e32 v82, v82
	v_rcp_f32_e32 v83, v83
	v_lshlrev_b32_e32 v94, 16, v102
	v_and_b32_e32 v95, 0xffff0000, v102
	v_pk_mul_f32 v[86:87], v[86:87], v[94:95]
	v_and_b32_e32 v91, 0xffff0000, v104
	v_or_b32_e32 v102, 48, v152
	s_waitcnt vmcnt(0)
	v_lshlrev_b32_e32 v108, 16, v98
	v_mul_f32_e32 v90, 0xbfb8aa3b, v108
	v_exp_f32_e32 v90, v90
	v_and_b32_e32 v109, 0xffff0000, v98
	v_add_f32_e32 v90, 1.0, v90
	v_rcp_f32_e32 v110, v90
	v_mul_f32_e32 v90, 0xbfb8aa3b, v109
	v_exp_f32_e32 v90, v90
	s_nop 0
	v_add_f32_e32 v90, 1.0, v90
	v_rcp_f32_e32 v111, v90
	v_lshlrev_b32_e32 v90, 16, v104
	v_pk_mul_f32 v[82:83], v[82:83], v[90:91]
	v_pk_mul_f32 v[94:95], v[110:111], v[108:109]
	s_nop 0
	v_pk_mul_f32 v[86:87], v[86:87], v[94:95]
	v_lshlrev_b32_e32 v94, 16, v100
	v_and_b32_e32 v95, 0xffff0000, v100
	v_mul_f32_e32 v98, 0xbfb8aa3b, v94
	v_mul_f32_e32 v90, 0xbfb8aa3b, v95
	v_exp_f32_e32 v98, v98
	v_exp_f32_e32 v90, v90
	v_add_f32_e32 v98, 1.0, v98
	v_add_f32_e32 v90, 1.0, v90
	v_rcp_f32_e32 v108, v98
	v_rcp_f32_e32 v109, v90
	s_nop 0
	v_pk_mul_f32 v[90:91], v[108:109], v[94:95]
	s_nop 0
	v_pk_mul_f32 v[90:91], v[82:83], v[90:91]
	v_add_f32_e32 v83, v84, v92
	v_mul_f32_e32 v83, 0xbfb8aa3b, v83
	v_exp_f32_e32 v83, v83
	v_add_f32_e32 v82, v88, v96
	v_mul_f32_e32 v82, 0xbfb8aa3b, v82
	v_exp_f32_e32 v82, v82
	v_add_f32_e32 v83, 1.0, v83
	v_rcp_f32_e32 v84, v83
	v_add_f32_e32 v83, v89, v97
	v_mul_f32_e32 v83, 0xbfb8aa3b, v83
	v_exp_f32_e32 v83, v83
	v_add_f32_e32 v82, 1.0, v82
	v_rcp_f32_e32 v82, v82
	v_lshlrev_b32_e32 v88, 16, v103
	v_add_f32_e32 v83, 1.0, v83
	v_rcp_f32_e32 v83, v83
	v_and_b32_e32 v89, 0xffff0000, v103
	v_lshlrev_b32_e32 v94, 16, v99
	v_and_b32_e32 v95, 0xffff0000, v99
	v_mul_f32_e32 v92, 0xbfb8aa3b, v94
	v_pk_mul_f32 v[82:83], v[82:83], v[88:89]
	v_mul_f32_e32 v88, 0xbfb8aa3b, v95
	v_exp_f32_e32 v92, v92
	v_exp_f32_e32 v88, v88
	v_ashrrev_i32_e32 v103, 31, v102
	v_add_f32_e32 v92, 1.0, v92
	v_add_f32_e32 v88, 1.0, v88
	v_rcp_f32_e32 v96, v92
	v_rcp_f32_e32 v97, v88
	v_lshlrev_b32_e32 v92, 16, v101
	v_pk_mul_f32 v[88:89], v[96:97], v[94:95]
	s_nop 0
	v_pk_mul_f32 v[88:89], v[82:83], v[88:89]
	v_add_f32_e32 v82, v85, v93
	v_mul_f32_e32 v82, 0xbfb8aa3b, v82
	v_exp_f32_e32 v82, v82
	v_and_b32_e32 v83, 0xffff0000, v105
	v_and_b32_e32 v93, 0xffff0000, v101
	v_mul_f32_e32 v94, 0xbfb8aa3b, v92
	v_add_f32_e32 v82, 1.0, v82
	v_rcp_f32_e32 v85, v82
	v_lshlrev_b32_e32 v82, 16, v105
	v_exp_f32_e32 v94, v94
	v_pk_mul_f32 v[82:83], v[84:85], v[82:83]
	v_mul_f32_e32 v84, 0xbfb8aa3b, v93
	v_exp_f32_e32 v84, v84
	v_add_f32_e32 v94, 1.0, v94
	v_rcp_f32_e32 v94, v94
	v_add_f32_e32 v84, 1.0, v84
	v_rcp_f32_e32 v95, v84
	s_nop 0
	v_pk_mul_f32 v[84:85], v[94:95], v[92:93]
	s_nop 0
	v_pk_mul_f32 v[92:93], v[82:83], v[84:85]
	v_cvt_pk_bf16_f32 v82, v86, v87
	v_cvt_pk_bf16_f32 v83, v88, v89
	v_cvt_pk_bf16_f32 v84, v90, v91
	v_cvt_pk_bf16_f32 v85, v92, v93
	global_store_dwordx4 v[106:107], v[82:85], off offset:2304
	global_load_dwordx4 v[86:89], v[148:149], off offset:16
	global_load_dwordx4 v[90:93], v[148:149], off
	v_lshlrev_b64 v[82:83], 11, v[102:103]
	v_lshl_add_u64 v[82:83], s[56:57], 0, v[82:83]
	v_lshl_add_u64 v[84:85], v[82:83], 0, v[150:151]
	v_mad_i64_i32 v[82:83], s[24:25], v102, s48, v[154:155]
	v_lshl_add_u64 v[82:83], v[82:83], 0, s[94:95]
	v_lshl_add_u64 v[98:99], v[82:83], 0, v[150:151]
	global_load_dwordx4 v[94:97], v[84:85], off
	v_lshl_add_u64 v[82:83], v[82:83], 0, v[156:157]
	global_load_dwordx4 v[98:101], v[98:99], off
	s_waitcnt vmcnt(0)
	v_add_f32_e32 v74, v74, v86
	v_add_f32_e32 v78, v78, v90
	v_add_f32_e32 v79, v79, v91
	v_mul_f32_e32 v78, 0xbfb8aa3b, v78
	v_mul_f32_e32 v79, 0xbfb8aa3b, v79
	v_exp_f32_e32 v78, v78
	v_exp_f32_e32 v79, v79
	v_add_f32_e32 v75, v75, v87
	v_mul_f32_e32 v74, 0xbfb8aa3b, v74
	v_mul_f32_e32 v75, 0xbfb8aa3b, v75
	v_exp_f32_e32 v74, v74
	v_lshlrev_b32_e32 v104, 16, v98
	v_mul_f32_e32 v86, 0xbfb8aa3b, v104
	v_exp_f32_e32 v86, v86
	v_and_b32_e32 v105, 0xffff0000, v98
	v_exp_f32_e32 v75, v75
	v_add_f32_e32 v78, 1.0, v78
	v_add_f32_e32 v86, 1.0, v86
	v_rcp_f32_e32 v106, v86
	v_mul_f32_e32 v86, 0xbfb8aa3b, v105
	v_exp_f32_e32 v86, v86
	v_add_f32_e32 v79, 1.0, v79
	v_rcp_f32_e32 v78, v78
	v_rcp_f32_e32 v79, v79
	v_add_f32_e32 v86, 1.0, v86
	v_rcp_f32_e32 v107, v86
	v_add_f32_e32 v74, 1.0, v74
	v_add_f32_e32 v75, 1.0, v75
	v_rcp_f32_e32 v74, v74
	v_rcp_f32_e32 v75, v75
	v_lshlrev_b32_e32 v90, 16, v94
	v_and_b32_e32 v91, 0xffff0000, v94
	v_pk_mul_f32 v[78:79], v[78:79], v[90:91]
	v_pk_mul_f32 v[90:91], v[106:107], v[104:105]
	v_lshlrev_b32_e32 v86, 16, v96
	v_pk_mul_f32 v[78:79], v[78:79], v[90:91]
	v_and_b32_e32 v87, 0xffff0000, v96
	v_lshlrev_b32_e32 v90, 16, v100
	v_and_b32_e32 v91, 0xffff0000, v100
	v_mul_f32_e32 v94, 0xbfb8aa3b, v90
	v_pk_mul_f32 v[74:75], v[74:75], v[86:87]
	v_mul_f32_e32 v86, 0xbfb8aa3b, v91
	v_exp_f32_e32 v94, v94
	v_exp_f32_e32 v86, v86
	v_add_f32_e32 v94, 1.0, v94
	v_add_f32_e32 v86, 1.0, v86
	v_rcp_f32_e32 v104, v94
	v_rcp_f32_e32 v105, v86
	s_nop 0
	v_pk_mul_f32 v[86:87], v[104:105], v[90:91]
	s_nop 0
	v_pk_mul_f32 v[86:87], v[74:75], v[86:87]
	v_add_f32_e32 v75, v76, v88
	v_mul_f32_e32 v75, 0xbfb8aa3b, v75
	v_exp_f32_e32 v75, v75
	v_add_f32_e32 v74, v80, v92
	v_mul_f32_e32 v74, 0xbfb8aa3b, v74
	v_exp_f32_e32 v74, v74
	v_add_f32_e32 v75, 1.0, v75
	v_rcp_f32_e32 v76, v75
	v_add_f32_e32 v75, v81, v93
	v_mul_f32_e32 v75, 0xbfb8aa3b, v75
	v_exp_f32_e32 v75, v75
	v_add_f32_e32 v74, 1.0, v74
	v_rcp_f32_e32 v74, v74
	v_lshlrev_b32_e32 v80, 16, v95
	v_add_f32_e32 v75, 1.0, v75
	v_rcp_f32_e32 v75, v75
	v_and_b32_e32 v81, 0xffff0000, v95
	v_lshlrev_b32_e32 v90, 16, v99
	v_and_b32_e32 v91, 0xffff0000, v99
	v_mul_f32_e32 v88, 0xbfb8aa3b, v90
	v_pk_mul_f32 v[74:75], v[74:75], v[80:81]
	v_mul_f32_e32 v80, 0xbfb8aa3b, v91
	v_exp_f32_e32 v88, v88
	v_exp_f32_e32 v80, v80
	v_add_f32_e32 v88, 1.0, v88
	v_add_f32_e32 v80, 1.0, v80
	v_rcp_f32_e32 v92, v88
	v_rcp_f32_e32 v93, v80
	v_lshlrev_b32_e32 v88, 16, v101
	v_pk_mul_f32 v[80:81], v[92:93], v[90:91]
	s_nop 0
	v_pk_mul_f32 v[80:81], v[74:75], v[80:81]
	v_add_f32_e32 v74, v77, v89
	v_mul_f32_e32 v74, 0xbfb8aa3b, v74
	v_exp_f32_e32 v74, v74
	v_and_b32_e32 v75, 0xffff0000, v97
	v_and_b32_e32 v89, 0xffff0000, v101
	v_mul_f32_e32 v90, 0xbfb8aa3b, v88
	v_add_f32_e32 v74, 1.0, v74
	v_rcp_f32_e32 v77, v74
	v_lshlrev_b32_e32 v74, 16, v97
	v_exp_f32_e32 v90, v90
	v_pk_mul_f32 v[74:75], v[76:77], v[74:75]
	v_mul_f32_e32 v76, 0xbfb8aa3b, v89
	v_exp_f32_e32 v76, v76
	v_add_f32_e32 v90, 1.0, v90
	v_rcp_f32_e32 v90, v90
	v_add_f32_e32 v76, 1.0, v76
	v_rcp_f32_e32 v91, v76
	s_nop 0
	v_pk_mul_f32 v[76:77], v[90:91], v[88:89]
	s_nop 0
	v_pk_mul_f32 v[88:89], v[74:75], v[76:77]
	v_cvt_pk_bf16_f32 v74, v78, v79
	v_lshlrev_b64 v[78:79], 12, v[102:103]
	v_lshl_add_u64 v[78:79], s[36:37], 0, v[78:79]
	v_cvt_pk_bf16_f32 v75, v80, v81
	v_cvt_pk_bf16_f32 v76, v86, v87
	v_cvt_pk_bf16_f32 v77, v88, v89
	v_lshl_add_u64 v[90:91], v[78:79], 0, v[150:151]
	global_store_dwordx4 v[90:91], v[74:77], off offset:2048
	global_load_dwordx4 v[74:77], v[148:149], off offset:528
	s_nop 0
	global_load_dwordx4 v[78:81], v[148:149], off offset:512
	global_load_dwordx4 v[86:89], v[84:85], off offset:256
	s_waitcnt vmcnt(0)
	v_add_f32_e32 v66, v66, v74
	global_load_dwordx4 v[82:85], v[82:83], off
	v_add_f32_e32 v70, v70, v78
	v_add_f32_e32 v71, v71, v79
	v_mul_f32_e32 v70, 0xbfb8aa3b, v70
	v_mul_f32_e32 v71, 0xbfb8aa3b, v71
	v_exp_f32_e32 v70, v70
	v_exp_f32_e32 v71, v71
	v_add_f32_e32 v67, v67, v75
	v_mul_f32_e32 v66, 0xbfb8aa3b, v66
	v_mul_f32_e32 v67, 0xbfb8aa3b, v67
	v_exp_f32_e32 v66, v66
	v_exp_f32_e32 v67, v67
	v_add_f32_e32 v70, 1.0, v70
	v_add_f32_e32 v71, 1.0, v71
	v_rcp_f32_e32 v70, v70
	v_rcp_f32_e32 v71, v71
	v_add_f32_e32 v66, 1.0, v66
	v_add_f32_e32 v67, 1.0, v67
	v_rcp_f32_e32 v66, v66
	v_rcp_f32_e32 v67, v67
	v_lshlrev_b32_e32 v78, 16, v86
	v_and_b32_e32 v79, 0xffff0000, v86
	v_pk_mul_f32 v[70:71], v[70:71], v[78:79]
	v_and_b32_e32 v75, 0xffff0000, v88
	v_add_u32_e32 v86, 0x80, v152
	s_waitcnt vmcnt(0)
	v_lshlrev_b32_e32 v92, 16, v82
	v_mul_f32_e32 v74, 0xbfb8aa3b, v92
	v_exp_f32_e32 v74, v74
	v_and_b32_e32 v93, 0xffff0000, v82
	v_add_f32_e32 v74, 1.0, v74
	v_rcp_f32_e32 v94, v74
	v_mul_f32_e32 v74, 0xbfb8aa3b, v93
	v_exp_f32_e32 v74, v74
	s_nop 0
	v_add_f32_e32 v74, 1.0, v74
	v_rcp_f32_e32 v95, v74
	v_lshlrev_b32_e32 v74, 16, v88
	v_pk_mul_f32 v[66:67], v[66:67], v[74:75]
	v_pk_mul_f32 v[78:79], v[94:95], v[92:93]
	s_nop 0
	v_pk_mul_f32 v[70:71], v[70:71], v[78:79]
	v_lshlrev_b32_e32 v78, 16, v84
	v_and_b32_e32 v79, 0xffff0000, v84
	v_mul_f32_e32 v82, 0xbfb8aa3b, v78
	v_mul_f32_e32 v74, 0xbfb8aa3b, v79
	v_exp_f32_e32 v82, v82
	v_exp_f32_e32 v74, v74
	v_add_f32_e32 v82, 1.0, v82
	v_add_f32_e32 v74, 1.0, v74
	v_rcp_f32_e32 v92, v82
	v_rcp_f32_e32 v93, v74
	s_nop 0
	v_pk_mul_f32 v[74:75], v[92:93], v[78:79]
	s_nop 0
	v_pk_mul_f32 v[74:75], v[66:67], v[74:75]
	v_add_f32_e32 v67, v68, v76
	v_mul_f32_e32 v67, 0xbfb8aa3b, v67
	v_exp_f32_e32 v67, v67
	v_add_f32_e32 v66, v72, v80
	v_mul_f32_e32 v66, 0xbfb8aa3b, v66
	v_exp_f32_e32 v66, v66
	v_add_f32_e32 v67, 1.0, v67
	v_rcp_f32_e32 v68, v67
	v_add_f32_e32 v67, v73, v81
	v_mul_f32_e32 v67, 0xbfb8aa3b, v67
	v_exp_f32_e32 v67, v67
	v_add_f32_e32 v66, 1.0, v66
	v_rcp_f32_e32 v66, v66
	v_lshlrev_b32_e32 v72, 16, v87
	v_add_f32_e32 v67, 1.0, v67
	v_rcp_f32_e32 v67, v67
	v_and_b32_e32 v73, 0xffff0000, v87
	v_lshlrev_b32_e32 v78, 16, v83
	v_and_b32_e32 v79, 0xffff0000, v83
	v_mul_f32_e32 v76, 0xbfb8aa3b, v78
	v_pk_mul_f32 v[66:67], v[66:67], v[72:73]
	v_mul_f32_e32 v72, 0xbfb8aa3b, v79
	v_exp_f32_e32 v76, v76
	v_exp_f32_e32 v72, v72
	v_ashrrev_i32_e32 v87, 31, v86
	v_add_f32_e32 v76, 1.0, v76
	v_add_f32_e32 v72, 1.0, v72
	v_rcp_f32_e32 v80, v76
	v_rcp_f32_e32 v81, v72
	v_lshlrev_b32_e32 v76, 16, v85
	v_pk_mul_f32 v[72:73], v[80:81], v[78:79]
	s_nop 0
	v_pk_mul_f32 v[72:73], v[66:67], v[72:73]
	v_add_f32_e32 v66, v69, v77
	v_mul_f32_e32 v66, 0xbfb8aa3b, v66
	v_exp_f32_e32 v66, v66
	v_and_b32_e32 v67, 0xffff0000, v89
	v_and_b32_e32 v77, 0xffff0000, v85
	v_mul_f32_e32 v78, 0xbfb8aa3b, v76
	v_add_f32_e32 v66, 1.0, v66
	v_rcp_f32_e32 v69, v66
	v_lshlrev_b32_e32 v66, 16, v89
	v_exp_f32_e32 v78, v78
	v_pk_mul_f32 v[66:67], v[68:69], v[66:67]
	v_mul_f32_e32 v68, 0xbfb8aa3b, v77
	v_exp_f32_e32 v68, v68
	v_add_f32_e32 v78, 1.0, v78
	v_rcp_f32_e32 v78, v78
	v_add_f32_e32 v68, 1.0, v68
	v_rcp_f32_e32 v79, v68
	s_nop 0
	v_pk_mul_f32 v[68:69], v[78:79], v[76:77]
	s_nop 0
	v_pk_mul_f32 v[76:77], v[66:67], v[68:69]
	v_cvt_pk_bf16_f32 v66, v70, v71
	v_cvt_pk_bf16_f32 v67, v72, v73
	v_cvt_pk_bf16_f32 v68, v74, v75
	v_cvt_pk_bf16_f32 v69, v76, v77
	global_store_dwordx4 v[90:91], v[66:69], off offset:2304
	global_load_dwordx4 v[70:73], v[148:149], off offset:16
	global_load_dwordx4 v[74:77], v[148:149], off
	v_lshlrev_b64 v[66:67], 11, v[86:87]
	v_lshl_add_u64 v[66:67], s[56:57], 0, v[66:67]
	v_lshl_add_u64 v[68:69], v[66:67], 0, v[150:151]
	v_mad_i64_i32 v[66:67], s[24:25], v86, s48, v[154:155]
	v_lshl_add_u64 v[66:67], v[66:67], 0, s[94:95]
	v_lshl_add_u64 v[82:83], v[66:67], 0, v[150:151]
	global_load_dwordx4 v[78:81], v[68:69], off
	v_lshl_add_u64 v[66:67], v[66:67], 0, v[156:157]
	global_load_dwordx4 v[82:85], v[82:83], off
	s_waitcnt vmcnt(0)
	v_add_f32_e32 v58, v58, v70
	v_add_f32_e32 v62, v62, v74
	v_add_f32_e32 v63, v63, v75
	v_mul_f32_e32 v62, 0xbfb8aa3b, v62
	v_mul_f32_e32 v63, 0xbfb8aa3b, v63
	v_exp_f32_e32 v62, v62
	v_exp_f32_e32 v63, v63
	v_add_f32_e32 v59, v59, v71
	v_mul_f32_e32 v58, 0xbfb8aa3b, v58
	v_mul_f32_e32 v59, 0xbfb8aa3b, v59
	v_exp_f32_e32 v58, v58
	v_lshlrev_b32_e32 v88, 16, v82
	v_mul_f32_e32 v70, 0xbfb8aa3b, v88
	v_exp_f32_e32 v70, v70
	v_and_b32_e32 v89, 0xffff0000, v82
	v_exp_f32_e32 v59, v59
	v_add_f32_e32 v62, 1.0, v62
	v_add_f32_e32 v70, 1.0, v70
	v_rcp_f32_e32 v90, v70
	v_mul_f32_e32 v70, 0xbfb8aa3b, v89
	v_exp_f32_e32 v70, v70
	v_add_f32_e32 v63, 1.0, v63
	v_rcp_f32_e32 v62, v62
	v_rcp_f32_e32 v63, v63
	v_add_f32_e32 v70, 1.0, v70
	v_rcp_f32_e32 v91, v70
	v_add_f32_e32 v58, 1.0, v58
	v_add_f32_e32 v59, 1.0, v59
	v_rcp_f32_e32 v58, v58
	v_rcp_f32_e32 v59, v59
	v_lshlrev_b32_e32 v74, 16, v78
	v_and_b32_e32 v75, 0xffff0000, v78
	v_pk_mul_f32 v[62:63], v[62:63], v[74:75]
	v_pk_mul_f32 v[74:75], v[90:91], v[88:89]
	v_lshlrev_b32_e32 v70, 16, v80
	v_pk_mul_f32 v[62:63], v[62:63], v[74:75]
	v_and_b32_e32 v71, 0xffff0000, v80
	v_lshlrev_b32_e32 v74, 16, v84
	v_and_b32_e32 v75, 0xffff0000, v84
	v_mul_f32_e32 v78, 0xbfb8aa3b, v74
	v_pk_mul_f32 v[58:59], v[58:59], v[70:71]
	v_mul_f32_e32 v70, 0xbfb8aa3b, v75
	v_exp_f32_e32 v78, v78
	v_exp_f32_e32 v70, v70
	v_add_f32_e32 v78, 1.0, v78
	v_add_f32_e32 v70, 1.0, v70
	v_rcp_f32_e32 v88, v78
	v_rcp_f32_e32 v89, v70
	s_nop 0
	v_pk_mul_f32 v[70:71], v[88:89], v[74:75]
	s_nop 0
	v_pk_mul_f32 v[70:71], v[58:59], v[70:71]
	v_add_f32_e32 v59, v60, v72
	v_mul_f32_e32 v59, 0xbfb8aa3b, v59
	v_exp_f32_e32 v59, v59
	v_add_f32_e32 v58, v64, v76
	v_mul_f32_e32 v58, 0xbfb8aa3b, v58
	v_exp_f32_e32 v58, v58
	v_add_f32_e32 v59, 1.0, v59
	v_rcp_f32_e32 v60, v59
	v_add_f32_e32 v59, v65, v77
	v_mul_f32_e32 v59, 0xbfb8aa3b, v59
	v_exp_f32_e32 v59, v59
	v_add_f32_e32 v58, 1.0, v58
	v_rcp_f32_e32 v58, v58
	v_lshlrev_b32_e32 v64, 16, v79
	v_add_f32_e32 v59, 1.0, v59
	v_rcp_f32_e32 v59, v59
	v_and_b32_e32 v65, 0xffff0000, v79
	v_lshlrev_b32_e32 v74, 16, v83
	v_and_b32_e32 v75, 0xffff0000, v83
	v_mul_f32_e32 v72, 0xbfb8aa3b, v74
	v_pk_mul_f32 v[58:59], v[58:59], v[64:65]
	v_mul_f32_e32 v64, 0xbfb8aa3b, v75
	v_exp_f32_e32 v72, v72
	v_exp_f32_e32 v64, v64
	v_add_f32_e32 v72, 1.0, v72
	v_add_f32_e32 v64, 1.0, v64
	v_rcp_f32_e32 v76, v72
	v_rcp_f32_e32 v77, v64
	v_lshlrev_b32_e32 v72, 16, v85
	v_pk_mul_f32 v[64:65], v[76:77], v[74:75]
	s_nop 0
	v_pk_mul_f32 v[64:65], v[58:59], v[64:65]
	v_add_f32_e32 v58, v61, v73
	v_mul_f32_e32 v58, 0xbfb8aa3b, v58
	v_exp_f32_e32 v58, v58
	v_and_b32_e32 v59, 0xffff0000, v81
	v_and_b32_e32 v73, 0xffff0000, v85
	v_mul_f32_e32 v74, 0xbfb8aa3b, v72
	v_add_f32_e32 v58, 1.0, v58
	v_rcp_f32_e32 v61, v58
	v_lshlrev_b32_e32 v58, 16, v81
	v_exp_f32_e32 v74, v74
	v_pk_mul_f32 v[58:59], v[60:61], v[58:59]
	v_mul_f32_e32 v60, 0xbfb8aa3b, v73
	v_exp_f32_e32 v60, v60
	v_add_f32_e32 v74, 1.0, v74
	v_rcp_f32_e32 v74, v74
	v_add_f32_e32 v60, 1.0, v60
	v_rcp_f32_e32 v75, v60
	s_nop 0
	v_pk_mul_f32 v[60:61], v[74:75], v[72:73]
	s_nop 0
	v_pk_mul_f32 v[72:73], v[58:59], v[60:61]
	v_cvt_pk_bf16_f32 v58, v62, v63
	v_lshlrev_b64 v[62:63], 12, v[86:87]
	v_lshl_add_u64 v[62:63], s[36:37], 0, v[62:63]
	v_cvt_pk_bf16_f32 v59, v64, v65
	v_cvt_pk_bf16_f32 v60, v70, v71
	v_cvt_pk_bf16_f32 v61, v72, v73
	v_lshl_add_u64 v[74:75], v[62:63], 0, v[150:151]
	global_store_dwordx4 v[74:75], v[58:61], off offset:2048
	global_load_dwordx4 v[58:61], v[148:149], off offset:528
	s_nop 0
	global_load_dwordx4 v[62:65], v[148:149], off offset:512
	global_load_dwordx4 v[70:73], v[68:69], off offset:256
	s_waitcnt vmcnt(0)
	v_add_f32_e32 v50, v50, v58
	global_load_dwordx4 v[66:69], v[66:67], off
	v_add_f32_e32 v54, v54, v62
	v_add_f32_e32 v55, v55, v63
	v_mul_f32_e32 v54, 0xbfb8aa3b, v54
	v_mul_f32_e32 v55, 0xbfb8aa3b, v55
	v_exp_f32_e32 v54, v54
	v_exp_f32_e32 v55, v55
	v_add_f32_e32 v51, v51, v59
	v_mul_f32_e32 v50, 0xbfb8aa3b, v50
	v_mul_f32_e32 v51, 0xbfb8aa3b, v51
	v_exp_f32_e32 v50, v50
	v_exp_f32_e32 v51, v51
	v_add_f32_e32 v54, 1.0, v54
	v_add_f32_e32 v55, 1.0, v55
	v_rcp_f32_e32 v54, v54
	v_rcp_f32_e32 v55, v55
	v_add_f32_e32 v50, 1.0, v50
	v_add_f32_e32 v51, 1.0, v51
	v_rcp_f32_e32 v50, v50
	v_rcp_f32_e32 v51, v51
	v_lshlrev_b32_e32 v62, 16, v70
	v_and_b32_e32 v63, 0xffff0000, v70
	v_pk_mul_f32 v[54:55], v[54:55], v[62:63]
	v_and_b32_e32 v59, 0xffff0000, v72
	v_add_u32_e32 v70, 0x90, v152
	s_waitcnt vmcnt(0)
	v_lshlrev_b32_e32 v76, 16, v66
	v_mul_f32_e32 v58, 0xbfb8aa3b, v76
	v_exp_f32_e32 v58, v58
	v_and_b32_e32 v77, 0xffff0000, v66
	v_add_f32_e32 v58, 1.0, v58
	v_rcp_f32_e32 v78, v58
	v_mul_f32_e32 v58, 0xbfb8aa3b, v77
	v_exp_f32_e32 v58, v58
	s_nop 0
	v_add_f32_e32 v58, 1.0, v58
	v_rcp_f32_e32 v79, v58
	v_lshlrev_b32_e32 v58, 16, v72
	v_pk_mul_f32 v[50:51], v[50:51], v[58:59]
	v_pk_mul_f32 v[62:63], v[78:79], v[76:77]
	s_nop 0
	v_pk_mul_f32 v[54:55], v[54:55], v[62:63]
	v_lshlrev_b32_e32 v62, 16, v68
	v_and_b32_e32 v63, 0xffff0000, v68
	v_mul_f32_e32 v66, 0xbfb8aa3b, v62
	v_mul_f32_e32 v58, 0xbfb8aa3b, v63
	v_exp_f32_e32 v66, v66
	v_exp_f32_e32 v58, v58
	v_add_f32_e32 v66, 1.0, v66
	v_add_f32_e32 v58, 1.0, v58
	v_rcp_f32_e32 v76, v66
	v_rcp_f32_e32 v77, v58
	s_nop 0
	v_pk_mul_f32 v[58:59], v[76:77], v[62:63]
	s_nop 0
	v_pk_mul_f32 v[58:59], v[50:51], v[58:59]
	v_add_f32_e32 v51, v52, v60
	v_mul_f32_e32 v51, 0xbfb8aa3b, v51
	v_exp_f32_e32 v51, v51
	v_add_f32_e32 v50, v56, v64
	v_mul_f32_e32 v50, 0xbfb8aa3b, v50
	v_exp_f32_e32 v50, v50
	v_add_f32_e32 v51, 1.0, v51
	v_rcp_f32_e32 v52, v51
	v_add_f32_e32 v51, v57, v65
	v_mul_f32_e32 v51, 0xbfb8aa3b, v51
	v_exp_f32_e32 v51, v51
	v_add_f32_e32 v50, 1.0, v50
	v_rcp_f32_e32 v50, v50
	v_lshlrev_b32_e32 v56, 16, v71
	v_add_f32_e32 v51, 1.0, v51
	v_rcp_f32_e32 v51, v51
	v_and_b32_e32 v57, 0xffff0000, v71
	v_lshlrev_b32_e32 v62, 16, v67
	v_and_b32_e32 v63, 0xffff0000, v67
	v_mul_f32_e32 v60, 0xbfb8aa3b, v62
	v_pk_mul_f32 v[50:51], v[50:51], v[56:57]
	v_mul_f32_e32 v56, 0xbfb8aa3b, v63
	v_exp_f32_e32 v60, v60
	v_exp_f32_e32 v56, v56
	v_ashrrev_i32_e32 v71, 31, v70
	v_add_f32_e32 v60, 1.0, v60
	v_add_f32_e32 v56, 1.0, v56
	v_rcp_f32_e32 v64, v60
	v_rcp_f32_e32 v65, v56
	v_lshlrev_b32_e32 v60, 16, v69
	v_pk_mul_f32 v[56:57], v[64:65], v[62:63]
	s_nop 0
	v_pk_mul_f32 v[56:57], v[50:51], v[56:57]
	v_add_f32_e32 v50, v53, v61
	v_mul_f32_e32 v50, 0xbfb8aa3b, v50
	v_exp_f32_e32 v50, v50
	v_and_b32_e32 v51, 0xffff0000, v73
	v_and_b32_e32 v61, 0xffff0000, v69
	v_mul_f32_e32 v62, 0xbfb8aa3b, v60
	v_add_f32_e32 v50, 1.0, v50
	v_rcp_f32_e32 v53, v50
	v_lshlrev_b32_e32 v50, 16, v73
	v_exp_f32_e32 v62, v62
	v_pk_mul_f32 v[50:51], v[52:53], v[50:51]
	v_mul_f32_e32 v52, 0xbfb8aa3b, v61
	v_exp_f32_e32 v52, v52
	v_add_f32_e32 v62, 1.0, v62
	v_rcp_f32_e32 v62, v62
	v_add_f32_e32 v52, 1.0, v52
	v_rcp_f32_e32 v63, v52
	s_nop 0
	v_pk_mul_f32 v[52:53], v[62:63], v[60:61]
	s_nop 0
	v_pk_mul_f32 v[60:61], v[50:51], v[52:53]
	v_cvt_pk_bf16_f32 v50, v54, v55
	v_cvt_pk_bf16_f32 v51, v56, v57
	v_cvt_pk_bf16_f32 v52, v58, v59
	v_cvt_pk_bf16_f32 v53, v60, v61
	global_store_dwordx4 v[74:75], v[50:53], off offset:2304
	global_load_dwordx4 v[54:57], v[148:149], off offset:16
	global_load_dwordx4 v[58:61], v[148:149], off
	v_lshlrev_b64 v[50:51], 11, v[70:71]
	v_lshl_add_u64 v[50:51], s[56:57], 0, v[50:51]
	v_lshl_add_u64 v[52:53], v[50:51], 0, v[150:151]
	v_mad_i64_i32 v[50:51], s[24:25], v70, s48, v[154:155]
	v_lshl_add_u64 v[50:51], v[50:51], 0, s[94:95]
	v_lshl_add_u64 v[66:67], v[50:51], 0, v[150:151]
	global_load_dwordx4 v[62:65], v[52:53], off
	v_lshl_add_u64 v[50:51], v[50:51], 0, v[156:157]
	global_load_dwordx4 v[66:69], v[66:67], off
	s_waitcnt vmcnt(0)
	v_add_f32_e32 v42, v42, v54
	v_add_f32_e32 v46, v46, v58
	v_add_f32_e32 v47, v47, v59
	v_mul_f32_e32 v46, 0xbfb8aa3b, v46
	v_mul_f32_e32 v47, 0xbfb8aa3b, v47
	v_exp_f32_e32 v46, v46
	v_exp_f32_e32 v47, v47
	v_add_f32_e32 v43, v43, v55
	v_mul_f32_e32 v42, 0xbfb8aa3b, v42
	v_mul_f32_e32 v43, 0xbfb8aa3b, v43
	v_exp_f32_e32 v42, v42
	v_lshlrev_b32_e32 v72, 16, v66
	v_mul_f32_e32 v54, 0xbfb8aa3b, v72
	v_exp_f32_e32 v54, v54
	v_and_b32_e32 v73, 0xffff0000, v66
	v_exp_f32_e32 v43, v43
	v_add_f32_e32 v46, 1.0, v46
	v_add_f32_e32 v54, 1.0, v54
	v_rcp_f32_e32 v74, v54
	v_mul_f32_e32 v54, 0xbfb8aa3b, v73
	v_exp_f32_e32 v54, v54
	v_add_f32_e32 v47, 1.0, v47
	v_rcp_f32_e32 v46, v46
	v_rcp_f32_e32 v47, v47
	v_add_f32_e32 v54, 1.0, v54
	v_rcp_f32_e32 v75, v54
	v_add_f32_e32 v42, 1.0, v42
	v_add_f32_e32 v43, 1.0, v43
	v_rcp_f32_e32 v42, v42
	v_rcp_f32_e32 v43, v43
	v_lshlrev_b32_e32 v58, 16, v62
	v_and_b32_e32 v59, 0xffff0000, v62
	v_pk_mul_f32 v[46:47], v[46:47], v[58:59]
	v_pk_mul_f32 v[58:59], v[74:75], v[72:73]
	v_lshlrev_b32_e32 v54, 16, v64
	v_pk_mul_f32 v[46:47], v[46:47], v[58:59]
	v_and_b32_e32 v55, 0xffff0000, v64
	v_lshlrev_b32_e32 v58, 16, v68
	v_and_b32_e32 v59, 0xffff0000, v68
	v_mul_f32_e32 v62, 0xbfb8aa3b, v58
	v_pk_mul_f32 v[42:43], v[42:43], v[54:55]
	v_mul_f32_e32 v54, 0xbfb8aa3b, v59
	v_exp_f32_e32 v62, v62
	v_exp_f32_e32 v54, v54
	v_add_f32_e32 v62, 1.0, v62
	v_add_f32_e32 v54, 1.0, v54
	v_rcp_f32_e32 v72, v62
	v_rcp_f32_e32 v73, v54
	s_nop 0
	v_pk_mul_f32 v[54:55], v[72:73], v[58:59]
	s_nop 0
	v_pk_mul_f32 v[54:55], v[42:43], v[54:55]
	v_add_f32_e32 v43, v44, v56
	v_mul_f32_e32 v43, 0xbfb8aa3b, v43
	v_exp_f32_e32 v43, v43
	v_add_f32_e32 v42, v48, v60
	v_mul_f32_e32 v42, 0xbfb8aa3b, v42
	v_exp_f32_e32 v42, v42
	v_add_f32_e32 v43, 1.0, v43
	v_rcp_f32_e32 v44, v43
	v_add_f32_e32 v43, v49, v61
	v_mul_f32_e32 v43, 0xbfb8aa3b, v43
	v_exp_f32_e32 v43, v43
	v_add_f32_e32 v42, 1.0, v42
	v_rcp_f32_e32 v42, v42
	v_lshlrev_b32_e32 v48, 16, v63
	v_add_f32_e32 v43, 1.0, v43
	v_rcp_f32_e32 v43, v43
	v_and_b32_e32 v49, 0xffff0000, v63
	v_lshlrev_b32_e32 v58, 16, v67
	v_and_b32_e32 v59, 0xffff0000, v67
	v_mul_f32_e32 v56, 0xbfb8aa3b, v58
	v_pk_mul_f32 v[42:43], v[42:43], v[48:49]
	v_mul_f32_e32 v48, 0xbfb8aa3b, v59
	v_exp_f32_e32 v56, v56
	v_exp_f32_e32 v48, v48
	v_add_f32_e32 v56, 1.0, v56
	v_add_f32_e32 v48, 1.0, v48
	v_rcp_f32_e32 v60, v56
	v_rcp_f32_e32 v61, v48
	v_lshlrev_b32_e32 v56, 16, v69
	v_pk_mul_f32 v[48:49], v[60:61], v[58:59]
	s_nop 0
	v_pk_mul_f32 v[48:49], v[42:43], v[48:49]
	v_add_f32_e32 v42, v45, v57
	v_mul_f32_e32 v42, 0xbfb8aa3b, v42
	v_exp_f32_e32 v42, v42
	v_and_b32_e32 v43, 0xffff0000, v65
	v_and_b32_e32 v57, 0xffff0000, v69
	v_mul_f32_e32 v58, 0xbfb8aa3b, v56
	v_add_f32_e32 v42, 1.0, v42
	v_rcp_f32_e32 v45, v42
	v_lshlrev_b32_e32 v42, 16, v65
	v_exp_f32_e32 v58, v58
	v_pk_mul_f32 v[42:43], v[44:45], v[42:43]
	v_mul_f32_e32 v44, 0xbfb8aa3b, v57
	v_exp_f32_e32 v44, v44
	v_add_f32_e32 v58, 1.0, v58
	v_rcp_f32_e32 v58, v58
	v_add_f32_e32 v44, 1.0, v44
	v_rcp_f32_e32 v59, v44
	s_nop 0
	v_pk_mul_f32 v[44:45], v[58:59], v[56:57]
	s_nop 0
	v_pk_mul_f32 v[56:57], v[42:43], v[44:45]
	v_cvt_pk_bf16_f32 v42, v46, v47
	v_lshlrev_b64 v[46:47], 12, v[70:71]
	v_lshl_add_u64 v[46:47], s[36:37], 0, v[46:47]
	v_cvt_pk_bf16_f32 v43, v48, v49
	v_cvt_pk_bf16_f32 v44, v54, v55
	v_cvt_pk_bf16_f32 v45, v56, v57
	v_lshl_add_u64 v[58:59], v[46:47], 0, v[150:151]
	global_store_dwordx4 v[58:59], v[42:45], off offset:2048
	global_load_dwordx4 v[42:45], v[148:149], off offset:528
	s_nop 0
	global_load_dwordx4 v[46:49], v[148:149], off offset:512
	global_load_dwordx4 v[54:57], v[52:53], off offset:256
	s_waitcnt vmcnt(0)
	v_add_f32_e32 v34, v34, v42
	global_load_dwordx4 v[50:53], v[50:51], off
	v_add_f32_e32 v38, v38, v46
	v_add_f32_e32 v39, v39, v47
	v_mul_f32_e32 v38, 0xbfb8aa3b, v38
	v_mul_f32_e32 v39, 0xbfb8aa3b, v39
	v_exp_f32_e32 v38, v38
	v_exp_f32_e32 v39, v39
	v_add_f32_e32 v35, v35, v43
	v_mul_f32_e32 v34, 0xbfb8aa3b, v34
	v_mul_f32_e32 v35, 0xbfb8aa3b, v35
	v_exp_f32_e32 v34, v34
	v_exp_f32_e32 v35, v35
	v_add_f32_e32 v38, 1.0, v38
	v_add_f32_e32 v39, 1.0, v39
	v_rcp_f32_e32 v38, v38
	v_rcp_f32_e32 v39, v39
	v_add_f32_e32 v34, 1.0, v34
	v_add_f32_e32 v35, 1.0, v35
	v_rcp_f32_e32 v34, v34
	v_rcp_f32_e32 v35, v35
	v_lshlrev_b32_e32 v46, 16, v54
	v_and_b32_e32 v47, 0xffff0000, v54
	v_pk_mul_f32 v[38:39], v[38:39], v[46:47]
	v_and_b32_e32 v43, 0xffff0000, v56
	v_add_u32_e32 v54, 0xa0, v152
	s_waitcnt vmcnt(0)
	v_lshlrev_b32_e32 v60, 16, v50
	v_mul_f32_e32 v42, 0xbfb8aa3b, v60
	v_exp_f32_e32 v42, v42
	v_and_b32_e32 v61, 0xffff0000, v50
	v_add_f32_e32 v42, 1.0, v42
	v_rcp_f32_e32 v62, v42
	v_mul_f32_e32 v42, 0xbfb8aa3b, v61
	v_exp_f32_e32 v42, v42
	s_nop 0
	v_add_f32_e32 v42, 1.0, v42
	v_rcp_f32_e32 v63, v42
	v_lshlrev_b32_e32 v42, 16, v56
	v_pk_mul_f32 v[34:35], v[34:35], v[42:43]
	v_pk_mul_f32 v[46:47], v[62:63], v[60:61]
	s_nop 0
	v_pk_mul_f32 v[38:39], v[38:39], v[46:47]
	v_lshlrev_b32_e32 v46, 16, v52
	v_and_b32_e32 v47, 0xffff0000, v52
	v_mul_f32_e32 v50, 0xbfb8aa3b, v46
	v_mul_f32_e32 v42, 0xbfb8aa3b, v47
	v_exp_f32_e32 v50, v50
	v_exp_f32_e32 v42, v42
	v_add_f32_e32 v50, 1.0, v50
	v_add_f32_e32 v42, 1.0, v42
	v_rcp_f32_e32 v60, v50
	v_rcp_f32_e32 v61, v42
	s_nop 0
	v_pk_mul_f32 v[42:43], v[60:61], v[46:47]
	s_nop 0
	v_pk_mul_f32 v[42:43], v[34:35], v[42:43]
	v_add_f32_e32 v35, v36, v44
	v_mul_f32_e32 v35, 0xbfb8aa3b, v35
	v_exp_f32_e32 v35, v35
	v_add_f32_e32 v34, v40, v48
	v_mul_f32_e32 v34, 0xbfb8aa3b, v34
	v_exp_f32_e32 v34, v34
	v_add_f32_e32 v35, 1.0, v35
	v_rcp_f32_e32 v36, v35
	v_add_f32_e32 v35, v41, v49
	v_mul_f32_e32 v35, 0xbfb8aa3b, v35
	v_exp_f32_e32 v35, v35
	v_add_f32_e32 v34, 1.0, v34
	v_rcp_f32_e32 v34, v34
	v_lshlrev_b32_e32 v40, 16, v55
	v_add_f32_e32 v35, 1.0, v35
	v_rcp_f32_e32 v35, v35
	v_and_b32_e32 v41, 0xffff0000, v55
	v_lshlrev_b32_e32 v46, 16, v51
	v_and_b32_e32 v47, 0xffff0000, v51
	v_mul_f32_e32 v44, 0xbfb8aa3b, v46
	v_pk_mul_f32 v[34:35], v[34:35], v[40:41]
	v_mul_f32_e32 v40, 0xbfb8aa3b, v47
	v_exp_f32_e32 v44, v44
	v_exp_f32_e32 v40, v40
	v_ashrrev_i32_e32 v55, 31, v54
	v_add_f32_e32 v44, 1.0, v44
	v_add_f32_e32 v40, 1.0, v40
	v_rcp_f32_e32 v48, v44
	v_rcp_f32_e32 v49, v40
	v_lshlrev_b32_e32 v44, 16, v53
	v_pk_mul_f32 v[40:41], v[48:49], v[46:47]
	s_nop 0
	v_pk_mul_f32 v[40:41], v[34:35], v[40:41]
	v_add_f32_e32 v34, v37, v45
	v_mul_f32_e32 v34, 0xbfb8aa3b, v34
	v_exp_f32_e32 v34, v34
	v_and_b32_e32 v35, 0xffff0000, v57
	v_and_b32_e32 v45, 0xffff0000, v53
	v_mul_f32_e32 v46, 0xbfb8aa3b, v44
	v_add_f32_e32 v34, 1.0, v34
	v_rcp_f32_e32 v37, v34
	v_lshlrev_b32_e32 v34, 16, v57
	v_exp_f32_e32 v46, v46
	v_pk_mul_f32 v[34:35], v[36:37], v[34:35]
	v_mul_f32_e32 v36, 0xbfb8aa3b, v45
	v_exp_f32_e32 v36, v36
	v_add_f32_e32 v46, 1.0, v46
	v_rcp_f32_e32 v46, v46
	v_add_f32_e32 v36, 1.0, v36
	v_rcp_f32_e32 v47, v36
	s_nop 0
	v_pk_mul_f32 v[36:37], v[46:47], v[44:45]
	s_nop 0
	v_pk_mul_f32 v[44:45], v[34:35], v[36:37]
	v_cvt_pk_bf16_f32 v34, v38, v39
	v_cvt_pk_bf16_f32 v35, v40, v41
	v_cvt_pk_bf16_f32 v36, v42, v43
	v_cvt_pk_bf16_f32 v37, v44, v45
	global_store_dwordx4 v[58:59], v[34:37], off offset:2304
	global_load_dwordx4 v[38:41], v[148:149], off offset:16
	global_load_dwordx4 v[42:45], v[148:149], off
	v_lshlrev_b64 v[34:35], 11, v[54:55]
	v_lshl_add_u64 v[34:35], s[56:57], 0, v[34:35]
	v_lshl_add_u64 v[36:37], v[34:35], 0, v[150:151]
	v_mad_i64_i32 v[34:35], s[24:25], v54, s48, v[154:155]
	v_lshl_add_u64 v[34:35], v[34:35], 0, s[94:95]
	v_lshl_add_u64 v[50:51], v[34:35], 0, v[150:151]
	global_load_dwordx4 v[46:49], v[36:37], off
	v_lshl_add_u64 v[34:35], v[34:35], 0, v[156:157]
	global_load_dwordx4 v[50:53], v[50:51], off
	s_waitcnt vmcnt(0)
	v_add_f32_e32 v26, v26, v38
	v_add_f32_e32 v30, v30, v42
	v_add_f32_e32 v31, v31, v43
	v_mul_f32_e32 v30, 0xbfb8aa3b, v30
	v_mul_f32_e32 v31, 0xbfb8aa3b, v31
	v_exp_f32_e32 v30, v30
	v_exp_f32_e32 v31, v31
	v_add_f32_e32 v27, v27, v39
	v_mul_f32_e32 v26, 0xbfb8aa3b, v26
	v_mul_f32_e32 v27, 0xbfb8aa3b, v27
	v_exp_f32_e32 v26, v26
	v_lshlrev_b32_e32 v56, 16, v50
	v_mul_f32_e32 v38, 0xbfb8aa3b, v56
	v_exp_f32_e32 v38, v38
	v_and_b32_e32 v57, 0xffff0000, v50
	v_exp_f32_e32 v27, v27
	v_add_f32_e32 v30, 1.0, v30
	v_add_f32_e32 v38, 1.0, v38
	v_rcp_f32_e32 v58, v38
	v_mul_f32_e32 v38, 0xbfb8aa3b, v57
	v_exp_f32_e32 v38, v38
	v_add_f32_e32 v31, 1.0, v31
	v_rcp_f32_e32 v30, v30
	v_rcp_f32_e32 v31, v31
	v_add_f32_e32 v38, 1.0, v38
	v_rcp_f32_e32 v59, v38
	v_add_f32_e32 v26, 1.0, v26
	v_add_f32_e32 v27, 1.0, v27
	v_rcp_f32_e32 v26, v26
	v_rcp_f32_e32 v27, v27
	v_lshlrev_b32_e32 v42, 16, v46
	v_and_b32_e32 v43, 0xffff0000, v46
	v_pk_mul_f32 v[30:31], v[30:31], v[42:43]
	v_pk_mul_f32 v[42:43], v[58:59], v[56:57]
	v_lshlrev_b32_e32 v38, 16, v48
	v_pk_mul_f32 v[30:31], v[30:31], v[42:43]
	v_and_b32_e32 v39, 0xffff0000, v48
	v_lshlrev_b32_e32 v42, 16, v52
	v_and_b32_e32 v43, 0xffff0000, v52
	v_mul_f32_e32 v46, 0xbfb8aa3b, v42
	v_pk_mul_f32 v[26:27], v[26:27], v[38:39]
	v_mul_f32_e32 v38, 0xbfb8aa3b, v43
	v_exp_f32_e32 v46, v46
	v_exp_f32_e32 v38, v38
	v_add_f32_e32 v46, 1.0, v46
	v_add_f32_e32 v38, 1.0, v38
	v_rcp_f32_e32 v56, v46
	v_rcp_f32_e32 v57, v38
	s_nop 0
	v_pk_mul_f32 v[38:39], v[56:57], v[42:43]
	s_nop 0
	v_pk_mul_f32 v[38:39], v[26:27], v[38:39]
	v_add_f32_e32 v27, v28, v40
	v_mul_f32_e32 v27, 0xbfb8aa3b, v27
	v_exp_f32_e32 v27, v27
	v_add_f32_e32 v26, v32, v44
	v_mul_f32_e32 v26, 0xbfb8aa3b, v26
	v_exp_f32_e32 v26, v26
	v_add_f32_e32 v27, 1.0, v27
	v_rcp_f32_e32 v28, v27
	v_add_f32_e32 v27, v33, v45
	v_mul_f32_e32 v27, 0xbfb8aa3b, v27
	v_exp_f32_e32 v27, v27
	v_add_f32_e32 v26, 1.0, v26
	v_rcp_f32_e32 v26, v26
	v_lshlrev_b32_e32 v32, 16, v47
	v_add_f32_e32 v27, 1.0, v27
	v_rcp_f32_e32 v27, v27
	v_and_b32_e32 v33, 0xffff0000, v47
	v_lshlrev_b32_e32 v42, 16, v51
	v_and_b32_e32 v43, 0xffff0000, v51
	v_mul_f32_e32 v40, 0xbfb8aa3b, v42
	v_pk_mul_f32 v[26:27], v[26:27], v[32:33]
	v_mul_f32_e32 v32, 0xbfb8aa3b, v43
	v_exp_f32_e32 v40, v40
	v_exp_f32_e32 v32, v32
	v_add_f32_e32 v40, 1.0, v40
	v_add_f32_e32 v32, 1.0, v32
	v_rcp_f32_e32 v44, v40
	v_rcp_f32_e32 v45, v32
	v_lshlrev_b32_e32 v40, 16, v53
	v_pk_mul_f32 v[32:33], v[44:45], v[42:43]
	s_nop 0
	v_pk_mul_f32 v[32:33], v[26:27], v[32:33]
	v_add_f32_e32 v26, v29, v41
	v_mul_f32_e32 v26, 0xbfb8aa3b, v26
	v_exp_f32_e32 v26, v26
	v_and_b32_e32 v27, 0xffff0000, v49
	v_and_b32_e32 v41, 0xffff0000, v53
	v_mul_f32_e32 v42, 0xbfb8aa3b, v40
	v_add_f32_e32 v26, 1.0, v26
	v_rcp_f32_e32 v29, v26
	v_lshlrev_b32_e32 v26, 16, v49
	v_exp_f32_e32 v42, v42
	v_pk_mul_f32 v[26:27], v[28:29], v[26:27]
	v_mul_f32_e32 v28, 0xbfb8aa3b, v41
	v_exp_f32_e32 v28, v28
	v_add_f32_e32 v42, 1.0, v42
	v_rcp_f32_e32 v42, v42
	v_add_f32_e32 v28, 1.0, v28
	v_rcp_f32_e32 v43, v28
	s_nop 0
	v_pk_mul_f32 v[28:29], v[42:43], v[40:41]
	s_nop 0
	v_pk_mul_f32 v[40:41], v[26:27], v[28:29]
	v_cvt_pk_bf16_f32 v26, v30, v31
	v_lshlrev_b64 v[30:31], 12, v[54:55]
	v_lshl_add_u64 v[30:31], s[36:37], 0, v[30:31]
	v_cvt_pk_bf16_f32 v27, v32, v33
	v_cvt_pk_bf16_f32 v28, v38, v39
	v_cvt_pk_bf16_f32 v29, v40, v41
	v_lshl_add_u64 v[42:43], v[30:31], 0, v[150:151]
	global_store_dwordx4 v[42:43], v[26:29], off offset:2048
	global_load_dwordx4 v[26:29], v[148:149], off offset:528
	s_nop 0
	global_load_dwordx4 v[30:33], v[148:149], off offset:512
	global_load_dwordx4 v[38:41], v[36:37], off offset:256
	s_waitcnt vmcnt(0)
	v_add_f32_e32 v18, v18, v26
	global_load_dwordx4 v[34:37], v[34:35], off
	v_add_f32_e32 v22, v22, v30
	v_add_f32_e32 v23, v23, v31
	v_mul_f32_e32 v22, 0xbfb8aa3b, v22
	v_mul_f32_e32 v23, 0xbfb8aa3b, v23
	v_exp_f32_e32 v22, v22
	v_exp_f32_e32 v23, v23
	v_add_f32_e32 v19, v19, v27
	v_mul_f32_e32 v18, 0xbfb8aa3b, v18
	v_mul_f32_e32 v19, 0xbfb8aa3b, v19
	v_exp_f32_e32 v18, v18
	v_exp_f32_e32 v19, v19
	v_add_f32_e32 v22, 1.0, v22
	v_add_f32_e32 v23, 1.0, v23
	v_rcp_f32_e32 v22, v22
	v_rcp_f32_e32 v23, v23
	v_add_f32_e32 v18, 1.0, v18
	v_add_f32_e32 v19, 1.0, v19
	v_rcp_f32_e32 v18, v18
	v_rcp_f32_e32 v19, v19
	v_lshlrev_b32_e32 v30, 16, v38
	v_and_b32_e32 v31, 0xffff0000, v38
	v_pk_mul_f32 v[22:23], v[22:23], v[30:31]
	v_and_b32_e32 v27, 0xffff0000, v40
	v_add_u32_e32 v38, 0xb0, v152
	s_waitcnt vmcnt(0)
	v_lshlrev_b32_e32 v44, 16, v34
	v_mul_f32_e32 v26, 0xbfb8aa3b, v44
	v_exp_f32_e32 v26, v26
	v_and_b32_e32 v45, 0xffff0000, v34
	v_add_f32_e32 v26, 1.0, v26
	v_rcp_f32_e32 v46, v26
	v_mul_f32_e32 v26, 0xbfb8aa3b, v45
	v_exp_f32_e32 v26, v26
	s_nop 0
	v_add_f32_e32 v26, 1.0, v26
	v_rcp_f32_e32 v47, v26
	v_lshlrev_b32_e32 v26, 16, v40
	v_pk_mul_f32 v[18:19], v[18:19], v[26:27]
	v_pk_mul_f32 v[30:31], v[46:47], v[44:45]
	s_nop 0
	v_pk_mul_f32 v[22:23], v[22:23], v[30:31]
	v_lshlrev_b32_e32 v30, 16, v36
	v_and_b32_e32 v31, 0xffff0000, v36
	v_mul_f32_e32 v34, 0xbfb8aa3b, v30
	v_mul_f32_e32 v26, 0xbfb8aa3b, v31
	v_exp_f32_e32 v34, v34
	v_exp_f32_e32 v26, v26
	v_add_f32_e32 v34, 1.0, v34
	v_add_f32_e32 v26, 1.0, v26
	v_rcp_f32_e32 v44, v34
	v_rcp_f32_e32 v45, v26
	s_nop 0
	v_pk_mul_f32 v[26:27], v[44:45], v[30:31]
	s_nop 0
	v_pk_mul_f32 v[26:27], v[18:19], v[26:27]
	v_add_f32_e32 v19, v20, v28
	v_mul_f32_e32 v19, 0xbfb8aa3b, v19
	v_exp_f32_e32 v19, v19
	v_add_f32_e32 v18, v24, v32
	v_mul_f32_e32 v18, 0xbfb8aa3b, v18
	v_exp_f32_e32 v18, v18
	v_add_f32_e32 v19, 1.0, v19
	v_rcp_f32_e32 v20, v19
	v_add_f32_e32 v19, v25, v33
	v_mul_f32_e32 v19, 0xbfb8aa3b, v19
	v_exp_f32_e32 v19, v19
	v_add_f32_e32 v18, 1.0, v18
	v_rcp_f32_e32 v18, v18
	v_lshlrev_b32_e32 v24, 16, v39
	v_add_f32_e32 v19, 1.0, v19
	v_rcp_f32_e32 v19, v19
	v_and_b32_e32 v25, 0xffff0000, v39
	v_lshlrev_b32_e32 v30, 16, v35
	v_and_b32_e32 v31, 0xffff0000, v35
	v_mul_f32_e32 v28, 0xbfb8aa3b, v30
	v_pk_mul_f32 v[18:19], v[18:19], v[24:25]
	v_mul_f32_e32 v24, 0xbfb8aa3b, v31
	v_exp_f32_e32 v28, v28
	v_exp_f32_e32 v24, v24
	v_ashrrev_i32_e32 v39, 31, v38
	v_add_f32_e32 v28, 1.0, v28
	v_add_f32_e32 v24, 1.0, v24
	v_rcp_f32_e32 v32, v28
	v_rcp_f32_e32 v33, v24
	v_lshlrev_b32_e32 v28, 16, v37
	v_pk_mul_f32 v[24:25], v[32:33], v[30:31]
	s_nop 0
	v_pk_mul_f32 v[24:25], v[18:19], v[24:25]
	v_add_f32_e32 v18, v21, v29
	v_mul_f32_e32 v18, 0xbfb8aa3b, v18
	v_exp_f32_e32 v18, v18
	v_and_b32_e32 v19, 0xffff0000, v41
	v_and_b32_e32 v29, 0xffff0000, v37
	v_mul_f32_e32 v30, 0xbfb8aa3b, v28
	v_add_f32_e32 v18, 1.0, v18
	v_rcp_f32_e32 v21, v18
	v_lshlrev_b32_e32 v18, 16, v41
	v_exp_f32_e32 v30, v30
	v_pk_mul_f32 v[18:19], v[20:21], v[18:19]
	v_mul_f32_e32 v20, 0xbfb8aa3b, v29
	v_exp_f32_e32 v20, v20
	v_add_f32_e32 v30, 1.0, v30
	v_rcp_f32_e32 v30, v30
	v_add_f32_e32 v20, 1.0, v20
	v_rcp_f32_e32 v31, v20
	s_nop 0
	v_pk_mul_f32 v[20:21], v[30:31], v[28:29]
	s_nop 0
	v_pk_mul_f32 v[28:29], v[18:19], v[20:21]
	v_cvt_pk_bf16_f32 v18, v22, v23
	v_cvt_pk_bf16_f32 v19, v24, v25
	v_cvt_pk_bf16_f32 v20, v26, v27
	v_cvt_pk_bf16_f32 v21, v28, v29
	global_store_dwordx4 v[42:43], v[18:21], off offset:2304
	global_load_dwordx4 v[22:25], v[148:149], off offset:16
	global_load_dwordx4 v[26:29], v[148:149], off
	v_lshlrev_b64 v[18:19], 11, v[38:39]
	v_lshl_add_u64 v[18:19], s[56:57], 0, v[18:19]
	v_lshl_add_u64 v[20:21], v[18:19], 0, v[150:151]
	v_mad_i64_i32 v[18:19], s[24:25], v38, s48, v[154:155]
	v_lshl_add_u64 v[18:19], v[18:19], 0, s[94:95]
	v_lshl_add_u64 v[34:35], v[18:19], 0, v[150:151]
	global_load_dwordx4 v[30:33], v[20:21], off
	v_lshl_add_u64 v[18:19], v[18:19], 0, v[156:157]
	global_load_dwordx4 v[34:37], v[34:35], off
	s_waitcnt vmcnt(0)
	v_add_f32_e32 v10, v10, v22
	v_add_f32_e32 v14, v14, v26
	v_add_f32_e32 v15, v15, v27
	v_mul_f32_e32 v14, 0xbfb8aa3b, v14
	v_mul_f32_e32 v15, 0xbfb8aa3b, v15
	v_exp_f32_e32 v14, v14
	v_exp_f32_e32 v15, v15
	v_add_f32_e32 v11, v11, v23
	v_mul_f32_e32 v10, 0xbfb8aa3b, v10
	v_mul_f32_e32 v11, 0xbfb8aa3b, v11
	v_exp_f32_e32 v10, v10
	v_lshlrev_b32_e32 v40, 16, v34
	v_mul_f32_e32 v22, 0xbfb8aa3b, v40
	v_exp_f32_e32 v22, v22
	v_and_b32_e32 v41, 0xffff0000, v34
	v_exp_f32_e32 v11, v11
	v_add_f32_e32 v14, 1.0, v14
	v_add_f32_e32 v22, 1.0, v22
	v_rcp_f32_e32 v42, v22
	v_mul_f32_e32 v22, 0xbfb8aa3b, v41
	v_exp_f32_e32 v22, v22
	v_add_f32_e32 v15, 1.0, v15
	v_rcp_f32_e32 v14, v14
	v_rcp_f32_e32 v15, v15
	v_add_f32_e32 v22, 1.0, v22
	v_rcp_f32_e32 v43, v22
	v_add_f32_e32 v10, 1.0, v10
	v_add_f32_e32 v11, 1.0, v11
	v_rcp_f32_e32 v10, v10
	v_rcp_f32_e32 v11, v11
	v_lshlrev_b32_e32 v26, 16, v30
	v_and_b32_e32 v27, 0xffff0000, v30
	v_pk_mul_f32 v[14:15], v[14:15], v[26:27]
	v_pk_mul_f32 v[26:27], v[42:43], v[40:41]
	v_lshlrev_b32_e32 v22, 16, v32
	v_pk_mul_f32 v[14:15], v[14:15], v[26:27]
	v_and_b32_e32 v23, 0xffff0000, v32
	v_lshlrev_b32_e32 v26, 16, v36
	v_and_b32_e32 v27, 0xffff0000, v36
	v_mul_f32_e32 v30, 0xbfb8aa3b, v26
	v_pk_mul_f32 v[10:11], v[10:11], v[22:23]
	v_mul_f32_e32 v22, 0xbfb8aa3b, v27
	v_exp_f32_e32 v30, v30
	v_exp_f32_e32 v22, v22
	v_add_f32_e32 v30, 1.0, v30
	v_add_f32_e32 v22, 1.0, v22
	v_rcp_f32_e32 v40, v30
	v_rcp_f32_e32 v41, v22
	s_nop 0
	v_pk_mul_f32 v[22:23], v[40:41], v[26:27]
	s_nop 0
	v_pk_mul_f32 v[22:23], v[10:11], v[22:23]
	v_add_f32_e32 v11, v12, v24
	v_mul_f32_e32 v11, 0xbfb8aa3b, v11
	v_exp_f32_e32 v11, v11
	v_add_f32_e32 v10, v16, v28
	v_mul_f32_e32 v10, 0xbfb8aa3b, v10
	v_exp_f32_e32 v10, v10
	v_add_f32_e32 v11, 1.0, v11
	v_rcp_f32_e32 v12, v11
	v_add_f32_e32 v11, v17, v29
	v_mul_f32_e32 v11, 0xbfb8aa3b, v11
	v_exp_f32_e32 v11, v11
	v_add_f32_e32 v10, 1.0, v10
	v_rcp_f32_e32 v10, v10
	v_lshlrev_b32_e32 v16, 16, v31
	v_add_f32_e32 v11, 1.0, v11
	v_rcp_f32_e32 v11, v11
	v_and_b32_e32 v17, 0xffff0000, v31
	v_lshlrev_b32_e32 v26, 16, v35
	v_and_b32_e32 v27, 0xffff0000, v35
	v_mul_f32_e32 v24, 0xbfb8aa3b, v26
	v_pk_mul_f32 v[10:11], v[10:11], v[16:17]
	v_mul_f32_e32 v16, 0xbfb8aa3b, v27
	v_exp_f32_e32 v24, v24
	v_exp_f32_e32 v16, v16
	v_add_f32_e32 v24, 1.0, v24
	v_add_f32_e32 v16, 1.0, v16
	v_rcp_f32_e32 v28, v24
	v_rcp_f32_e32 v29, v16
	v_lshlrev_b32_e32 v24, 16, v37
	v_pk_mul_f32 v[16:17], v[28:29], v[26:27]
	s_nop 0
	v_pk_mul_f32 v[16:17], v[10:11], v[16:17]
	v_add_f32_e32 v10, v13, v25
	v_mul_f32_e32 v10, 0xbfb8aa3b, v10
	v_exp_f32_e32 v10, v10
	v_and_b32_e32 v11, 0xffff0000, v33
	v_and_b32_e32 v25, 0xffff0000, v37
	v_mul_f32_e32 v26, 0xbfb8aa3b, v24
	v_add_f32_e32 v10, 1.0, v10
	v_rcp_f32_e32 v13, v10
	v_lshlrev_b32_e32 v10, 16, v33
	v_exp_f32_e32 v26, v26
	v_pk_mul_f32 v[10:11], v[12:13], v[10:11]
	v_mul_f32_e32 v12, 0xbfb8aa3b, v25
	v_exp_f32_e32 v12, v12
	v_add_f32_e32 v26, 1.0, v26
	v_rcp_f32_e32 v26, v26
	v_add_f32_e32 v12, 1.0, v12
	v_rcp_f32_e32 v27, v12
	s_nop 0
	v_pk_mul_f32 v[12:13], v[26:27], v[24:25]
	s_nop 0
	v_pk_mul_f32 v[24:25], v[10:11], v[12:13]
	v_cvt_pk_bf16_f32 v10, v14, v15
	v_lshlrev_b64 v[14:15], 12, v[38:39]
	v_lshl_add_u64 v[14:15], s[36:37], 0, v[14:15]
	v_cvt_pk_bf16_f32 v11, v16, v17
	v_cvt_pk_bf16_f32 v12, v22, v23
	v_cvt_pk_bf16_f32 v13, v24, v25
	v_lshl_add_u64 v[26:27], v[14:15], 0, v[150:151]
	global_store_dwordx4 v[26:27], v[10:13], off offset:2048
	global_load_dwordx4 v[10:13], v[148:149], off offset:528
	s_nop 0
	global_load_dwordx4 v[14:17], v[148:149], off offset:512
	global_load_dwordx4 v[22:25], v[20:21], off offset:256
	s_waitcnt vmcnt(0)
	v_add_f32_e32 v2, v2, v10
	global_load_dwordx4 v[18:21], v[18:19], off
	v_add_f32_e32 v6, v6, v14
	v_add_f32_e32 v7, v7, v15
	v_mul_f32_e32 v6, 0xbfb8aa3b, v6
	v_mul_f32_e32 v7, 0xbfb8aa3b, v7
	v_exp_f32_e32 v6, v6
	v_exp_f32_e32 v7, v7
	v_add_f32_e32 v3, v3, v11
	v_mul_f32_e32 v2, 0xbfb8aa3b, v2
	v_mul_f32_e32 v3, 0xbfb8aa3b, v3
	v_exp_f32_e32 v2, v2
	v_exp_f32_e32 v3, v3
	v_add_f32_e32 v6, 1.0, v6
	v_add_f32_e32 v7, 1.0, v7
	v_rcp_f32_e32 v6, v6
	v_rcp_f32_e32 v7, v7
	v_add_f32_e32 v2, 1.0, v2
	v_add_f32_e32 v3, 1.0, v3
	v_rcp_f32_e32 v2, v2
	v_rcp_f32_e32 v3, v3
	v_lshlrev_b32_e32 v14, 16, v22
	v_and_b32_e32 v15, 0xffff0000, v22
	v_pk_mul_f32 v[6:7], v[6:7], v[14:15]
	v_and_b32_e32 v11, 0xffff0000, v24
	s_waitcnt vmcnt(0)
	v_lshlrev_b32_e32 v28, 16, v18
	v_mul_f32_e32 v10, 0xbfb8aa3b, v28
	v_exp_f32_e32 v10, v10
	v_and_b32_e32 v29, 0xffff0000, v18
	v_add_f32_e32 v10, 1.0, v10
	v_rcp_f32_e32 v30, v10
	v_mul_f32_e32 v10, 0xbfb8aa3b, v29
	v_exp_f32_e32 v10, v10
	s_nop 0
	v_add_f32_e32 v10, 1.0, v10
	v_rcp_f32_e32 v31, v10
	v_lshlrev_b32_e32 v10, 16, v24
	v_pk_mul_f32 v[2:3], v[2:3], v[10:11]
	v_pk_mul_f32 v[14:15], v[30:31], v[28:29]
	s_nop 0
	v_pk_mul_f32 v[6:7], v[6:7], v[14:15]
	v_lshlrev_b32_e32 v14, 16, v20
	v_and_b32_e32 v15, 0xffff0000, v20
	v_mul_f32_e32 v18, 0xbfb8aa3b, v14
	v_mul_f32_e32 v10, 0xbfb8aa3b, v15
	v_exp_f32_e32 v18, v18
	v_exp_f32_e32 v10, v10
	v_add_f32_e32 v18, 1.0, v18
	v_add_f32_e32 v10, 1.0, v10
	v_rcp_f32_e32 v28, v18
	v_rcp_f32_e32 v29, v10
	s_nop 0
	v_pk_mul_f32 v[10:11], v[28:29], v[14:15]
	s_nop 0
	v_pk_mul_f32 v[10:11], v[2:3], v[10:11]
	v_add_f32_e32 v3, v4, v12
	v_mul_f32_e32 v3, 0xbfb8aa3b, v3
	v_exp_f32_e32 v3, v3
	v_add_f32_e32 v2, v8, v16
	v_mul_f32_e32 v2, 0xbfb8aa3b, v2
	v_exp_f32_e32 v2, v2
	v_add_f32_e32 v3, 1.0, v3
	v_rcp_f32_e32 v4, v3
	v_add_f32_e32 v3, v9, v17
	v_mul_f32_e32 v3, 0xbfb8aa3b, v3
	v_exp_f32_e32 v3, v3
	v_add_f32_e32 v2, 1.0, v2
	v_rcp_f32_e32 v2, v2
	v_lshlrev_b32_e32 v8, 16, v23
	v_add_f32_e32 v3, 1.0, v3
	v_rcp_f32_e32 v3, v3
	v_and_b32_e32 v9, 0xffff0000, v23
	v_lshlrev_b32_e32 v14, 16, v19
	v_and_b32_e32 v15, 0xffff0000, v19
	v_mul_f32_e32 v12, 0xbfb8aa3b, v14
	v_pk_mul_f32 v[2:3], v[2:3], v[8:9]
	v_mul_f32_e32 v8, 0xbfb8aa3b, v15
	v_exp_f32_e32 v12, v12
	v_exp_f32_e32 v8, v8
	v_add_f32_e32 v12, 1.0, v12
	v_add_f32_e32 v8, 1.0, v8
	v_rcp_f32_e32 v16, v12
	v_rcp_f32_e32 v17, v8
	v_lshlrev_b32_e32 v12, 16, v21
	v_pk_mul_f32 v[8:9], v[16:17], v[14:15]
	s_nop 0
	v_pk_mul_f32 v[8:9], v[2:3], v[8:9]
	v_add_f32_e32 v2, v5, v13
	v_mul_f32_e32 v2, 0xbfb8aa3b, v2
	v_exp_f32_e32 v2, v2
	v_and_b32_e32 v3, 0xffff0000, v25
	v_and_b32_e32 v13, 0xffff0000, v21
	v_mul_f32_e32 v14, 0xbfb8aa3b, v12
	v_add_f32_e32 v2, 1.0, v2
	v_rcp_f32_e32 v5, v2
	v_lshlrev_b32_e32 v2, 16, v25
	v_exp_f32_e32 v14, v14
	v_pk_mul_f32 v[2:3], v[4:5], v[2:3]
	v_mul_f32_e32 v4, 0xbfb8aa3b, v13
	v_exp_f32_e32 v4, v4
	v_add_f32_e32 v14, 1.0, v14
	v_rcp_f32_e32 v14, v14
	v_add_f32_e32 v4, 1.0, v4
	v_rcp_f32_e32 v15, v4
	s_nop 0
	v_pk_mul_f32 v[4:5], v[14:15], v[12:13]
	s_nop 0
	v_pk_mul_f32 v[12:13], v[2:3], v[4:5]
	v_cvt_pk_bf16_f32 v2, v6, v7
	v_cvt_pk_bf16_f32 v3, v8, v9
	v_cvt_pk_bf16_f32 v4, v10, v11
	v_cvt_pk_bf16_f32 v5, v12, v13
	global_store_dwordx4 v[26:27], v[2:5], off offset:2304
	s_cbranch_vccz .LBB0_970
	v_readlane_b32 s4, v254, 12
	s_waitcnt vmcnt(0)
	v_readlane_b32 s5, v254, 13
	s_andn2_b64 vcc, exec, s[4:5]
	s_cbranch_vccnz .LBB0_981
	s_barrier

.LBB0_1044:
	s_add_u32 s2, s68, 0xfff80080
	s_addc_u32 s17, s69, -1
	s_add_i32 s26, 0, 0x10000
	v_add_u32_e32 v156, s26, v141
	ds_read_b128 v[144:147], v156
	ds_read_b128 v[148:151], v156 offset:1024
	ds_read_b128 v[152:155], v156 offset:2048
	ds_read_b128 v[156:159], v156 offset:3072
	s_cmp_eq_u32 s44, 28
	s_cselect_b32 s73, s55, s17
	s_cselect_b32 s72, s24, s2
	s_cselect_b32 s71, s25, s92
	s_cselect_b32 s70, s43, s83
	v_lshl_add_u64 v[164:165], s[68:69], 0, v[136:137]
	s_add_i32 m0, s58, 0xc000
	ds_read_b128 v[160:163], v143
	ds_read_b128 v[188:191], v143 offset:1024
	ds_read_b128 v[192:195], v143 offset:2048
	ds_read_b128 v[196:199], v143 offset:3072
	ds_read_b128 v[200:203], v143 offset:4096
	ds_read_b128 v[216:219], v143 offset:5120
	ds_read_b128 v[220:223], v143 offset:6144
	ds_read_b128 v[224:227], v143 offset:7168
	global_load_lds_dwordx4 v[164:165], off
	v_lshl_add_u64 v[164:165], s[68:69], 0, v[138:139]
	s_add_i32 m0, s58, 0xe000
	s_nop 0
	global_load_lds_dwordx4 v[164:165], off
	s_waitcnt lgkmcnt(8)
	s_barrier
	s_waitcnt lgkmcnt(12)
	s_waitcnt lgkmcnt(12)
	s_waitcnt lgkmcnt(7)
	v_mfma_f32_16x16x32_bf16 v[126:129], v[144:147], v[160:163], v[126:129]
	v_mfma_f32_16x16x32_bf16 v[122:125], v[152:155], v[160:163], v[122:125]
	s_waitcnt lgkmcnt(5)
	v_mfma_f32_16x16x32_bf16 v[118:121], v[144:147], v[192:195], v[118:121]
	v_mfma_f32_16x16x32_bf16 v[114:117], v[152:155], v[192:195], v[114:117]
	s_waitcnt lgkmcnt(3)
	v_mfma_f32_16x16x32_bf16 v[102:105], v[144:147], v[200:203], v[102:105]
	v_mfma_f32_16x16x32_bf16 v[98:101], v[152:155], v[200:203], v[98:101]
	s_waitcnt lgkmcnt(1)
	v_mfma_f32_16x16x32_bf16 v[86:89], v[144:147], v[220:223], v[86:89]
	v_mfma_f32_16x16x32_bf16 v[82:85], v[152:155], v[220:223], v[82:85]
	v_mfma_f32_16x16x32_bf16 v[126:129], v[148:151], v[188:191], v[126:129]
	v_mfma_f32_16x16x32_bf16 v[122:125], v[156:159], v[188:191], v[122:125]
	v_mfma_f32_16x16x32_bf16 v[118:121], v[148:151], v[196:199], v[118:121]
	v_mfma_f32_16x16x32_bf16 v[114:117], v[156:159], v[196:199], v[114:117]
	v_mfma_f32_16x16x32_bf16 v[102:105], v[148:151], v[216:219], v[102:105]
	v_mfma_f32_16x16x32_bf16 v[98:101], v[156:159], v[216:219], v[98:101]
	s_waitcnt lgkmcnt(0)
	v_mfma_f32_16x16x32_bf16 v[86:89], v[148:151], v[224:227], v[86:89]
	v_mfma_f32_16x16x32_bf16 v[82:85], v[156:159], v[224:227], v[82:85]
	s_barrier
	s_add_i32 s2, 0, 0x14000
	v_add_u32_e32 v164, s2, v141
	s_add_i32 s17, s26, s3
	ds_read_b128 v[228:231], v164
	ds_read_b128 v[232:235], v164 offset:1024
	ds_read_b128 v[236:239], v164 offset:2048
	ds_read_b128 v[240:243], v164 offset:3072
	v_lshl_add_u64 v[164:165], s[70:71], 0, v[0:1]
	s_mov_b32 m0, s17
	v_lshl_add_u64 v[204:205], s[70:71], 0, v[130:131]
	global_load_lds_dwordx4 v[164:165], off
	s_add_i32 m0, s17, 0x2000
	s_nop 0
	global_load_lds_dwordx4 v[204:205], off
	s_barrier
	s_waitcnt lgkmcnt(4)
	s_waitcnt lgkmcnt(4)
	s_waitcnt lgkmcnt(3)
	v_mfma_f32_16x16x32_bf16 v[110:113], v[228:231], v[160:163], v[110:113]
	s_waitcnt lgkmcnt(1)
	v_mfma_f32_16x16x32_bf16 v[106:109], v[236:239], v[160:163], v[106:109]
	v_mfma_f32_16x16x32_bf16 v[94:97], v[228:231], v[192:195], v[94:97]
	v_mfma_f32_16x16x32_bf16 v[90:93], v[236:239], v[192:195], v[90:93]
	v_mfma_f32_16x16x32_bf16 v[78:81], v[228:231], v[200:203], v[78:81]
	v_mfma_f32_16x16x32_bf16 v[74:77], v[236:239], v[200:203], v[74:77]
	v_mfma_f32_16x16x32_bf16 v[70:73], v[228:231], v[220:223], v[70:73]
	v_mfma_f32_16x16x32_bf16 v[66:69], v[236:239], v[220:223], v[66:69]
	v_mfma_f32_16x16x32_bf16 v[110:113], v[232:235], v[188:191], v[110:113]
	s_waitcnt lgkmcnt(0)
	v_mfma_f32_16x16x32_bf16 v[106:109], v[240:243], v[188:191], v[106:109]
	v_mfma_f32_16x16x32_bf16 v[94:97], v[232:235], v[196:199], v[94:97]
	v_mfma_f32_16x16x32_bf16 v[90:93], v[240:243], v[196:199], v[90:93]
	v_mfma_f32_16x16x32_bf16 v[78:81], v[232:235], v[216:219], v[78:81]
	v_mfma_f32_16x16x32_bf16 v[74:77], v[240:243], v[216:219], v[74:77]
	v_mfma_f32_16x16x32_bf16 v[70:73], v[232:235], v[224:227], v[70:73]
	v_mfma_f32_16x16x32_bf16 v[66:69], v[240:243], v[224:227], v[66:69]
	s_mov_b32 m0, s58
	v_lshl_add_u64 v[244:245], s[72:73], 0, v[134:135]
	s_barrier
	ds_read_b128 v[160:163], v143 offset:16384
	ds_read_b128 v[188:191], v143 offset:17408
	ds_read_b128 v[192:195], v143 offset:18432
	ds_read_b128 v[196:199], v143 offset:19456
	ds_read_b128 v[200:203], v143 offset:20480
	ds_read_b128 v[216:219], v143 offset:21504
	ds_read_b128 v[220:223], v143 offset:22528
	ds_read_b128 v[224:227], v143 offset:23552
	global_load_lds_dwordx4 v[244:245], off
	v_lshl_add_u64 v[246:247], s[72:73], 0, v[132:133]
	s_mov_b32 m0, s74
	s_nop 0
	global_load_lds_dwordx4 v[246:247], off
	s_barrier
	s_waitcnt lgkmcnt(8)
	s_waitcnt lgkmcnt(8)
	s_waitcnt lgkmcnt(7)
	v_mfma_f32_16x16x32_bf16 v[62:65], v[144:147], v[160:163], v[62:65]
	v_mfma_f32_16x16x32_bf16 v[58:61], v[152:155], v[160:163], v[58:61]
	s_waitcnt lgkmcnt(5)
	v_mfma_f32_16x16x32_bf16 v[54:57], v[144:147], v[192:195], v[54:57]
	v_mfma_f32_16x16x32_bf16 v[50:53], v[152:155], v[192:195], v[50:53]
	s_waitcnt lgkmcnt(3)
	v_mfma_f32_16x16x32_bf16 v[38:41], v[144:147], v[200:203], v[38:41]
	v_mfma_f32_16x16x32_bf16 v[34:37], v[152:155], v[200:203], v[34:37]
	s_waitcnt lgkmcnt(1)
	v_mfma_f32_16x16x32_bf16 v[22:25], v[144:147], v[220:223], v[22:25]
	v_mfma_f32_16x16x32_bf16 v[18:21], v[152:155], v[220:223], v[18:21]
	v_mfma_f32_16x16x32_bf16 v[62:65], v[148:151], v[188:191], v[62:65]
	v_mfma_f32_16x16x32_bf16 v[58:61], v[156:159], v[188:191], v[58:61]
	v_mfma_f32_16x16x32_bf16 v[54:57], v[148:151], v[196:199], v[54:57]
	v_mfma_f32_16x16x32_bf16 v[50:53], v[156:159], v[196:199], v[50:53]
	v_mfma_f32_16x16x32_bf16 v[38:41], v[148:151], v[216:219], v[38:41]
	v_mfma_f32_16x16x32_bf16 v[34:37], v[156:159], v[216:219], v[34:37]
	s_waitcnt lgkmcnt(0)
	v_mfma_f32_16x16x32_bf16 v[22:25], v[148:151], v[224:227], v[22:25]
	v_mfma_f32_16x16x32_bf16 v[18:21], v[156:159], v[224:227], v[18:21]
	s_barrier
	s_add_u32 s26, s70, 0x80000
	s_addc_u32 s27, s71, 0
	s_add_i32 s2, s2, s3
	v_lshl_add_u64 v[144:145], s[26:27], 0, v[0:1]
	s_mov_b32 m0, s2
	s_nop 0
	global_load_lds_dwordx4 v[144:145], off
	v_lshl_add_u64 v[144:145], s[26:27], 0, v[130:131]
	s_add_i32 m0, s2, 0x2000
	s_nop 0
	global_load_lds_dwordx4 v[144:145], off
	s_waitcnt vmcnt(6)
	s_barrier
	v_mfma_f32_16x16x32_bf16 v[46:49], v[228:231], v[160:163], v[46:49]
	v_mfma_f32_16x16x32_bf16 v[42:45], v[236:239], v[160:163], v[42:45]
	v_mfma_f32_16x16x32_bf16 v[30:33], v[228:231], v[192:195], v[30:33]
	v_mfma_f32_16x16x32_bf16 v[26:29], v[236:239], v[192:195], v[26:29]
	v_mfma_f32_16x16x32_bf16 v[14:17], v[228:231], v[200:203], v[14:17]
	v_mfma_f32_16x16x32_bf16 v[10:13], v[236:239], v[200:203], v[10:13]
	v_mfma_f32_16x16x32_bf16 v[6:9], v[228:231], v[220:223], v[6:9]
	v_mfma_f32_16x16x32_bf16 v[2:5], v[236:239], v[220:223], v[2:5]
	v_mfma_f32_16x16x32_bf16 v[46:49], v[232:235], v[188:191], v[46:49]
	v_mfma_f32_16x16x32_bf16 v[42:45], v[240:243], v[188:191], v[42:45]
	v_mfma_f32_16x16x32_bf16 v[30:33], v[232:235], v[196:199], v[30:33]
	v_mfma_f32_16x16x32_bf16 v[26:29], v[240:243], v[196:199], v[26:29]
	v_mfma_f32_16x16x32_bf16 v[14:17], v[232:235], v[216:219], v[14:17]
	v_mfma_f32_16x16x32_bf16 v[10:13], v[240:243], v[216:219], v[10:13]
	v_mfma_f32_16x16x32_bf16 v[6:9], v[232:235], v[224:227], v[6:9]
	v_mfma_f32_16x16x32_bf16 v[2:5], v[240:243], v[224:227], v[2:5]
	s_add_i32 s2, 0, 0x18000
	v_add_u32_e32 v156, s2, v141
	s_barrier
	ds_read_b128 v[144:147], v156
	ds_read_b128 v[148:151], v156 offset:1024
	ds_read_b128 v[152:155], v156 offset:2048
	ds_read_b128 v[156:159], v156 offset:3072
	s_add_u32 s26, s72, 0x80000
	s_addc_u32 s27, s73, 0
	s_mov_b32 m0, s75
	v_lshl_add_u64 v[228:229], s[26:27], 0, v[134:135]
	ds_read_b128 v[160:163], v143 offset:32768
	ds_read_b128 v[188:191], v143 offset:33792
	ds_read_b128 v[192:195], v143 offset:34816
	ds_read_b128 v[196:199], v143 offset:35840
	ds_read_b128 v[200:203], v143 offset:36864
	ds_read_b128 v[216:219], v143 offset:37888
	ds_read_b128 v[220:223], v143 offset:38912
	ds_read_b128 v[224:227], v143 offset:39936
	global_load_lds_dwordx4 v[228:229], off
	v_lshl_add_u64 v[228:229], s[26:27], 0, v[132:133]
	s_mov_b32 m0, s79
	s_nop 0
	global_load_lds_dwordx4 v[228:229], off
	s_waitcnt lgkmcnt(8)
	s_barrier
	s_waitcnt lgkmcnt(12)
	s_waitcnt lgkmcnt(12)
	s_waitcnt lgkmcnt(7)
	v_mfma_f32_16x16x32_bf16 v[126:129], v[144:147], v[160:163], v[126:129]
	v_mfma_f32_16x16x32_bf16 v[122:125], v[152:155], v[160:163], v[122:125]
	s_waitcnt lgkmcnt(5)
	v_mfma_f32_16x16x32_bf16 v[118:121], v[144:147], v[192:195], v[118:121]
	v_mfma_f32_16x16x32_bf16 v[114:117], v[152:155], v[192:195], v[114:117]
	s_waitcnt lgkmcnt(3)
	v_mfma_f32_16x16x32_bf16 v[102:105], v[144:147], v[200:203], v[102:105]
	v_mfma_f32_16x16x32_bf16 v[98:101], v[152:155], v[200:203], v[98:101]
	s_waitcnt lgkmcnt(1)
	v_mfma_f32_16x16x32_bf16 v[86:89], v[144:147], v[220:223], v[86:89]
	v_mfma_f32_16x16x32_bf16 v[82:85], v[152:155], v[220:223], v[82:85]
	v_mfma_f32_16x16x32_bf16 v[126:129], v[148:151], v[188:191], v[126:129]
	v_mfma_f32_16x16x32_bf16 v[122:125], v[156:159], v[188:191], v[122:125]
	v_mfma_f32_16x16x32_bf16 v[118:121], v[148:151], v[196:199], v[118:121]
	v_mfma_f32_16x16x32_bf16 v[114:117], v[156:159], v[196:199], v[114:117]
	v_mfma_f32_16x16x32_bf16 v[102:105], v[148:151], v[216:219], v[102:105]
	v_mfma_f32_16x16x32_bf16 v[98:101], v[156:159], v[216:219], v[98:101]
	s_waitcnt lgkmcnt(0)
	v_mfma_f32_16x16x32_bf16 v[86:89], v[148:151], v[224:227], v[86:89]
	v_mfma_f32_16x16x32_bf16 v[82:85], v[156:159], v[224:227], v[82:85]
	s_barrier
	s_add_i32 s17, 0, 0x1c000
	s_add_i32 s2, s2, s3
	v_add_u32_e32 v206, s17, v141
	v_lshl_add_u64 v[164:165], v[164:165], 0, s[28:29]
	s_mov_b32 m0, s2
	ds_read_b128 v[228:231], v206
	ds_read_b128 v[232:235], v206 offset:1024
	ds_read_b128 v[236:239], v206 offset:2048
	ds_read_b128 v[240:243], v206 offset:3072
	global_load_lds_dwordx4 v[164:165], off
	v_lshl_add_u64 v[164:165], v[204:205], 0, s[28:29]
	s_add_i32 m0, s2, 0x2000
	s_nop 0
	global_load_lds_dwordx4 v[164:165], off
	s_barrier
	s_waitcnt lgkmcnt(4)
	s_waitcnt lgkmcnt(4)
	s_waitcnt lgkmcnt(3)
	v_mfma_f32_16x16x32_bf16 v[110:113], v[228:231], v[160:163], v[110:113]
	s_waitcnt lgkmcnt(1)
	v_mfma_f32_16x16x32_bf16 v[106:109], v[236:239], v[160:163], v[106:109]
	v_mfma_f32_16x16x32_bf16 v[94:97], v[228:231], v[192:195], v[94:97]
	v_mfma_f32_16x16x32_bf16 v[90:93], v[236:239], v[192:195], v[90:93]
	v_mfma_f32_16x16x32_bf16 v[78:81], v[228:231], v[200:203], v[78:81]
	v_mfma_f32_16x16x32_bf16 v[74:77], v[236:239], v[200:203], v[74:77]
	v_mfma_f32_16x16x32_bf16 v[70:73], v[228:231], v[220:223], v[70:73]
	v_mfma_f32_16x16x32_bf16 v[66:69], v[236:239], v[220:223], v[66:69]
	v_mfma_f32_16x16x32_bf16 v[110:113], v[232:235], v[188:191], v[110:113]
	s_waitcnt lgkmcnt(0)
	v_mfma_f32_16x16x32_bf16 v[106:109], v[240:243], v[188:191], v[106:109]
	v_mfma_f32_16x16x32_bf16 v[94:97], v[232:235], v[196:199], v[94:97]
	v_mfma_f32_16x16x32_bf16 v[90:93], v[240:243], v[196:199], v[90:93]
	v_mfma_f32_16x16x32_bf16 v[78:81], v[232:235], v[216:219], v[78:81]
	v_mfma_f32_16x16x32_bf16 v[74:77], v[240:243], v[216:219], v[74:77]
	v_mfma_f32_16x16x32_bf16 v[70:73], v[232:235], v[224:227], v[70:73]
	v_mfma_f32_16x16x32_bf16 v[66:69], v[240:243], v[224:227], v[66:69]
	s_mov_b32 m0, s80
	v_lshl_add_u64 v[164:165], v[244:245], 0, s[28:29]
	s_barrier
	ds_read_b128 v[160:163], v143 offset:49152
	ds_read_b128 v[188:191], v143 offset:50176
	ds_read_b128 v[192:195], v143 offset:51200
	ds_read_b128 v[196:199], v143 offset:52224
	ds_read_b128 v[200:203], v143 offset:53248
	ds_read_b128 v[216:219], v143 offset:54272
	ds_read_b128 v[220:223], v143 offset:55296
	ds_read_b128 v[224:227], v143 offset:56320
	global_load_lds_dwordx4 v[164:165], off
	v_lshl_add_u64 v[164:165], v[246:247], 0, s[28:29]
	s_mov_b32 m0, s81
	s_nop 0
	global_load_lds_dwordx4 v[164:165], off
	s_barrier
	s_waitcnt lgkmcnt(8)
	s_waitcnt lgkmcnt(8)
	s_waitcnt lgkmcnt(7)
	v_mfma_f32_16x16x32_bf16 v[62:65], v[144:147], v[160:163], v[62:65]
	v_mfma_f32_16x16x32_bf16 v[58:61], v[152:155], v[160:163], v[58:61]
	s_waitcnt lgkmcnt(5)
	v_mfma_f32_16x16x32_bf16 v[54:57], v[144:147], v[192:195], v[54:57]
	v_mfma_f32_16x16x32_bf16 v[50:53], v[152:155], v[192:195], v[50:53]
	s_waitcnt lgkmcnt(3)
	v_mfma_f32_16x16x32_bf16 v[38:41], v[144:147], v[200:203], v[38:41]
	v_mfma_f32_16x16x32_bf16 v[34:37], v[152:155], v[200:203], v[34:37]
	s_waitcnt lgkmcnt(1)
	v_mfma_f32_16x16x32_bf16 v[22:25], v[144:147], v[220:223], v[22:25]
	v_mfma_f32_16x16x32_bf16 v[18:21], v[152:155], v[220:223], v[18:21]
	v_mfma_f32_16x16x32_bf16 v[62:65], v[148:151], v[188:191], v[62:65]
	v_mfma_f32_16x16x32_bf16 v[58:61], v[156:159], v[188:191], v[58:61]
	v_mfma_f32_16x16x32_bf16 v[54:57], v[148:151], v[196:199], v[54:57]
	v_mfma_f32_16x16x32_bf16 v[50:53], v[156:159], v[196:199], v[50:53]
	v_mfma_f32_16x16x32_bf16 v[38:41], v[148:151], v[216:219], v[38:41]
	v_mfma_f32_16x16x32_bf16 v[34:37], v[156:159], v[216:219], v[34:37]
	s_waitcnt lgkmcnt(0)
	v_mfma_f32_16x16x32_bf16 v[22:25], v[148:151], v[224:227], v[22:25]
	v_mfma_f32_16x16x32_bf16 v[18:21], v[156:159], v[224:227], v[18:21]
	s_barrier
	s_add_u32 s26, s70, 0x80080
	s_addc_u32 s27, s71, 0
	s_add_i32 s2, s17, s3
	v_lshl_add_u64 v[144:145], s[26:27], 0, v[0:1]
	s_mov_b32 m0, s2
	s_nop 0
	global_load_lds_dwordx4 v[144:145], off
	v_lshl_add_u64 v[144:145], s[26:27], 0, v[130:131]
	s_add_i32 m0, s2, 0x2000
	s_nop 0
	global_load_lds_dwordx4 v[144:145], off
	s_waitcnt vmcnt(6)
	s_barrier
	v_mfma_f32_16x16x32_bf16 v[46:49], v[228:231], v[160:163], v[46:49]
	v_mfma_f32_16x16x32_bf16 v[42:45], v[236:239], v[160:163], v[42:45]
	v_mfma_f32_16x16x32_bf16 v[30:33], v[228:231], v[192:195], v[30:33]
	v_mfma_f32_16x16x32_bf16 v[26:29], v[236:239], v[192:195], v[26:29]
	v_mfma_f32_16x16x32_bf16 v[14:17], v[228:231], v[200:203], v[14:17]
	v_mfma_f32_16x16x32_bf16 v[10:13], v[236:239], v[200:203], v[10:13]
	v_mfma_f32_16x16x32_bf16 v[6:9], v[228:231], v[220:223], v[6:9]
	v_mfma_f32_16x16x32_bf16 v[2:5], v[236:239], v[220:223], v[2:5]
	v_mfma_f32_16x16x32_bf16 v[46:49], v[232:235], v[188:191], v[46:49]
	v_mfma_f32_16x16x32_bf16 v[42:45], v[240:243], v[188:191], v[42:45]
	v_mfma_f32_16x16x32_bf16 v[30:33], v[232:235], v[196:199], v[30:33]
	v_mfma_f32_16x16x32_bf16 v[26:29], v[240:243], v[196:199], v[26:29]
	v_mfma_f32_16x16x32_bf16 v[14:17], v[232:235], v[216:219], v[14:17]
	v_mfma_f32_16x16x32_bf16 v[10:13], v[240:243], v[216:219], v[10:13]
	v_mfma_f32_16x16x32_bf16 v[6:9], v[232:235], v[224:227], v[6:9]
	v_mfma_f32_16x16x32_bf16 v[2:5], v[240:243], v[224:227], v[2:5]
	s_add_i32 s44, s44, 2
	s_add_u32 s68, s68, 0x100
	s_addc_u32 s69, s69, 0
	s_add_u32 s83, s83, 0x100
	s_addc_u32 s92, s92, 0
	s_cmp_gt_u32 s44, 29
	s_barrier
	s_cbranch_scc0 .LBB0_1044
	v_lshl_add_u32 v144, s47, 8, v140
	v_lshl_or_b32 v146, s46, 8, v142
	v_ashrrev_i32_e32 v145, 31, v144
	v_cvt_pk_bf16_f32 v126, v126, v127
	v_cvt_pk_bf16_f32 v127, v128, v129
	v_cvt_pk_bf16_f32 v128, v122, v123
	v_lshlrev_b64 v[122:123], 12, v[144:145]
	v_ashrrev_i32_e32 v147, 31, v146
	v_cvt_pk_bf16_f32 v129, v124, v125
	v_lshl_add_u64 v[122:123], s[22:23], 0, v[122:123]
	v_lshlrev_b64 v[124:125], 1, v[146:147]
	v_lshl_add_u64 v[122:123], v[122:123], 0, v[124:125]
	v_cvt_pk_bf16_f32 v110, v110, v111
	v_cvt_pk_bf16_f32 v111, v112, v113
	v_cvt_pk_bf16_f32 v112, v106, v107
	v_cvt_pk_bf16_f32 v113, v108, v109
	global_store_dwordx4 v[122:123], v[110:113], off offset:256
	v_cvt_pk_bf16_f32 v94, v94, v95
	v_cvt_pk_bf16_f32 v95, v96, v97
	v_or_b32_e32 v110, 16, v144
	v_ashrrev_i32_e32 v111, 31, v110
	v_lshlrev_b64 v[110:111], 12, v[110:111]
	v_lshl_add_u64 v[110:111], s[22:23], 0, v[110:111]
	v_lshl_add_u64 v[110:111], v[110:111], 0, v[124:125]
	v_cvt_pk_bf16_f32 v96, v90, v91
	v_cvt_pk_bf16_f32 v97, v92, v93
	global_store_dwordx4 v[110:111], v[94:97], off offset:256
	s_mov_b32 s2, 0x80000
	v_cvt_pk_bf16_f32 v62, v62, v63
	v_or_b32_e32 v94, 32, v144
	v_ashrrev_i32_e32 v95, 31, v94
	v_cvt_pk_bf16_f32 v63, v64, v65
	v_cvt_pk_bf16_f32 v65, v60, v61
	s_mov_b64 s[4:5], 0x80000
	v_add_co_u32_e32 v60, vcc, s2, v122
	v_lshlrev_b64 v[94:95], 12, v[94:95]
	v_cvt_pk_bf16_f32 v64, v58, v59
	v_lshl_add_u64 v[58:59], v[122:123], 0, s[4:5]
	v_addc_co_u32_e32 v61, vcc, 0, v123, vcc
	v_cvt_pk_bf16_f32 v46, v46, v47
	v_cvt_pk_bf16_f32 v47, v48, v49
	v_cvt_pk_bf16_f32 v48, v42, v43
	v_cvt_pk_bf16_f32 v49, v44, v45
	s_mov_b32 s2, 0x90000
	v_lshl_add_u64 v[94:95], s[22:23], 0, v[94:95]
	global_store_dwordx4 v[58:59], v[46:49], off offset:256
	s_mov_b64 s[4:5], 0x90000
	v_lshl_add_u64 v[94:95], v[94:95], 0, v[124:125]
	v_add_co_u32_e32 v48, vcc, s2, v122
	v_cvt_pk_bf16_f32 v78, v78, v79
	v_cvt_pk_bf16_f32 v79, v80, v81
	v_cvt_pk_bf16_f32 v80, v74, v75
	v_cvt_pk_bf16_f32 v81, v76, v77
	v_lshl_add_u64 v[46:47], v[122:123], 0, s[4:5]
	v_addc_co_u32_e32 v49, vcc, 0, v123, vcc
	v_cvt_pk_bf16_f32 v30, v30, v31
	v_cvt_pk_bf16_f32 v31, v32, v33
	v_cvt_pk_bf16_f32 v32, v26, v27
	v_cvt_pk_bf16_f32 v33, v28, v29
	s_mov_b32 s2, 0xa0000
	global_store_dwordx4 v[94:95], v[78:81], off offset:256
	global_store_dwordx4 v[46:47], v[30:33], off offset:256
	s_mov_b64 s[4:5], 0xa0000
	v_or_b32_e32 v78, 48, v144
	v_add_co_u32_e32 v32, vcc, s2, v122
	v_ashrrev_i32_e32 v79, 31, v78
	v_lshl_add_u64 v[30:31], v[122:123], 0, s[4:5]
	v_addc_co_u32_e32 v33, vcc, 0, v123, vcc
	v_cvt_pk_bf16_f32 v14, v14, v15
	v_cvt_pk_bf16_f32 v15, v16, v17
	v_cvt_pk_bf16_f32 v16, v10, v11
	v_cvt_pk_bf16_f32 v17, v12, v13
	s_mov_b32 s2, 0xb0000
	v_lshlrev_b64 v[78:79], 12, v[78:79]
	global_store_dwordx4 v[30:31], v[14:17], off offset:256
	v_lshl_add_u64 v[78:79], s[22:23], 0, v[78:79]
	s_mov_b64 s[4:5], 0xb0000
	v_add_co_u32_e32 v16, vcc, s2, v122
	v_cvt_pk_bf16_f32 v106, v118, v119
	s_nop 0
	v_addc_co_u32_e32 v17, vcc, 0, v123, vcc
	v_cvt_pk_bf16_f32 v107, v120, v121
	v_cvt_pk_bf16_f32 v108, v114, v115
	v_cvt_pk_bf16_f32 v109, v116, v117
	v_cvt_pk_bf16_f32 v90, v102, v103
	v_cvt_pk_bf16_f32 v91, v104, v105
	v_cvt_pk_bf16_f32 v92, v98, v99
	v_cvt_pk_bf16_f32 v93, v100, v101
	v_cvt_pk_bf16_f32 v74, v86, v87
	v_cvt_pk_bf16_f32 v75, v88, v89
	v_cvt_pk_bf16_f32 v76, v82, v83
	v_cvt_pk_bf16_f32 v77, v84, v85
	v_lshl_add_u64 v[78:79], v[78:79], 0, v[124:125]
	v_cvt_pk_bf16_f32 v70, v70, v71
	v_cvt_pk_bf16_f32 v71, v72, v73
	v_cvt_pk_bf16_f32 v72, v66, v67
	v_cvt_pk_bf16_f32 v73, v68, v69
	v_cvt_pk_bf16_f32 v42, v54, v55
	v_cvt_pk_bf16_f32 v43, v56, v57
	v_cvt_pk_bf16_f32 v44, v50, v51
	v_cvt_pk_bf16_f32 v45, v52, v53
	v_cvt_pk_bf16_f32 v26, v38, v39
	v_cvt_pk_bf16_f32 v27, v40, v41
	v_cvt_pk_bf16_f32 v28, v34, v35
	v_cvt_pk_bf16_f32 v29, v36, v37
	v_cvt_pk_bf16_f32 v10, v22, v23
	v_cvt_pk_bf16_f32 v11, v24, v25
	v_cvt_pk_bf16_f32 v12, v18, v19
	v_cvt_pk_bf16_f32 v13, v20, v21
	v_lshl_add_u64 v[14:15], v[122:123], 0, s[4:5]
	v_cvt_pk_bf16_f32 v6, v6, v7
	v_cvt_pk_bf16_f32 v7, v8, v9
	v_cvt_pk_bf16_f32 v8, v2, v3
	v_cvt_pk_bf16_f32 v9, v4, v5
	s_and_b64 vcc, exec, s[0:1]
	s_mov_b32 s46, s42
	s_mov_b32 s47, s54
	s_mov_b64 s[70:71], s[64:65]
	s_mov_b64 s[68:69], s[62:63]
	global_store_dwordx4 v[122:123], v[126:129], off
	global_store_dwordx4 v[110:111], v[106:109], off
	global_store_dwordx4 v[94:95], v[90:93], off
	global_store_dwordx4 v[78:79], v[74:77], off
	global_store_dwordx4 v[78:79], v[70:73], off offset:256
	global_store_dwordx4 v[60:61], v[62:65], off
	global_store_dwordx4 v[48:49], v[42:45], off
	global_store_dwordx4 v[32:33], v[26:29], off
	global_store_dwordx4 v[16:17], v[10:13], off
	global_store_dwordx4 v[14:15], v[6:9], off offset:256
	s_cbranch_vccz .LBB0_1041
	v_readlane_b32 s0, v254, 12
	s_waitcnt vmcnt(0)
	v_readlane_b32 s1, v254, 13
	v_readlane_b32 s84, v251, 38
	s_andn2_b64 vcc, exec, s[0:1]
	v_readlane_b32 s85, v251, 39
	v_readlane_b32 s86, v251, 40
	v_readlane_b32 s87, v251, 41
	s_cbranch_vccnz .LBB0_1048
	s_barrier
